# priority raise hoisted in front of the pre-MFMA barrier; mid-segment priority flip pairs removed
# speedup vs baseline: 1.0120x; 1.0012x over previous
; #define PG8_STAGE(bufoff, gbase, voff) do { _Pragma("unroll") for (int _i = 0; _i < 2; ++_i) \
;         __builtin_amdgcn_global_load_lds((const unsigned*)((const char*)(gbase) + (voff)[_i]), (PG8_LAS unsigned*)(lds + (bufoff) + ldsw + _i * 8192), 16, 0, 0); } while (0)
; #define PG8_LDA(dst, b, h) do { _Pragma("unroll") for (int m = 0; m < 4; ++m) _Pragma("unroll") for (int k = 0; k < 2; ++k) dst[m][k] = *(const PG8_LAS bf16x8*)(lds + PG8_SA(b, h) + aoff + m * 2048 + k * 1024); } while (0)
; #define PG8_LDB(dst, b, h) do { _Pragma("unroll") for (int n = 0; n < 2; ++n) _Pragma("unroll") for (int k = 0; k < 2; ++k) dst[n][k] = *(const PG8_LAS bf16x8*)(lds + PG8_SB(b, h) + boff + n * 2048 + k * 1024); } while (0)
; #define PG8_MMA(ai, bj, At, Bt) do { __builtin_amdgcn_s_setprio(1); _Pragma("unroll") for (int m = 0; m < 4; ++m) _Pragma("unroll") for (int n = 0; n < 2; ++n) _Pragma("unroll") for (int k = 0; k < 2; ++k) \
;         acc[ai][bj][m][n] = __builtin_amdgcn_mfma_f32_16x16x32_bf16(Bt[n][k], At[m][k], acc[ai][bj][m][n], 0, 0, 0); __builtin_amdgcn_s_setprio(0); } while (0)
; #define PG8_WAIT_V(n) asm volatile("s_waitcnt vmcnt(" #n ")" ::: "memory")
; #define PG8_WAIT_L(n) asm volatile("s_waitcnt lgkmcnt(" #n ")" ::: "memory")
; template <class Epi, class Sched, bool ALIGN_EPI = false, bool SP2 = false>
; __device__ __forceinline__ void gemm_phase(PG8_LAS unsigned char* lds, const Gemm g, const Sched& S, const Epi& E) {
;     ...
;             const bool last = (t == nt - 2);
;             const char* a1 = cA + (size_t)(t + 1) * kstep;
;             const char* a2 = last ? nA : cA + (size_t)(t + 2) * kstep; const char* b2 = last ? nB : cB + (size_t)(t + 2) * kstep;
;             const char* a3 = a2 + kstep; const char* b3 = b2 + kstep;
;             if (last && has_next) S.a_ready(nxt);
;             if constexpr (SP2) {
;             PG8_LDB(B0, 0, 0); PG8_LDB(B1, 0, 1); PG8_SCHED; PG8_LDA(At, 0, 0); PG8_STAGE(PG8_SA(1, 1), a1 + hstep, voffA);
;             PG8_WAIT_V(8); PG8_WAIT_L(0); PG8_BAR; PG8_MMA(0, 0, At, B0); PG8_MMA(0, 1, At, B1); PG8_BAR; PG8_SCHED;
;             PG8_LDA(At, 0, 1); PG8_STAGE(PG8_SB(0, 0), b2, voffB); PG8_STAGE(PG8_SB(0, 1), b2 + hstep, voffB); PG8_STAGE(PG8_SA(0, 0), a2, voffA);
;             PG8_WAIT_V(8); PG8_WAIT_L(0); PG8_BAR; PG8_MMA(1, 0, At, B0); PG8_MMA(1, 1, At, B1); PG8_BAR; PG8_SCHED;
.LBB0_129:
	ds_read_b128 v[96:99], v173
	ds_read_b128 v[100:103], v173 offset:1024
	ds_read_b128 v[104:107], v173 offset:2048
	ds_read_b128 v[112:115], v173 offset:3072
	ds_read_b128 v[178:181], v175
	ds_read_b128 v[182:185], v175 offset:1024
	ds_read_b128 v[186:189], v175 offset:2048
	ds_read_b128 v[190:193], v175 offset:3072
	s_add_u32 s44, s8, 0xfff80080
	s_addc_u32 s45, s9, -1
	s_cmp_eq_u32 s54, 28
	s_cselect_b32 s47, s25, s45
	s_cselect_b32 s46, s35, s44
	s_cselect_b32 s45, s23, s49
	s_cselect_b32 s44, s43, s48
	v_lshl_add_u64 v[160:161], s[8:9], 0, v[154:155]
	s_add_i32 m0, s63, 0xc000
	ds_read_b128 v[198:201], v177
	ds_read_b128 v[202:205], v177 offset:1024
	ds_read_b128 v[206:209], v177 offset:2048
	ds_read_b128 v[210:213], v177 offset:3072
	ds_read_b128 v[214:217], v177 offset:4096
	ds_read_b128 v[218:221], v177 offset:5120
	ds_read_b128 v[222:225], v177 offset:6144
	ds_read_b128 v[226:229], v177 offset:7168
	global_load_lds_dwordx4 v[160:161], off
	v_lshl_add_u64 v[160:161], s[8:9], 0, v[156:157]
	s_add_i32 m0, s63, 0xe000
	s_nop 0
	global_load_lds_dwordx4 v[160:161], off
	s_waitcnt vmcnt(8)
	s_waitcnt lgkmcnt(0)
	s_setprio 1
	s_barrier
	v_mfma_f32_16x16x32_bf16 v[140:143], v[96:99], v[198:201], v[140:143]
	v_mfma_f32_16x16x32_bf16 v[132:135], v[104:107], v[198:201], v[132:135]
	v_mfma_f32_16x16x32_bf16 v[116:119], v[96:99], v[206:209], v[116:119]
	v_mfma_f32_16x16x32_bf16 v[124:127], v[104:107], v[206:209], v[124:127]
	v_mfma_f32_16x16x32_bf16 v[84:87], v[96:99], v[214:217], v[84:87]
	v_mfma_f32_16x16x32_bf16 v[92:95], v[104:107], v[214:217], v[92:95]
	v_mfma_f32_16x16x32_bf16 v[68:71], v[96:99], v[222:225], v[68:71]
	v_mfma_f32_16x16x32_bf16 v[76:79], v[104:107], v[222:225], v[76:79]
	v_mfma_f32_16x16x32_bf16 v[140:143], v[100:103], v[202:205], v[140:143]
	v_mfma_f32_16x16x32_bf16 v[132:135], v[112:115], v[202:205], v[132:135]
	v_mfma_f32_16x16x32_bf16 v[116:119], v[100:103], v[210:213], v[116:119]
	v_mfma_f32_16x16x32_bf16 v[124:127], v[112:115], v[210:213], v[124:127]
	v_mfma_f32_16x16x32_bf16 v[84:87], v[100:103], v[218:221], v[84:87]
	v_mfma_f32_16x16x32_bf16 v[92:95], v[112:115], v[218:221], v[92:95]
	v_mfma_f32_16x16x32_bf16 v[68:71], v[100:103], v[226:229], v[68:71]
	v_mfma_f32_16x16x32_bf16 v[76:79], v[112:115], v[226:229], v[76:79]
	v_mfma_f32_16x16x32_bf16 v[128:131], v[178:181], v[198:201], v[128:131]
	v_mfma_f32_16x16x32_bf16 v[136:139], v[186:189], v[198:201], v[136:139]
	v_mfma_f32_16x16x32_bf16 v[120:123], v[178:181], v[206:209], v[120:123]
	v_mfma_f32_16x16x32_bf16 v[108:111], v[186:189], v[206:209], v[108:111]
	v_mfma_f32_16x16x32_bf16 v[88:91], v[178:181], v[214:217], v[88:91]
	v_mfma_f32_16x16x32_bf16 v[80:83], v[186:189], v[214:217], v[80:83]
	v_mfma_f32_16x16x32_bf16 v[72:75], v[178:181], v[222:225], v[72:75]
	v_mfma_f32_16x16x32_bf16 v[64:67], v[186:189], v[222:225], v[64:67]
	v_mfma_f32_16x16x32_bf16 v[128:131], v[182:185], v[202:205], v[128:131]
	v_mfma_f32_16x16x32_bf16 v[136:139], v[190:193], v[202:205], v[136:139]
	v_mfma_f32_16x16x32_bf16 v[120:123], v[182:185], v[210:213], v[120:123]
	v_mfma_f32_16x16x32_bf16 v[108:111], v[190:193], v[210:213], v[108:111]
	v_mfma_f32_16x16x32_bf16 v[88:91], v[182:185], v[218:221], v[88:91]
	v_mfma_f32_16x16x32_bf16 v[80:83], v[190:193], v[218:221], v[80:83]
	v_mfma_f32_16x16x32_bf16 v[72:75], v[182:185], v[226:229], v[72:75]
	v_mfma_f32_16x16x32_bf16 v[64:67], v[190:193], v[226:229], v[64:67]
	s_barrier
	s_setprio 0
	s_add_i32 s55, s52, s62
	v_lshl_add_u64 v[160:161], s[44:45], 0, v[144:145]
	s_mov_b32 m0, s55
	ds_read_b128 v[198:201], v177 offset:16384
	ds_read_b128 v[202:205], v177 offset:17408
	ds_read_b128 v[206:209], v177 offset:18432
	ds_read_b128 v[210:213], v177 offset:19456
	ds_read_b128 v[214:217], v177 offset:20480
	ds_read_b128 v[218:221], v177 offset:21504
	ds_read_b128 v[222:225], v177 offset:22528
	ds_read_b128 v[226:229], v177 offset:23552
	global_load_lds_dwordx4 v[160:161], off
	s_add_i32 m0, s55, 0x2000
	s_add_u32 s56, s44, 0x80000
	v_lshl_add_u64 v[164:165], s[44:45], 0, v[146:147]
	s_addc_u32 s57, s45, 0
	s_add_i32 s55, s53, s62
	global_load_lds_dwordx4 v[164:165], off
	v_lshl_add_u64 v[170:171], s[56:57], 0, v[144:145]
	s_mov_b32 m0, s55
	v_lshl_add_u64 v[194:195], s[46:47], 0, v[146:147]
	global_load_lds_dwordx4 v[170:171], off
	v_lshl_add_u64 v[170:171], s[56:57], 0, v[146:147]
	s_add_i32 m0, s55, 0x2000
	s_nop 0
	global_load_lds_dwordx4 v[170:171], off
	v_lshl_add_u64 v[170:171], s[46:47], 0, v[144:145]
	s_mov_b32 m0, s63
	s_nop 0
	global_load_lds_dwordx4 v[170:171], off
	s_mov_b32 m0, s64
	s_nop 0
	global_load_lds_dwordx4 v[194:195], off
	s_waitcnt vmcnt(8)
	s_waitcnt lgkmcnt(0)
	s_setprio 1
	s_barrier
; #define PG8_STAGE(bufoff, gbase, voff) do { _Pragma("unroll") for (int _i = 0; _i < 2; ++_i) \
;         __builtin_amdgcn_global_load_lds((const unsigned*)((const char*)(gbase) + (voff)[_i]), (PG8_LAS unsigned*)(lds + (bufoff) + ldsw + _i * 8192), 16, 0, 0); } while (0)
; #define PG8_LDA(dst, b, h) do { _Pragma("unroll") for (int m = 0; m < 4; ++m) _Pragma("unroll") for (int k = 0; k < 2; ++k) dst[m][k] = *(const PG8_LAS bf16x8*)(lds + PG8_SA(b, h) + aoff + m * 2048 + k * 1024); } while (0)
; #define PG8_LDB(dst, b, h) do { _Pragma("unroll") for (int n = 0; n < 2; ++n) _Pragma("unroll") for (int k = 0; k < 2; ++k) dst[n][k] = *(const PG8_LAS bf16x8*)(lds + PG8_SB(b, h) + boff + n * 2048 + k * 1024); } while (0)
; #define PG8_MMA(ai, bj, At, Bt) do { __builtin_amdgcn_s_setprio(1); _Pragma("unroll") for (int m = 0; m < 4; ++m) _Pragma("unroll") for (int n = 0; n < 2; ++n) _Pragma("unroll") for (int k = 0; k < 2; ++k) \
;         acc[ai][bj][m][n] = __builtin_amdgcn_mfma_f32_16x16x32_bf16(Bt[n][k], At[m][k], acc[ai][bj][m][n], 0, 0, 0); __builtin_amdgcn_s_setprio(0); } while (0)
; #define PG8_WAIT_V(n) asm volatile("s_waitcnt vmcnt(" #n ")" ::: "memory")
; #define PG8_WAIT_L(n) asm volatile("s_waitcnt lgkmcnt(" #n ")" ::: "memory")
; #define PG8_BAR __builtin_amdgcn_s_barrier()
; #define PG8_SCHED __builtin_amdgcn_sched_barrier(0)
; template <class Epi, class Sched, bool ALIGN_EPI = false, bool SP2 = false>
; __device__ __forceinline__ void gemm_phase(PG8_LAS unsigned char* lds, const Gemm g, const Sched& S, const Epi& E) {
;     ...
;             PG8_WAIT_V(8); PG8_WAIT_L(0); PG8_BAR; PG8_MMA(1, 0, At, B0); PG8_MMA(1, 1, At, B1); PG8_BAR; PG8_SCHED;
;             PG8_LDB(B0, 1, 0); PG8_LDB(B1, 1, 1); PG8_SCHED; PG8_LDA(At, 1, 0); PG8_STAGE(PG8_SA(0, 1), a2 + hstep, voffA);
;             PG8_WAIT_V(8); PG8_WAIT_L(0); PG8_BAR; PG8_MMA(0, 0, At, B0); PG8_MMA(0, 1, At, B1); PG8_BAR; PG8_SCHED;
	v_mfma_f32_16x16x32_bf16 v[60:63], v[96:99], v[198:201], v[60:63]
	v_mfma_f32_16x16x32_bf16 v[52:55], v[104:107], v[198:201], v[52:55]
	v_mfma_f32_16x16x32_bf16 v[36:39], v[96:99], v[206:209], v[36:39]
	v_mfma_f32_16x16x32_bf16 v[44:47], v[104:107], v[206:209], v[44:47]
	v_mfma_f32_16x16x32_bf16 v[20:23], v[96:99], v[214:217], v[20:23]
	v_mfma_f32_16x16x32_bf16 v[28:31], v[104:107], v[214:217], v[28:31]
	v_mfma_f32_16x16x32_bf16 v[4:7], v[96:99], v[222:225], v[4:7]
	v_mfma_f32_16x16x32_bf16 v[12:15], v[104:107], v[222:225], v[12:15]
	v_mfma_f32_16x16x32_bf16 v[60:63], v[100:103], v[202:205], v[60:63]
	v_mfma_f32_16x16x32_bf16 v[52:55], v[112:115], v[202:205], v[52:55]
	v_mfma_f32_16x16x32_bf16 v[36:39], v[100:103], v[210:213], v[36:39]
	v_mfma_f32_16x16x32_bf16 v[44:47], v[112:115], v[210:213], v[44:47]
	v_mfma_f32_16x16x32_bf16 v[20:23], v[100:103], v[218:221], v[20:23]
	v_mfma_f32_16x16x32_bf16 v[28:31], v[112:115], v[218:221], v[28:31]
	v_mfma_f32_16x16x32_bf16 v[4:7], v[100:103], v[226:229], v[4:7]
	v_mfma_f32_16x16x32_bf16 v[12:15], v[112:115], v[226:229], v[12:15]
	v_mfma_f32_16x16x32_bf16 v[48:51], v[178:181], v[198:201], v[48:51]
	v_mfma_f32_16x16x32_bf16 v[56:59], v[186:189], v[198:201], v[56:59]
	v_mfma_f32_16x16x32_bf16 v[40:43], v[178:181], v[206:209], v[40:43]
	v_mfma_f32_16x16x32_bf16 v[32:35], v[186:189], v[206:209], v[32:35]
	v_mfma_f32_16x16x32_bf16 v[24:27], v[178:181], v[214:217], v[24:27]
	v_mfma_f32_16x16x32_bf16 v[16:19], v[186:189], v[214:217], v[16:19]
	v_mfma_f32_16x16x32_bf16 v[8:11], v[178:181], v[222:225], v[8:11]
	v_mfma_f32_16x16x32_bf16 v[0:3], v[186:189], v[222:225], v[0:3]
	v_mfma_f32_16x16x32_bf16 v[48:51], v[182:185], v[202:205], v[48:51]
	v_mfma_f32_16x16x32_bf16 v[56:59], v[190:193], v[202:205], v[56:59]
	v_mfma_f32_16x16x32_bf16 v[40:43], v[182:185], v[210:213], v[40:43]
	v_mfma_f32_16x16x32_bf16 v[32:35], v[190:193], v[210:213], v[32:35]
	v_mfma_f32_16x16x32_bf16 v[24:27], v[182:185], v[218:221], v[24:27]
	v_mfma_f32_16x16x32_bf16 v[16:19], v[190:193], v[218:221], v[16:19]
	v_mfma_f32_16x16x32_bf16 v[8:11], v[182:185], v[226:229], v[8:11]
	v_mfma_f32_16x16x32_bf16 v[0:3], v[190:193], v[226:229], v[0:3]
	s_barrier
	s_setprio 0
	s_add_i32 s55, 0, 0x18000
	s_add_i32 s56, 0, 0x1c000
	v_add_u32_e32 v112, s55, v167
	v_add_u32_e32 v162, s56, v167
	ds_read_b128 v[96:99], v112
	ds_read_b128 v[100:103], v112 offset:1024
	ds_read_b128 v[104:107], v112 offset:2048
	ds_read_b128 v[112:115], v112 offset:3072
	ds_read_b128 v[178:181], v162
	ds_read_b128 v[182:185], v162 offset:1024
	ds_read_b128 v[186:189], v162 offset:2048
	ds_read_b128 v[190:193], v162 offset:3072
	s_add_u32 s46, s46, 0x80000
	s_addc_u32 s47, s47, 0
	s_mov_b32 m0, s65
	v_lshl_add_u64 v[230:231], s[46:47], 0, v[144:145]
	ds_read_b128 v[198:201], v177 offset:32768
	ds_read_b128 v[202:205], v177 offset:33792
	ds_read_b128 v[206:209], v177 offset:34816
	ds_read_b128 v[210:213], v177 offset:35840
	ds_read_b128 v[214:217], v177 offset:36864
	ds_read_b128 v[218:221], v177 offset:37888
	ds_read_b128 v[222:225], v177 offset:38912
	ds_read_b128 v[226:229], v177 offset:39936
	global_load_lds_dwordx4 v[230:231], off
	v_lshl_add_u64 v[230:231], s[46:47], 0, v[146:147]
	s_mov_b32 m0, s66
	s_nop 0
	global_load_lds_dwordx4 v[230:231], off
	s_waitcnt vmcnt(8)
	s_waitcnt lgkmcnt(0)
	s_setprio 1
	s_barrier
	v_mfma_f32_16x16x32_bf16 v[140:143], v[96:99], v[198:201], v[140:143]
	v_mfma_f32_16x16x32_bf16 v[132:135], v[104:107], v[198:201], v[132:135]
	v_mfma_f32_16x16x32_bf16 v[116:119], v[96:99], v[206:209], v[116:119]
	v_mfma_f32_16x16x32_bf16 v[124:127], v[104:107], v[206:209], v[124:127]
	v_mfma_f32_16x16x32_bf16 v[84:87], v[96:99], v[214:217], v[84:87]
	v_mfma_f32_16x16x32_bf16 v[92:95], v[104:107], v[214:217], v[92:95]
	v_mfma_f32_16x16x32_bf16 v[68:71], v[96:99], v[222:225], v[68:71]
	v_mfma_f32_16x16x32_bf16 v[76:79], v[104:107], v[222:225], v[76:79]
	v_mfma_f32_16x16x32_bf16 v[140:143], v[100:103], v[202:205], v[140:143]
	v_mfma_f32_16x16x32_bf16 v[132:135], v[112:115], v[202:205], v[132:135]
	v_mfma_f32_16x16x32_bf16 v[116:119], v[100:103], v[210:213], v[116:119]
	v_mfma_f32_16x16x32_bf16 v[124:127], v[112:115], v[210:213], v[124:127]
	v_mfma_f32_16x16x32_bf16 v[84:87], v[100:103], v[218:221], v[84:87]
	v_mfma_f32_16x16x32_bf16 v[92:95], v[112:115], v[218:221], v[92:95]
	v_mfma_f32_16x16x32_bf16 v[68:71], v[100:103], v[226:229], v[68:71]
	v_mfma_f32_16x16x32_bf16 v[76:79], v[112:115], v[226:229], v[76:79]
	v_mfma_f32_16x16x32_bf16 v[128:131], v[178:181], v[198:201], v[128:131]
	v_mfma_f32_16x16x32_bf16 v[136:139], v[186:189], v[198:201], v[136:139]
	v_mfma_f32_16x16x32_bf16 v[120:123], v[178:181], v[206:209], v[120:123]
	v_mfma_f32_16x16x32_bf16 v[108:111], v[186:189], v[206:209], v[108:111]
	v_mfma_f32_16x16x32_bf16 v[88:91], v[178:181], v[214:217], v[88:91]
	v_mfma_f32_16x16x32_bf16 v[80:83], v[186:189], v[214:217], v[80:83]
	v_mfma_f32_16x16x32_bf16 v[72:75], v[178:181], v[222:225], v[72:75]
	v_mfma_f32_16x16x32_bf16 v[64:67], v[186:189], v[222:225], v[64:67]
	v_mfma_f32_16x16x32_bf16 v[128:131], v[182:185], v[202:205], v[128:131]
	v_mfma_f32_16x16x32_bf16 v[136:139], v[190:193], v[202:205], v[136:139]
	v_mfma_f32_16x16x32_bf16 v[120:123], v[182:185], v[210:213], v[120:123]
	v_mfma_f32_16x16x32_bf16 v[108:111], v[190:193], v[210:213], v[108:111]
	v_mfma_f32_16x16x32_bf16 v[88:91], v[182:185], v[218:221], v[88:91]
	v_mfma_f32_16x16x32_bf16 v[80:83], v[190:193], v[218:221], v[80:83]
	v_mfma_f32_16x16x32_bf16 v[72:75], v[182:185], v[226:229], v[72:75]
	v_mfma_f32_16x16x32_bf16 v[64:67], v[190:193], v[226:229], v[64:67]
	s_barrier
; #define PG8_STAGE(bufoff, gbase, voff) do { _Pragma("unroll") for (int _i = 0; _i < 2; ++_i) \
;         __builtin_amdgcn_global_load_lds((const unsigned*)((const char*)(gbase) + (voff)[_i]), (PG8_LAS unsigned*)(lds + (bufoff) + ldsw + _i * 8192), 16, 0, 0); } while (0)
; #define PG8_LDA(dst, b, h) do { _Pragma("unroll") for (int m = 0; m < 4; ++m) _Pragma("unroll") for (int k = 0; k < 2; ++k) dst[m][k] = *(const PG8_LAS bf16x8*)(lds + PG8_SA(b, h) + aoff + m * 2048 + k * 1024); } while (0)
; #define PG8_MMA(ai, bj, At, Bt) do { __builtin_amdgcn_s_setprio(1); _Pragma("unroll") for (int m = 0; m < 4; ++m) _Pragma("unroll") for (int n = 0; n < 2; ++n) _Pragma("unroll") for (int k = 0; k < 2; ++k) \
;         acc[ai][bj][m][n] = __builtin_amdgcn_mfma_f32_16x16x32_bf16(Bt[n][k], At[m][k], acc[ai][bj][m][n], 0, 0, 0); __builtin_amdgcn_s_setprio(0); } while (0)
; #define PG8_WAIT_V(n) asm volatile("s_waitcnt vmcnt(" #n ")" ::: "memory")
; #define PG8_WAIT_L(n) asm volatile("s_waitcnt lgkmcnt(" #n ")" ::: "memory")
; #define PG8_BAR __builtin_amdgcn_s_barrier()
; #define PG8_SCHED __builtin_amdgcn_sched_barrier(0)
; template <class Epi, class Sched, bool ALIGN_EPI = false, bool SP2 = false>
; __device__ __forceinline__ void gemm_phase(PG8_LAS unsigned char* lds, const Gemm g, const Sched& S, const Epi& E) {
;     ...
;             PG8_WAIT_V(8); PG8_WAIT_L(0); PG8_BAR; PG8_MMA(0, 0, At, B0); PG8_MMA(0, 1, At, B1); PG8_BAR; PG8_SCHED;
;             PG8_LDA(At, 1, 1); PG8_STAGE(PG8_SB(1, 0), b3, voffB); PG8_STAGE(PG8_SB(1, 1), b3 + hstep, voffB); PG8_STAGE(PG8_SA(1, 0), a3, voffA);
;             PG8_WAIT_V(8); PG8_WAIT_L(0); PG8_BAR; PG8_MMA(1, 0, At, B0); PG8_MMA(1, 1, At, B1); PG8_BAR; PG8_SCHED;
;     ...
;         if constexpr (ALIGN_EPI) { if (wr == 0) PG8_BAR; }
	s_setprio 0
	s_add_i32 s46, s55, s62
	v_lshl_add_u64 v[160:161], v[160:161], 0, s[12:13]
	s_mov_b32 m0, s46
	ds_read_b128 v[198:201], v177 offset:49152
	ds_read_b128 v[202:205], v177 offset:50176
	ds_read_b128 v[206:209], v177 offset:51200
	ds_read_b128 v[210:213], v177 offset:52224
	ds_read_b128 v[214:217], v177 offset:53248
	ds_read_b128 v[218:221], v177 offset:54272
	ds_read_b128 v[222:225], v177 offset:55296
	ds_read_b128 v[226:229], v177 offset:56320
	global_load_lds_dwordx4 v[160:161], off
	s_add_i32 m0, s46, 0x2000
	s_add_u32 s44, s44, 0x80080
	v_lshl_add_u64 v[160:161], v[164:165], 0, s[12:13]
	s_addc_u32 s45, s45, 0
	s_add_i32 s46, s56, s62
	global_load_lds_dwordx4 v[160:161], off
	v_lshl_add_u64 v[160:161], s[44:45], 0, v[144:145]
	s_mov_b32 m0, s46
	s_nop 0
	global_load_lds_dwordx4 v[160:161], off
	v_lshl_add_u64 v[160:161], s[44:45], 0, v[146:147]
	s_add_i32 m0, s46, 0x2000
	s_nop 0
	global_load_lds_dwordx4 v[160:161], off
	v_lshl_add_u64 v[160:161], v[170:171], 0, s[12:13]
	s_mov_b32 m0, s68
	s_nop 0
	global_load_lds_dwordx4 v[160:161], off
	v_lshl_add_u64 v[160:161], v[194:195], 0, s[12:13]
	s_mov_b32 m0, s69
	s_nop 0
	global_load_lds_dwordx4 v[160:161], off
	s_waitcnt vmcnt(8)
	s_waitcnt lgkmcnt(0)
	s_setprio 1
	s_barrier
	v_mfma_f32_16x16x32_bf16 v[60:63], v[96:99], v[198:201], v[60:63]
	v_mfma_f32_16x16x32_bf16 v[52:55], v[104:107], v[198:201], v[52:55]
	v_mfma_f32_16x16x32_bf16 v[36:39], v[96:99], v[206:209], v[36:39]
	v_mfma_f32_16x16x32_bf16 v[44:47], v[104:107], v[206:209], v[44:47]
	v_mfma_f32_16x16x32_bf16 v[20:23], v[96:99], v[214:217], v[20:23]
	v_mfma_f32_16x16x32_bf16 v[28:31], v[104:107], v[214:217], v[28:31]
	v_mfma_f32_16x16x32_bf16 v[4:7], v[96:99], v[222:225], v[4:7]
	v_mfma_f32_16x16x32_bf16 v[12:15], v[104:107], v[222:225], v[12:15]
	v_mfma_f32_16x16x32_bf16 v[60:63], v[100:103], v[202:205], v[60:63]
	v_mfma_f32_16x16x32_bf16 v[52:55], v[112:115], v[202:205], v[52:55]
	v_mfma_f32_16x16x32_bf16 v[36:39], v[100:103], v[210:213], v[36:39]
	v_mfma_f32_16x16x32_bf16 v[44:47], v[112:115], v[210:213], v[44:47]
	v_mfma_f32_16x16x32_bf16 v[20:23], v[100:103], v[218:221], v[20:23]
	v_mfma_f32_16x16x32_bf16 v[28:31], v[112:115], v[218:221], v[28:31]
	v_mfma_f32_16x16x32_bf16 v[4:7], v[100:103], v[226:229], v[4:7]
	v_mfma_f32_16x16x32_bf16 v[12:15], v[112:115], v[226:229], v[12:15]
	v_mfma_f32_16x16x32_bf16 v[48:51], v[178:181], v[198:201], v[48:51]
	v_mfma_f32_16x16x32_bf16 v[56:59], v[186:189], v[198:201], v[56:59]
	v_mfma_f32_16x16x32_bf16 v[40:43], v[178:181], v[206:209], v[40:43]
	v_mfma_f32_16x16x32_bf16 v[32:35], v[186:189], v[206:209], v[32:35]
	v_mfma_f32_16x16x32_bf16 v[24:27], v[178:181], v[214:217], v[24:27]
	v_mfma_f32_16x16x32_bf16 v[16:19], v[186:189], v[214:217], v[16:19]
	v_mfma_f32_16x16x32_bf16 v[8:11], v[178:181], v[222:225], v[8:11]
	v_mfma_f32_16x16x32_bf16 v[0:3], v[186:189], v[222:225], v[0:3]
	v_mfma_f32_16x16x32_bf16 v[48:51], v[182:185], v[202:205], v[48:51]
	v_mfma_f32_16x16x32_bf16 v[56:59], v[190:193], v[202:205], v[56:59]
	v_mfma_f32_16x16x32_bf16 v[40:43], v[182:185], v[210:213], v[40:43]
	v_mfma_f32_16x16x32_bf16 v[32:35], v[190:193], v[210:213], v[32:35]
	v_mfma_f32_16x16x32_bf16 v[24:27], v[182:185], v[218:221], v[24:27]
	v_mfma_f32_16x16x32_bf16 v[16:19], v[190:193], v[218:221], v[16:19]
	v_mfma_f32_16x16x32_bf16 v[8:11], v[182:185], v[226:229], v[8:11]
	v_mfma_f32_16x16x32_bf16 v[0:3], v[190:193], v[226:229], v[0:3]
	s_barrier
	s_setprio 0
	s_add_i32 s54, s54, 2
	s_add_u32 s8, s8, 0x100
	s_addc_u32 s9, s9, 0
	s_add_u32 s48, s48, 0x100
	s_addc_u32 s49, s49, 0
	s_cmp_gt_u32 s54, 29
	s_cbranch_scc0 .LBB0_129
	s_and_b64 vcc, exec, s[14:15]
	s_cbranch_vccz .LBB0_132
	s_barrier

; #define PG8_STAGE(bufoff, gbase, voff) do { _Pragma("unroll") for (int _i = 0; _i < 2; ++_i) \
;         __builtin_amdgcn_global_load_lds((const unsigned*)((const char*)(gbase) + (voff)[_i]), (PG8_LAS unsigned*)(lds + (bufoff) + ldsw + _i * 8192), 16, 0, 0); } while (0)
; #define PG8_LDA(dst, b, h) do { _Pragma("unroll") for (int m = 0; m < 4; ++m) _Pragma("unroll") for (int k = 0; k < 2; ++k) dst[m][k] = *(const PG8_LAS bf16x8*)(lds + PG8_SA(b, h) + aoff + m * 2048 + k * 1024); } while (0)
; #define PG8_LDB(dst, b, h) do { _Pragma("unroll") for (int n = 0; n < 2; ++n) _Pragma("unroll") for (int k = 0; k < 2; ++k) dst[n][k] = *(const PG8_LAS bf16x8*)(lds + PG8_SB(b, h) + boff + n * 2048 + k * 1024); } while (0)
; #define PG8_MMA(ai, bj, At, Bt) do { __builtin_amdgcn_s_setprio(1); _Pragma("unroll") for (int m = 0; m < 4; ++m) _Pragma("unroll") for (int n = 0; n < 2; ++n) _Pragma("unroll") for (int k = 0; k < 2; ++k) \
;         acc[ai][bj][m][n] = __builtin_amdgcn_mfma_f32_16x16x32_bf16(Bt[n][k], At[m][k], acc[ai][bj][m][n], 0, 0, 0); __builtin_amdgcn_s_setprio(0); } while (0)
; #define PG8_WAIT_V(n) asm volatile("s_waitcnt vmcnt(" #n ")" ::: "memory")
; #define PG8_WAIT_L(n) asm volatile("s_waitcnt lgkmcnt(" #n ")" ::: "memory")
; template <class Epi, class Sched, bool ALIGN_EPI = false, bool SP2 = false>
; __device__ __forceinline__ void gemm_phase(PG8_LAS unsigned char* lds, const Gemm g, const Sched& S, const Epi& E) {
;     ...
;             const bool last = (t == nt - 2);
;             const char* a1 = cA + (size_t)(t + 1) * kstep;
;             const char* a2 = last ? nA : cA + (size_t)(t + 2) * kstep; const char* b2 = last ? nB : cB + (size_t)(t + 2) * kstep;
;             const char* a3 = a2 + kstep; const char* b3 = b2 + kstep;
;             if (last && has_next) S.a_ready(nxt);
;             if constexpr (SP2) {
;             PG8_LDB(B0, 0, 0); PG8_LDB(B1, 0, 1); PG8_SCHED; PG8_LDA(At, 0, 0); PG8_STAGE(PG8_SA(1, 1), a1 + hstep, voffA);
;             PG8_WAIT_V(8); PG8_WAIT_L(0); PG8_BAR; PG8_MMA(0, 0, At, B0); PG8_MMA(0, 1, At, B1); PG8_BAR; PG8_SCHED;
;             PG8_LDA(At, 0, 1); PG8_STAGE(PG8_SB(0, 0), b2, voffB); PG8_STAGE(PG8_SB(0, 1), b2 + hstep, voffB); PG8_STAGE(PG8_SA(0, 0), a2, voffA);
;             PG8_WAIT_V(8); PG8_WAIT_L(0); PG8_BAR; PG8_MMA(1, 0, At, B0); PG8_MMA(1, 1, At, B1); PG8_BAR; PG8_SCHED;
.LBB0_307:
	ds_read_b128 v[128:131], v181
	ds_read_b128 v[132:135], v181 offset:1024
	ds_read_b128 v[136:139], v181 offset:2048
	ds_read_b128 v[140:143], v181 offset:3072
	ds_read_b128 v[144:147], v182
	ds_read_b128 v[148:151], v182 offset:1024
	ds_read_b128 v[168:171], v182 offset:2048
	ds_read_b128 v[172:175], v182 offset:3072
	s_add_u32 s28, s26, 0xfff80080
	s_addc_u32 s29, s27, -1
	s_cmp_eq_u32 s50, 28
	s_cselect_b32 s31, s7, s29
	s_cselect_b32 s30, s21, s28
	s_cselect_b32 s29, s19, s49
	s_cselect_b32 s28, s33, s48
	v_lshl_add_u64 v[176:177], s[26:27], 0, v[160:161]
	s_add_i32 m0, s35, 0xc000
	ds_read_b128 v[186:189], v183
	ds_read_b128 v[190:193], v183 offset:1024
	ds_read_b128 v[198:201], v183 offset:2048
	ds_read_b128 v[202:205], v183 offset:3072
	ds_read_b128 v[206:209], v183 offset:4096
	ds_read_b128 v[210:213], v183 offset:5120
	ds_read_b128 v[214:217], v183 offset:6144
	ds_read_b128 v[218:221], v183 offset:7168
	global_load_lds_dwordx4 v[176:177], off
	v_lshl_add_u64 v[176:177], s[26:27], 0, v[162:163]
	s_add_i32 m0, s35, 0xe000
	s_nop 0
	global_load_lds_dwordx4 v[176:177], off
	s_waitcnt vmcnt(8)
	s_waitcnt lgkmcnt(0)
	s_setprio 1
	s_barrier
	v_mfma_f32_16x16x32_bf16 v[124:127], v[128:131], v[186:189], v[124:127]
	v_mfma_f32_16x16x32_bf16 v[120:123], v[136:139], v[186:189], v[120:123]
	v_mfma_f32_16x16x32_bf16 v[104:107], v[128:131], v[198:201], v[104:107]
	v_mfma_f32_16x16x32_bf16 v[108:111], v[136:139], v[198:201], v[108:111]
	v_mfma_f32_16x16x32_bf16 v[88:91], v[128:131], v[206:209], v[88:91]
	v_mfma_f32_16x16x32_bf16 v[92:95], v[136:139], v[206:209], v[92:95]
	v_mfma_f32_16x16x32_bf16 v[72:75], v[128:131], v[214:217], v[72:75]
	v_mfma_f32_16x16x32_bf16 v[76:79], v[136:139], v[214:217], v[76:79]
	v_mfma_f32_16x16x32_bf16 v[124:127], v[132:135], v[190:193], v[124:127]
	v_mfma_f32_16x16x32_bf16 v[120:123], v[140:143], v[190:193], v[120:123]
	v_mfma_f32_16x16x32_bf16 v[104:107], v[132:135], v[202:205], v[104:107]
	v_mfma_f32_16x16x32_bf16 v[108:111], v[140:143], v[202:205], v[108:111]
	v_mfma_f32_16x16x32_bf16 v[88:91], v[132:135], v[210:213], v[88:91]
	v_mfma_f32_16x16x32_bf16 v[92:95], v[140:143], v[210:213], v[92:95]
	v_mfma_f32_16x16x32_bf16 v[72:75], v[132:135], v[218:221], v[72:75]
	v_mfma_f32_16x16x32_bf16 v[76:79], v[140:143], v[218:221], v[76:79]
	v_mfma_f32_16x16x32_bf16 v[116:119], v[144:147], v[186:189], v[116:119]
	v_mfma_f32_16x16x32_bf16 v[112:115], v[168:171], v[186:189], v[112:115]
	v_mfma_f32_16x16x32_bf16 v[100:103], v[144:147], v[198:201], v[100:103]
	v_mfma_f32_16x16x32_bf16 v[96:99], v[168:171], v[198:201], v[96:99]
	v_mfma_f32_16x16x32_bf16 v[84:87], v[144:147], v[206:209], v[84:87]
	v_mfma_f32_16x16x32_bf16 v[80:83], v[168:171], v[206:209], v[80:83]
	v_mfma_f32_16x16x32_bf16 v[68:71], v[144:147], v[214:217], v[68:71]
	v_mfma_f32_16x16x32_bf16 v[64:67], v[168:171], v[214:217], v[64:67]
	v_mfma_f32_16x16x32_bf16 v[116:119], v[148:151], v[190:193], v[116:119]
	v_mfma_f32_16x16x32_bf16 v[112:115], v[172:175], v[190:193], v[112:115]
	v_mfma_f32_16x16x32_bf16 v[100:103], v[148:151], v[202:205], v[100:103]
	v_mfma_f32_16x16x32_bf16 v[96:99], v[172:175], v[202:205], v[96:99]
	v_mfma_f32_16x16x32_bf16 v[84:87], v[148:151], v[210:213], v[84:87]
	v_mfma_f32_16x16x32_bf16 v[80:83], v[172:175], v[210:213], v[80:83]
	v_mfma_f32_16x16x32_bf16 v[68:71], v[148:151], v[218:221], v[68:71]
	v_mfma_f32_16x16x32_bf16 v[64:67], v[172:175], v[218:221], v[64:67]
	s_barrier
	s_setprio 0
	s_add_i32 s51, s62, s34
	v_lshl_add_u64 v[176:177], s[28:29], 0, v[154:155]
	s_mov_b32 m0, s51
	ds_read_b128 v[186:189], v183 offset:16384
	ds_read_b128 v[190:193], v183 offset:17408
	ds_read_b128 v[198:201], v183 offset:18432
	ds_read_b128 v[202:205], v183 offset:19456
	ds_read_b128 v[206:209], v183 offset:20480
	ds_read_b128 v[210:213], v183 offset:21504
	ds_read_b128 v[214:217], v183 offset:22528
	ds_read_b128 v[218:221], v183 offset:23552
	global_load_lds_dwordx4 v[176:177], off
	s_add_i32 m0, s51, 0x2000
	s_add_u32 s52, s28, 0x80000
	v_lshl_add_u64 v[194:195], s[28:29], 0, v[158:159]
	s_addc_u32 s53, s29, 0
	s_add_i32 s51, s63, s34
	global_load_lds_dwordx4 v[194:195], off
	v_lshl_add_u64 v[222:223], s[52:53], 0, v[154:155]
	s_mov_b32 m0, s51
	v_lshl_add_u64 v[224:225], s[30:31], 0, v[156:157]
	global_load_lds_dwordx4 v[222:223], off
	v_lshl_add_u64 v[222:223], s[52:53], 0, v[158:159]
	s_add_i32 m0, s51, 0x2000
	s_nop 0
	global_load_lds_dwordx4 v[222:223], off
	v_lshl_add_u64 v[222:223], s[30:31], 0, v[152:153]
	s_mov_b32 m0, s35
	s_nop 0
	global_load_lds_dwordx4 v[222:223], off
	s_mov_b32 m0, s37
	s_nop 0
	global_load_lds_dwordx4 v[224:225], off
	s_waitcnt vmcnt(8)
	s_waitcnt lgkmcnt(0)
	s_setprio 1
	s_barrier
; #define PG8_STAGE(bufoff, gbase, voff) do { _Pragma("unroll") for (int _i = 0; _i < 2; ++_i) \
;         __builtin_amdgcn_global_load_lds((const unsigned*)((const char*)(gbase) + (voff)[_i]), (PG8_LAS unsigned*)(lds + (bufoff) + ldsw + _i * 8192), 16, 0, 0); } while (0)
; #define PG8_LDA(dst, b, h) do { _Pragma("unroll") for (int m = 0; m < 4; ++m) _Pragma("unroll") for (int k = 0; k < 2; ++k) dst[m][k] = *(const PG8_LAS bf16x8*)(lds + PG8_SA(b, h) + aoff + m * 2048 + k * 1024); } while (0)
; #define PG8_LDB(dst, b, h) do { _Pragma("unroll") for (int n = 0; n < 2; ++n) _Pragma("unroll") for (int k = 0; k < 2; ++k) dst[n][k] = *(const PG8_LAS bf16x8*)(lds + PG8_SB(b, h) + boff + n * 2048 + k * 1024); } while (0)
; #define PG8_MMA(ai, bj, At, Bt) do { __builtin_amdgcn_s_setprio(1); _Pragma("unroll") for (int m = 0; m < 4; ++m) _Pragma("unroll") for (int n = 0; n < 2; ++n) _Pragma("unroll") for (int k = 0; k < 2; ++k) \
;         acc[ai][bj][m][n] = __builtin_amdgcn_mfma_f32_16x16x32_bf16(Bt[n][k], At[m][k], acc[ai][bj][m][n], 0, 0, 0); __builtin_amdgcn_s_setprio(0); } while (0)
; #define PG8_WAIT_V(n) asm volatile("s_waitcnt vmcnt(" #n ")" ::: "memory")
; #define PG8_WAIT_L(n) asm volatile("s_waitcnt lgkmcnt(" #n ")" ::: "memory")
; #define PG8_BAR __builtin_amdgcn_s_barrier()
; #define PG8_SCHED __builtin_amdgcn_sched_barrier(0)
; template <class Epi, class Sched, bool ALIGN_EPI = false, bool SP2 = false>
; __device__ __forceinline__ void gemm_phase(PG8_LAS unsigned char* lds, const Gemm g, const Sched& S, const Epi& E) {
;     ...
;             PG8_WAIT_V(8); PG8_WAIT_L(0); PG8_BAR; PG8_MMA(1, 0, At, B0); PG8_MMA(1, 1, At, B1); PG8_BAR; PG8_SCHED;
;             PG8_LDB(B0, 1, 0); PG8_LDB(B1, 1, 1); PG8_SCHED; PG8_LDA(At, 1, 0); PG8_STAGE(PG8_SA(0, 1), a2 + hstep, voffA);
;             PG8_WAIT_V(8); PG8_WAIT_L(0); PG8_BAR; PG8_MMA(0, 0, At, B0); PG8_MMA(0, 1, At, B1); PG8_BAR; PG8_SCHED;
	v_mfma_f32_16x16x32_bf16 v[56:59], v[128:131], v[186:189], v[56:59]
	v_mfma_f32_16x16x32_bf16 v[60:63], v[136:139], v[186:189], v[60:63]
	v_mfma_f32_16x16x32_bf16 v[40:43], v[128:131], v[198:201], v[40:43]
	v_mfma_f32_16x16x32_bf16 v[44:47], v[136:139], v[198:201], v[44:47]
	v_mfma_f32_16x16x32_bf16 v[24:27], v[128:131], v[206:209], v[24:27]
	v_mfma_f32_16x16x32_bf16 v[28:31], v[136:139], v[206:209], v[28:31]
	v_mfma_f32_16x16x32_bf16 v[8:11], v[128:131], v[214:217], v[8:11]
	v_mfma_f32_16x16x32_bf16 v[12:15], v[136:139], v[214:217], v[12:15]
	v_mfma_f32_16x16x32_bf16 v[56:59], v[132:135], v[190:193], v[56:59]
	v_mfma_f32_16x16x32_bf16 v[60:63], v[140:143], v[190:193], v[60:63]
	v_mfma_f32_16x16x32_bf16 v[40:43], v[132:135], v[202:205], v[40:43]
	v_mfma_f32_16x16x32_bf16 v[44:47], v[140:143], v[202:205], v[44:47]
	v_mfma_f32_16x16x32_bf16 v[24:27], v[132:135], v[210:213], v[24:27]
	v_mfma_f32_16x16x32_bf16 v[28:31], v[140:143], v[210:213], v[28:31]
	v_mfma_f32_16x16x32_bf16 v[8:11], v[132:135], v[218:221], v[8:11]
	v_mfma_f32_16x16x32_bf16 v[12:15], v[140:143], v[218:221], v[12:15]
	v_mfma_f32_16x16x32_bf16 v[52:55], v[144:147], v[186:189], v[52:55]
	v_mfma_f32_16x16x32_bf16 v[48:51], v[168:171], v[186:189], v[48:51]
	v_mfma_f32_16x16x32_bf16 v[36:39], v[144:147], v[198:201], v[36:39]
	v_mfma_f32_16x16x32_bf16 v[32:35], v[168:171], v[198:201], v[32:35]
	v_mfma_f32_16x16x32_bf16 v[20:23], v[144:147], v[206:209], v[20:23]
	v_mfma_f32_16x16x32_bf16 v[16:19], v[168:171], v[206:209], v[16:19]
	v_mfma_f32_16x16x32_bf16 v[4:7], v[144:147], v[214:217], v[4:7]
	v_mfma_f32_16x16x32_bf16 v[0:3], v[168:171], v[214:217], v[0:3]
	v_mfma_f32_16x16x32_bf16 v[52:55], v[148:151], v[190:193], v[52:55]
	v_mfma_f32_16x16x32_bf16 v[48:51], v[172:175], v[190:193], v[48:51]
	v_mfma_f32_16x16x32_bf16 v[36:39], v[148:151], v[202:205], v[36:39]
	v_mfma_f32_16x16x32_bf16 v[32:35], v[172:175], v[202:205], v[32:35]
	v_mfma_f32_16x16x32_bf16 v[20:23], v[148:151], v[210:213], v[20:23]
	v_mfma_f32_16x16x32_bf16 v[16:19], v[172:175], v[210:213], v[16:19]
	v_mfma_f32_16x16x32_bf16 v[4:7], v[148:151], v[218:221], v[4:7]
	v_mfma_f32_16x16x32_bf16 v[0:3], v[172:175], v[218:221], v[0:3]
	s_barrier
	s_setprio 0
	s_add_i32 s51, 0, 0x18000
	s_add_i32 s52, 0, 0x1c000
	v_add_u32_e32 v140, s51, v179
	v_add_u32_e32 v172, s52, v179
	ds_read_b128 v[128:131], v140
	ds_read_b128 v[132:135], v140 offset:1024
	ds_read_b128 v[136:139], v140 offset:2048
	ds_read_b128 v[140:143], v140 offset:3072
	ds_read_b128 v[144:147], v172
	ds_read_b128 v[148:151], v172 offset:1024
	ds_read_b128 v[168:171], v172 offset:2048
	ds_read_b128 v[172:175], v172 offset:3072
	s_add_u32 s30, s30, 0x80000
	s_addc_u32 s31, s31, 0
	s_mov_b32 m0, s39
	v_lshl_add_u64 v[226:227], s[30:31], 0, v[152:153]
	ds_read_b128 v[186:189], v183 offset:32768
	ds_read_b128 v[190:193], v183 offset:33792
	ds_read_b128 v[198:201], v183 offset:34816
	ds_read_b128 v[202:205], v183 offset:35840
	ds_read_b128 v[206:209], v183 offset:36864
	ds_read_b128 v[210:213], v183 offset:37888
	ds_read_b128 v[214:217], v183 offset:38912
	ds_read_b128 v[218:221], v183 offset:39936
	global_load_lds_dwordx4 v[226:227], off
	v_lshl_add_u64 v[226:227], s[30:31], 0, v[156:157]
	s_mov_b32 m0, s42
	s_nop 0
	global_load_lds_dwordx4 v[226:227], off
	s_waitcnt vmcnt(8)
	s_waitcnt lgkmcnt(0)
	s_setprio 1
	s_barrier
	v_mfma_f32_16x16x32_bf16 v[124:127], v[128:131], v[186:189], v[124:127]
	v_mfma_f32_16x16x32_bf16 v[120:123], v[136:139], v[186:189], v[120:123]
	v_mfma_f32_16x16x32_bf16 v[104:107], v[128:131], v[198:201], v[104:107]
	v_mfma_f32_16x16x32_bf16 v[108:111], v[136:139], v[198:201], v[108:111]
	v_mfma_f32_16x16x32_bf16 v[88:91], v[128:131], v[206:209], v[88:91]
	v_mfma_f32_16x16x32_bf16 v[92:95], v[136:139], v[206:209], v[92:95]
	v_mfma_f32_16x16x32_bf16 v[72:75], v[128:131], v[214:217], v[72:75]
	v_mfma_f32_16x16x32_bf16 v[76:79], v[136:139], v[214:217], v[76:79]
	v_mfma_f32_16x16x32_bf16 v[124:127], v[132:135], v[190:193], v[124:127]
	v_mfma_f32_16x16x32_bf16 v[120:123], v[140:143], v[190:193], v[120:123]
	v_mfma_f32_16x16x32_bf16 v[104:107], v[132:135], v[202:205], v[104:107]
	v_mfma_f32_16x16x32_bf16 v[108:111], v[140:143], v[202:205], v[108:111]
	v_mfma_f32_16x16x32_bf16 v[88:91], v[132:135], v[210:213], v[88:91]
	v_mfma_f32_16x16x32_bf16 v[92:95], v[140:143], v[210:213], v[92:95]
	v_mfma_f32_16x16x32_bf16 v[72:75], v[132:135], v[218:221], v[72:75]
	v_mfma_f32_16x16x32_bf16 v[76:79], v[140:143], v[218:221], v[76:79]
	v_mfma_f32_16x16x32_bf16 v[116:119], v[144:147], v[186:189], v[116:119]
	v_mfma_f32_16x16x32_bf16 v[112:115], v[168:171], v[186:189], v[112:115]
	v_mfma_f32_16x16x32_bf16 v[100:103], v[144:147], v[198:201], v[100:103]
	v_mfma_f32_16x16x32_bf16 v[96:99], v[168:171], v[198:201], v[96:99]
	v_mfma_f32_16x16x32_bf16 v[84:87], v[144:147], v[206:209], v[84:87]
	v_mfma_f32_16x16x32_bf16 v[80:83], v[168:171], v[206:209], v[80:83]
	v_mfma_f32_16x16x32_bf16 v[68:71], v[144:147], v[214:217], v[68:71]
	v_mfma_f32_16x16x32_bf16 v[64:67], v[168:171], v[214:217], v[64:67]
	v_mfma_f32_16x16x32_bf16 v[116:119], v[148:151], v[190:193], v[116:119]
	v_mfma_f32_16x16x32_bf16 v[112:115], v[172:175], v[190:193], v[112:115]
	v_mfma_f32_16x16x32_bf16 v[100:103], v[148:151], v[202:205], v[100:103]
	v_mfma_f32_16x16x32_bf16 v[96:99], v[172:175], v[202:205], v[96:99]
	v_mfma_f32_16x16x32_bf16 v[84:87], v[148:151], v[210:213], v[84:87]
	v_mfma_f32_16x16x32_bf16 v[80:83], v[172:175], v[210:213], v[80:83]
	v_mfma_f32_16x16x32_bf16 v[68:71], v[148:151], v[218:221], v[68:71]
	v_mfma_f32_16x16x32_bf16 v[64:67], v[172:175], v[218:221], v[64:67]
	s_barrier
; #define PG8_STAGE(bufoff, gbase, voff) do { _Pragma("unroll") for (int _i = 0; _i < 2; ++_i) \
;         __builtin_amdgcn_global_load_lds((const unsigned*)((const char*)(gbase) + (voff)[_i]), (PG8_LAS unsigned*)(lds + (bufoff) + ldsw + _i * 8192), 16, 0, 0); } while (0)
; #define PG8_LDA(dst, b, h) do { _Pragma("unroll") for (int m = 0; m < 4; ++m) _Pragma("unroll") for (int k = 0; k < 2; ++k) dst[m][k] = *(const PG8_LAS bf16x8*)(lds + PG8_SA(b, h) + aoff + m * 2048 + k * 1024); } while (0)
; #define PG8_MMA(ai, bj, At, Bt) do { __builtin_amdgcn_s_setprio(1); _Pragma("unroll") for (int m = 0; m < 4; ++m) _Pragma("unroll") for (int n = 0; n < 2; ++n) _Pragma("unroll") for (int k = 0; k < 2; ++k) \
;         acc[ai][bj][m][n] = __builtin_amdgcn_mfma_f32_16x16x32_bf16(Bt[n][k], At[m][k], acc[ai][bj][m][n], 0, 0, 0); __builtin_amdgcn_s_setprio(0); } while (0)
; #define PG8_WAIT_V(n) asm volatile("s_waitcnt vmcnt(" #n ")" ::: "memory")
; #define PG8_WAIT_L(n) asm volatile("s_waitcnt lgkmcnt(" #n ")" ::: "memory")
; #define PG8_BAR __builtin_amdgcn_s_barrier()
; #define PG8_SCHED __builtin_amdgcn_sched_barrier(0)
; template <class Epi, class Sched, bool ALIGN_EPI = false, bool SP2 = false>
; __device__ __forceinline__ void gemm_phase(PG8_LAS unsigned char* lds, const Gemm g, const Sched& S, const Epi& E) {
;     ...
;             PG8_WAIT_V(8); PG8_WAIT_L(0); PG8_BAR; PG8_MMA(0, 0, At, B0); PG8_MMA(0, 1, At, B1); PG8_BAR; PG8_SCHED;
;             PG8_LDA(At, 1, 1); PG8_STAGE(PG8_SB(1, 0), b3, voffB); PG8_STAGE(PG8_SB(1, 1), b3 + hstep, voffB); PG8_STAGE(PG8_SA(1, 0), a3, voffA);
;             PG8_WAIT_V(8); PG8_WAIT_L(0); PG8_BAR; PG8_MMA(1, 0, At, B0); PG8_MMA(1, 1, At, B1); PG8_BAR; PG8_SCHED;
;     ...
;         if constexpr (ALIGN_EPI) { if (wr == 0) PG8_BAR; }
	s_setprio 0
	s_add_i32 s30, s51, s34
	v_lshl_add_u64 v[176:177], v[176:177], 0, s[12:13]
	s_mov_b32 m0, s30
	ds_read_b128 v[186:189], v183 offset:49152
	ds_read_b128 v[190:193], v183 offset:50176
	ds_read_b128 v[198:201], v183 offset:51200
	ds_read_b128 v[202:205], v183 offset:52224
	ds_read_b128 v[206:209], v183 offset:53248
	ds_read_b128 v[210:213], v183 offset:54272
	ds_read_b128 v[214:217], v183 offset:55296
	ds_read_b128 v[218:221], v183 offset:56320
	global_load_lds_dwordx4 v[176:177], off
	s_add_i32 m0, s30, 0x2000
	s_add_u32 s28, s28, 0x80080
	v_lshl_add_u64 v[176:177], v[194:195], 0, s[12:13]
	s_addc_u32 s29, s29, 0
	s_add_i32 s30, s52, s34
	global_load_lds_dwordx4 v[176:177], off
	v_lshl_add_u64 v[176:177], s[28:29], 0, v[154:155]
	s_mov_b32 m0, s30
	s_nop 0
	global_load_lds_dwordx4 v[176:177], off
	v_lshl_add_u64 v[176:177], s[28:29], 0, v[158:159]
	s_add_i32 m0, s30, 0x2000
	s_nop 0
	global_load_lds_dwordx4 v[176:177], off
	v_lshl_add_u64 v[176:177], v[222:223], 0, s[12:13]
	s_mov_b32 m0, s44
	s_nop 0
	global_load_lds_dwordx4 v[176:177], off
	v_lshl_add_u64 v[176:177], v[224:225], 0, s[12:13]
	s_mov_b32 m0, s45
	s_nop 0
	global_load_lds_dwordx4 v[176:177], off
	s_waitcnt vmcnt(8)
	s_waitcnt lgkmcnt(0)
	s_setprio 1
	s_barrier
	v_mfma_f32_16x16x32_bf16 v[56:59], v[128:131], v[186:189], v[56:59]
	v_mfma_f32_16x16x32_bf16 v[60:63], v[136:139], v[186:189], v[60:63]
	v_mfma_f32_16x16x32_bf16 v[40:43], v[128:131], v[198:201], v[40:43]
	v_mfma_f32_16x16x32_bf16 v[44:47], v[136:139], v[198:201], v[44:47]
	v_mfma_f32_16x16x32_bf16 v[24:27], v[128:131], v[206:209], v[24:27]
	v_mfma_f32_16x16x32_bf16 v[28:31], v[136:139], v[206:209], v[28:31]
	v_mfma_f32_16x16x32_bf16 v[8:11], v[128:131], v[214:217], v[8:11]
	v_mfma_f32_16x16x32_bf16 v[12:15], v[136:139], v[214:217], v[12:15]
	v_mfma_f32_16x16x32_bf16 v[56:59], v[132:135], v[190:193], v[56:59]
	v_mfma_f32_16x16x32_bf16 v[60:63], v[140:143], v[190:193], v[60:63]
	v_mfma_f32_16x16x32_bf16 v[40:43], v[132:135], v[202:205], v[40:43]
	v_mfma_f32_16x16x32_bf16 v[44:47], v[140:143], v[202:205], v[44:47]
	v_mfma_f32_16x16x32_bf16 v[24:27], v[132:135], v[210:213], v[24:27]
	v_mfma_f32_16x16x32_bf16 v[28:31], v[140:143], v[210:213], v[28:31]
	v_mfma_f32_16x16x32_bf16 v[8:11], v[132:135], v[218:221], v[8:11]
	v_mfma_f32_16x16x32_bf16 v[12:15], v[140:143], v[218:221], v[12:15]
	v_mfma_f32_16x16x32_bf16 v[52:55], v[144:147], v[186:189], v[52:55]
	v_mfma_f32_16x16x32_bf16 v[48:51], v[168:171], v[186:189], v[48:51]
	v_mfma_f32_16x16x32_bf16 v[36:39], v[144:147], v[198:201], v[36:39]
	v_mfma_f32_16x16x32_bf16 v[32:35], v[168:171], v[198:201], v[32:35]
	v_mfma_f32_16x16x32_bf16 v[20:23], v[144:147], v[206:209], v[20:23]
	v_mfma_f32_16x16x32_bf16 v[16:19], v[168:171], v[206:209], v[16:19]
	v_mfma_f32_16x16x32_bf16 v[4:7], v[144:147], v[214:217], v[4:7]
	v_mfma_f32_16x16x32_bf16 v[0:3], v[168:171], v[214:217], v[0:3]
	v_mfma_f32_16x16x32_bf16 v[52:55], v[148:151], v[190:193], v[52:55]
	v_mfma_f32_16x16x32_bf16 v[48:51], v[172:175], v[190:193], v[48:51]
	v_mfma_f32_16x16x32_bf16 v[36:39], v[148:151], v[202:205], v[36:39]
	v_mfma_f32_16x16x32_bf16 v[32:35], v[172:175], v[202:205], v[32:35]
	v_mfma_f32_16x16x32_bf16 v[20:23], v[148:151], v[210:213], v[20:23]
	v_mfma_f32_16x16x32_bf16 v[16:19], v[172:175], v[210:213], v[16:19]
	v_mfma_f32_16x16x32_bf16 v[4:7], v[148:151], v[218:221], v[4:7]
	v_mfma_f32_16x16x32_bf16 v[0:3], v[172:175], v[218:221], v[0:3]
	s_barrier
	s_setprio 0
	s_add_i32 s50, s50, 2
	s_add_u32 s26, s26, 0x100
	s_addc_u32 s27, s27, 0
	s_add_u32 s48, s48, 0x100
	s_addc_u32 s49, s49, 0
	s_cmp_gt_u32 s50, 29
	s_cbranch_scc0 .LBB0_307
	s_and_b64 vcc, exec, s[14:15]
	s_cbranch_vccz .LBB0_310
	s_barrier

; #define PG8_STAGE(bufoff, gbase, voff) do { _Pragma("unroll") for (int _i = 0; _i < 2; ++_i) \
;         __builtin_amdgcn_global_load_lds((const unsigned*)((const char*)(gbase) + (voff)[_i]), (PG8_LAS unsigned*)(lds + (bufoff) + ldsw + _i * 8192), 16, 0, 0); } while (0)
; #define PG8_LDA(dst, b, h) do { _Pragma("unroll") for (int m = 0; m < 4; ++m) _Pragma("unroll") for (int k = 0; k < 2; ++k) dst[m][k] = *(const PG8_LAS bf16x8*)(lds + PG8_SA(b, h) + aoff + m * 2048 + k * 1024); } while (0)
; #define PG8_LDB(dst, b, h) do { _Pragma("unroll") for (int n = 0; n < 2; ++n) _Pragma("unroll") for (int k = 0; k < 2; ++k) dst[n][k] = *(const PG8_LAS bf16x8*)(lds + PG8_SB(b, h) + boff + n * 2048 + k * 1024); } while (0)
; #define PG8_MMA(ai, bj, At, Bt) do { __builtin_amdgcn_s_setprio(1); _Pragma("unroll") for (int m = 0; m < 4; ++m) _Pragma("unroll") for (int n = 0; n < 2; ++n) _Pragma("unroll") for (int k = 0; k < 2; ++k) \
;         acc[ai][bj][m][n] = __builtin_amdgcn_mfma_f32_16x16x32_bf16(Bt[n][k], At[m][k], acc[ai][bj][m][n], 0, 0, 0); __builtin_amdgcn_s_setprio(0); } while (0)
; #define PG8_WAIT_V(n) asm volatile("s_waitcnt vmcnt(" #n ")" ::: "memory")
; #define PG8_WAIT_L(n) asm volatile("s_waitcnt lgkmcnt(" #n ")" ::: "memory")
; template <class Epi, class Sched, bool ALIGN_EPI = false, bool SP2 = false>
; __device__ __forceinline__ void gemm_phase(PG8_LAS unsigned char* lds, const Gemm g, const Sched& S, const Epi& E) {
;     ...
;             const bool last = (t == nt - 2);
;             const char* a1 = cA + (size_t)(t + 1) * kstep;
;             const char* a2 = last ? nA : cA + (size_t)(t + 2) * kstep; const char* b2 = last ? nB : cB + (size_t)(t + 2) * kstep;
;             const char* a3 = a2 + kstep; const char* b3 = b2 + kstep;
;             if (last && has_next) S.a_ready(nxt);
;             if constexpr (SP2) {
;             PG8_LDB(B0, 0, 0); PG8_LDB(B1, 0, 1); PG8_SCHED; PG8_LDA(At, 0, 0); PG8_STAGE(PG8_SA(1, 1), a1 + hstep, voffA);
;             PG8_WAIT_V(8); PG8_WAIT_L(0); PG8_BAR; PG8_MMA(0, 0, At, B0); PG8_MMA(0, 1, At, B1); PG8_BAR; PG8_SCHED;
;             PG8_LDA(At, 0, 1); PG8_STAGE(PG8_SB(0, 0), b2, voffB); PG8_STAGE(PG8_SB(0, 1), b2 + hstep, voffB); PG8_STAGE(PG8_SA(0, 0), a2, voffA);
;             PG8_WAIT_V(8); PG8_WAIT_L(0); PG8_BAR; PG8_MMA(1, 0, At, B0); PG8_MMA(1, 1, At, B1); PG8_BAR; PG8_SCHED;
.LBB0_491:
	v_add_u32_e32 v140, s68, v163
	v_add_u32_e32 v152, s69, v163
	ds_read_b128 v[128:131], v140
	ds_read_b128 v[132:135], v140 offset:1024
	ds_read_b128 v[136:139], v140 offset:2048
	ds_read_b128 v[140:143], v140 offset:3072
	ds_read_b128 v[184:187], v152
	ds_read_b128 v[218:221], v152 offset:1024
	ds_read_b128 v[222:225], v152 offset:2048
	ds_read_b128 v[226:229], v152 offset:3072
	s_add_u32 s28, s0, 0xfff80080
	s_addc_u32 s29, s1, -1
	s_cmp_eq_u32 s48, 28
	s_cselect_b32 s31, s5, s29
	s_cselect_b32 s30, s21, s28
	s_cselect_b32 s29, s19, s45
	s_cselect_b32 s28, s33, s44
	v_lshl_add_u64 v[172:173], s[0:1], 0, v[156:157]
	s_add_i32 m0, s17, 0xc000
	ds_read_b128 v[230:233], v214
	ds_read_b128 v[234:237], v214 offset:1024
	ds_read_b128 v[238:241], v214 offset:2048
	ds_read_b128 v[242:245], v214 offset:3072
	ds_read_b128 v[246:249], v214 offset:4096
	ds_read_b128 v[250:253], v214 offset:5120
	ds_read_b128 v[206:209], v214 offset:6144
	ds_read_b128 v[210:213], v214 offset:7168
	global_load_lds_dwordx4 v[172:173], off
	v_lshl_add_u64 v[172:173], s[0:1], 0, v[158:159]
	s_add_i32 m0, s17, 0xe000
	s_nop 0
	global_load_lds_dwordx4 v[172:173], off
	s_waitcnt vmcnt(8)
	s_waitcnt lgkmcnt(0)
	s_setprio 1
	s_barrier
	v_mfma_f32_16x16x32_bf16 v[124:127], v[128:131], v[230:233], v[124:127]
	v_mfma_f32_16x16x32_bf16 v[120:123], v[136:139], v[230:233], v[120:123]
	v_mfma_f32_16x16x32_bf16 v[116:119], v[128:131], v[238:241], v[116:119]
	v_mfma_f32_16x16x32_bf16 v[108:111], v[136:139], v[238:241], v[108:111]
	v_mfma_f32_16x16x32_bf16 v[100:103], v[128:131], v[246:249], v[100:103]
	v_mfma_f32_16x16x32_bf16 v[92:95], v[136:139], v[246:249], v[92:95]
	v_mfma_f32_16x16x32_bf16 v[84:87], v[128:131], v[206:209], v[84:87]
	v_mfma_f32_16x16x32_bf16 v[76:79], v[136:139], v[206:209], v[76:79]
	v_mfma_f32_16x16x32_bf16 v[124:127], v[132:135], v[234:237], v[124:127]
	v_mfma_f32_16x16x32_bf16 v[120:123], v[140:143], v[234:237], v[120:123]
	v_mfma_f32_16x16x32_bf16 v[116:119], v[132:135], v[242:245], v[116:119]
	v_mfma_f32_16x16x32_bf16 v[108:111], v[140:143], v[242:245], v[108:111]
	v_mfma_f32_16x16x32_bf16 v[100:103], v[132:135], v[250:253], v[100:103]
	v_mfma_f32_16x16x32_bf16 v[92:95], v[140:143], v[250:253], v[92:95]
	v_mfma_f32_16x16x32_bf16 v[84:87], v[132:135], v[210:213], v[84:87]
	v_mfma_f32_16x16x32_bf16 v[76:79], v[140:143], v[210:213], v[76:79]
	v_mfma_f32_16x16x32_bf16 v[112:115], v[184:187], v[230:233], v[112:115]
	v_mfma_f32_16x16x32_bf16 v[104:107], v[222:225], v[230:233], v[104:107]
	v_mfma_f32_16x16x32_bf16 v[96:99], v[184:187], v[238:241], v[96:99]
	v_mfma_f32_16x16x32_bf16 v[88:91], v[222:225], v[238:241], v[88:91]
	v_mfma_f32_16x16x32_bf16 v[80:83], v[184:187], v[246:249], v[80:83]
	v_mfma_f32_16x16x32_bf16 v[72:75], v[222:225], v[246:249], v[72:75]
	v_mfma_f32_16x16x32_bf16 v[68:71], v[184:187], v[206:209], v[68:71]
	v_mfma_f32_16x16x32_bf16 v[64:67], v[222:225], v[206:209], v[64:67]
	v_mfma_f32_16x16x32_bf16 v[112:115], v[218:221], v[234:237], v[112:115]
	v_mfma_f32_16x16x32_bf16 v[104:107], v[226:229], v[234:237], v[104:107]
	v_mfma_f32_16x16x32_bf16 v[96:99], v[218:221], v[242:245], v[96:99]
	v_mfma_f32_16x16x32_bf16 v[88:91], v[226:229], v[242:245], v[88:91]
	v_mfma_f32_16x16x32_bf16 v[80:83], v[218:221], v[250:253], v[80:83]
	v_mfma_f32_16x16x32_bf16 v[72:75], v[226:229], v[250:253], v[72:75]
	v_mfma_f32_16x16x32_bf16 v[68:71], v[218:221], v[210:213], v[68:71]
	v_mfma_f32_16x16x32_bf16 v[64:67], v[226:229], v[210:213], v[64:67]
	s_barrier
	s_setprio 0
	s_add_i32 s49, s68, s34
	v_lshl_add_u64 v[172:173], s[28:29], 0, v[146:147]
	s_mov_b32 m0, s49
	ds_read_b128 v[206:209], v214 offset:16384
	ds_read_b128 v[210:213], v214 offset:17408
	ds_read_b128 v[230:233], v214 offset:18432
	ds_read_b128 v[234:237], v214 offset:19456
	ds_read_b128 v[238:241], v214 offset:20480
	ds_read_b128 v[242:245], v214 offset:21504
	ds_read_b128 v[246:249], v214 offset:22528
	ds_read_b128 v[250:253], v214 offset:23552
	global_load_lds_dwordx4 v[172:173], off
	s_add_i32 m0, s49, 0x2000
	s_add_u32 s50, s28, 0x80000
	v_lshl_add_u64 v[176:177], s[28:29], 0, v[150:151]
	s_addc_u32 s51, s29, 0
	s_add_i32 s49, s69, s34
	global_load_lds_dwordx4 v[176:177], off
	v_lshl_add_u64 v[180:181], s[50:51], 0, v[146:147]
	s_mov_b32 m0, s49
	v_lshl_add_u64 v[188:189], s[30:31], 0, v[148:149]
	global_load_lds_dwordx4 v[180:181], off
	v_lshl_add_u64 v[180:181], s[50:51], 0, v[150:151]
	s_add_i32 m0, s49, 0x2000
	s_nop 0
	global_load_lds_dwordx4 v[180:181], off
	v_lshl_add_u64 v[180:181], s[30:31], 0, v[144:145]
	s_mov_b32 m0, s17
	s_nop 0
	global_load_lds_dwordx4 v[180:181], off
	s_mov_b32 m0, s35
	s_nop 0
	global_load_lds_dwordx4 v[188:189], off
	s_waitcnt vmcnt(8)
	s_waitcnt lgkmcnt(0)
	s_setprio 1
	s_barrier
; #define PG8_STAGE(bufoff, gbase, voff) do { _Pragma("unroll") for (int _i = 0; _i < 2; ++_i) \
;         __builtin_amdgcn_global_load_lds((const unsigned*)((const char*)(gbase) + (voff)[_i]), (PG8_LAS unsigned*)(lds + (bufoff) + ldsw + _i * 8192), 16, 0, 0); } while (0)
; #define PG8_LDA(dst, b, h) do { _Pragma("unroll") for (int m = 0; m < 4; ++m) _Pragma("unroll") for (int k = 0; k < 2; ++k) dst[m][k] = *(const PG8_LAS bf16x8*)(lds + PG8_SA(b, h) + aoff + m * 2048 + k * 1024); } while (0)
; #define PG8_LDB(dst, b, h) do { _Pragma("unroll") for (int n = 0; n < 2; ++n) _Pragma("unroll") for (int k = 0; k < 2; ++k) dst[n][k] = *(const PG8_LAS bf16x8*)(lds + PG8_SB(b, h) + boff + n * 2048 + k * 1024); } while (0)
; #define PG8_MMA(ai, bj, At, Bt) do { __builtin_amdgcn_s_setprio(1); _Pragma("unroll") for (int m = 0; m < 4; ++m) _Pragma("unroll") for (int n = 0; n < 2; ++n) _Pragma("unroll") for (int k = 0; k < 2; ++k) \
;         acc[ai][bj][m][n] = __builtin_amdgcn_mfma_f32_16x16x32_bf16(Bt[n][k], At[m][k], acc[ai][bj][m][n], 0, 0, 0); __builtin_amdgcn_s_setprio(0); } while (0)
; #define PG8_WAIT_V(n) asm volatile("s_waitcnt vmcnt(" #n ")" ::: "memory")
; #define PG8_WAIT_L(n) asm volatile("s_waitcnt lgkmcnt(" #n ")" ::: "memory")
; #define PG8_BAR __builtin_amdgcn_s_barrier()
; #define PG8_SCHED __builtin_amdgcn_sched_barrier(0)
; template <class Epi, class Sched, bool ALIGN_EPI = false, bool SP2 = false>
; __device__ __forceinline__ void gemm_phase(PG8_LAS unsigned char* lds, const Gemm g, const Sched& S, const Epi& E) {
;     ...
;             PG8_WAIT_V(8); PG8_WAIT_L(0); PG8_BAR; PG8_MMA(1, 0, At, B0); PG8_MMA(1, 1, At, B1); PG8_BAR; PG8_SCHED;
;             PG8_LDB(B0, 1, 0); PG8_LDB(B1, 1, 1); PG8_SCHED; PG8_LDA(At, 1, 0); PG8_STAGE(PG8_SA(0, 1), a2 + hstep, voffA);
;             PG8_WAIT_V(8); PG8_WAIT_L(0); PG8_BAR; PG8_MMA(0, 0, At, B0); PG8_MMA(0, 1, At, B1); PG8_BAR; PG8_SCHED;
	v_mfma_f32_16x16x32_bf16 v[60:63], v[128:131], v[206:209], v[60:63]
	v_mfma_f32_16x16x32_bf16 v[56:59], v[136:139], v[206:209], v[56:59]
	v_mfma_f32_16x16x32_bf16 v[52:55], v[128:131], v[230:233], v[52:55]
	v_mfma_f32_16x16x32_bf16 v[44:47], v[136:139], v[230:233], v[44:47]
	v_mfma_f32_16x16x32_bf16 v[36:39], v[128:131], v[238:241], v[36:39]
	v_mfma_f32_16x16x32_bf16 v[28:31], v[136:139], v[238:241], v[28:31]
	v_mfma_f32_16x16x32_bf16 v[20:23], v[128:131], v[246:249], v[20:23]
	v_mfma_f32_16x16x32_bf16 v[12:15], v[136:139], v[246:249], v[12:15]
	v_mfma_f32_16x16x32_bf16 v[60:63], v[132:135], v[210:213], v[60:63]
	v_mfma_f32_16x16x32_bf16 v[56:59], v[140:143], v[210:213], v[56:59]
	v_mfma_f32_16x16x32_bf16 v[52:55], v[132:135], v[234:237], v[52:55]
	v_mfma_f32_16x16x32_bf16 v[44:47], v[140:143], v[234:237], v[44:47]
	v_mfma_f32_16x16x32_bf16 v[36:39], v[132:135], v[242:245], v[36:39]
	v_mfma_f32_16x16x32_bf16 v[28:31], v[140:143], v[242:245], v[28:31]
	v_mfma_f32_16x16x32_bf16 v[20:23], v[132:135], v[250:253], v[20:23]
	v_mfma_f32_16x16x32_bf16 v[12:15], v[140:143], v[250:253], v[12:15]
	v_mfma_f32_16x16x32_bf16 v[48:51], v[184:187], v[206:209], v[48:51]
	v_mfma_f32_16x16x32_bf16 v[40:43], v[222:225], v[206:209], v[40:43]
	v_mfma_f32_16x16x32_bf16 v[32:35], v[184:187], v[230:233], v[32:35]
	v_mfma_f32_16x16x32_bf16 v[24:27], v[222:225], v[230:233], v[24:27]
	v_mfma_f32_16x16x32_bf16 v[16:19], v[184:187], v[238:241], v[16:19]
	v_mfma_f32_16x16x32_bf16 v[8:11], v[222:225], v[238:241], v[8:11]
	v_mfma_f32_16x16x32_bf16 v[4:7], v[184:187], v[246:249], v[4:7]
	v_mfma_f32_16x16x32_bf16 v[0:3], v[222:225], v[246:249], v[0:3]
	v_mfma_f32_16x16x32_bf16 v[48:51], v[218:221], v[210:213], v[48:51]
	v_mfma_f32_16x16x32_bf16 v[40:43], v[226:229], v[210:213], v[40:43]
	v_mfma_f32_16x16x32_bf16 v[32:35], v[218:221], v[234:237], v[32:35]
	v_mfma_f32_16x16x32_bf16 v[24:27], v[226:229], v[234:237], v[24:27]
	v_mfma_f32_16x16x32_bf16 v[16:19], v[218:221], v[242:245], v[16:19]
	v_mfma_f32_16x16x32_bf16 v[8:11], v[226:229], v[242:245], v[8:11]
	v_mfma_f32_16x16x32_bf16 v[4:7], v[218:221], v[250:253], v[4:7]
	v_mfma_f32_16x16x32_bf16 v[0:3], v[226:229], v[250:253], v[0:3]
	s_barrier
	s_setprio 0
	s_add_i32 s49, 0, 0x18000
	s_add_i32 s50, 0, 0x1c000
	v_add_u32_e32 v140, s49, v163
	v_add_u32_e32 v152, s50, v163
	ds_read_b128 v[128:131], v140
	ds_read_b128 v[132:135], v140 offset:1024
	ds_read_b128 v[136:139], v140 offset:2048
	ds_read_b128 v[140:143], v140 offset:3072
	ds_read_b128 v[184:187], v152
	ds_read_b128 v[206:209], v152 offset:1024
	ds_read_b128 v[210:213], v152 offset:2048
	ds_read_b128 v[218:221], v152 offset:3072
	s_add_u32 s30, s30, 0x80000
	s_addc_u32 s31, s31, 0
	s_mov_b32 m0, s37
	v_lshl_add_u64 v[216:217], s[30:31], 0, v[144:145]
	ds_read_b128 v[222:225], v214 offset:32768
	ds_read_b128 v[226:229], v214 offset:33792
	ds_read_b128 v[230:233], v214 offset:34816
	ds_read_b128 v[234:237], v214 offset:35840
	ds_read_b128 v[238:241], v214 offset:36864
	ds_read_b128 v[242:245], v214 offset:37888
	ds_read_b128 v[246:249], v214 offset:38912
	ds_read_b128 v[250:253], v214 offset:39936
	global_load_lds_dwordx4 v[216:217], off
	v_lshl_add_u64 v[216:217], s[30:31], 0, v[148:149]
	s_mov_b32 m0, s39
	s_nop 0
	global_load_lds_dwordx4 v[216:217], off
	s_waitcnt vmcnt(8)
	s_waitcnt lgkmcnt(0)
	s_setprio 1
	s_barrier
	v_mfma_f32_16x16x32_bf16 v[124:127], v[128:131], v[222:225], v[124:127]
	v_mfma_f32_16x16x32_bf16 v[120:123], v[136:139], v[222:225], v[120:123]
	v_mfma_f32_16x16x32_bf16 v[116:119], v[128:131], v[230:233], v[116:119]
	v_mfma_f32_16x16x32_bf16 v[108:111], v[136:139], v[230:233], v[108:111]
	v_mfma_f32_16x16x32_bf16 v[100:103], v[128:131], v[238:241], v[100:103]
	v_mfma_f32_16x16x32_bf16 v[92:95], v[136:139], v[238:241], v[92:95]
	v_mfma_f32_16x16x32_bf16 v[84:87], v[128:131], v[246:249], v[84:87]
	v_mfma_f32_16x16x32_bf16 v[76:79], v[136:139], v[246:249], v[76:79]
	v_mfma_f32_16x16x32_bf16 v[124:127], v[132:135], v[226:229], v[124:127]
	v_mfma_f32_16x16x32_bf16 v[120:123], v[140:143], v[226:229], v[120:123]
	v_mfma_f32_16x16x32_bf16 v[116:119], v[132:135], v[234:237], v[116:119]
	v_mfma_f32_16x16x32_bf16 v[108:111], v[140:143], v[234:237], v[108:111]
	v_mfma_f32_16x16x32_bf16 v[100:103], v[132:135], v[242:245], v[100:103]
	v_mfma_f32_16x16x32_bf16 v[92:95], v[140:143], v[242:245], v[92:95]
	v_mfma_f32_16x16x32_bf16 v[84:87], v[132:135], v[250:253], v[84:87]
	v_mfma_f32_16x16x32_bf16 v[76:79], v[140:143], v[250:253], v[76:79]
	v_mfma_f32_16x16x32_bf16 v[112:115], v[184:187], v[222:225], v[112:115]
	v_mfma_f32_16x16x32_bf16 v[104:107], v[210:213], v[222:225], v[104:107]
	v_mfma_f32_16x16x32_bf16 v[96:99], v[184:187], v[230:233], v[96:99]
	v_mfma_f32_16x16x32_bf16 v[88:91], v[210:213], v[230:233], v[88:91]
	v_mfma_f32_16x16x32_bf16 v[80:83], v[184:187], v[238:241], v[80:83]
	v_mfma_f32_16x16x32_bf16 v[72:75], v[210:213], v[238:241], v[72:75]
	v_mfma_f32_16x16x32_bf16 v[68:71], v[184:187], v[246:249], v[68:71]
	v_mfma_f32_16x16x32_bf16 v[64:67], v[210:213], v[246:249], v[64:67]
	v_mfma_f32_16x16x32_bf16 v[112:115], v[206:209], v[226:229], v[112:115]
	v_mfma_f32_16x16x32_bf16 v[104:107], v[218:221], v[226:229], v[104:107]
	v_mfma_f32_16x16x32_bf16 v[96:99], v[206:209], v[234:237], v[96:99]
	v_mfma_f32_16x16x32_bf16 v[88:91], v[218:221], v[234:237], v[88:91]
	v_mfma_f32_16x16x32_bf16 v[80:83], v[206:209], v[242:245], v[80:83]
	v_mfma_f32_16x16x32_bf16 v[72:75], v[218:221], v[242:245], v[72:75]
	v_mfma_f32_16x16x32_bf16 v[68:71], v[206:209], v[250:253], v[68:71]
	v_mfma_f32_16x16x32_bf16 v[64:67], v[218:221], v[250:253], v[64:67]
	s_barrier
; #define PG8_STAGE(bufoff, gbase, voff) do { _Pragma("unroll") for (int _i = 0; _i < 2; ++_i) \
;         __builtin_amdgcn_global_load_lds((const unsigned*)((const char*)(gbase) + (voff)[_i]), (PG8_LAS unsigned*)(lds + (bufoff) + ldsw + _i * 8192), 16, 0, 0); } while (0)
; #define PG8_LDA(dst, b, h) do { _Pragma("unroll") for (int m = 0; m < 4; ++m) _Pragma("unroll") for (int k = 0; k < 2; ++k) dst[m][k] = *(const PG8_LAS bf16x8*)(lds + PG8_SA(b, h) + aoff + m * 2048 + k * 1024); } while (0)
; #define PG8_MMA(ai, bj, At, Bt) do { __builtin_amdgcn_s_setprio(1); _Pragma("unroll") for (int m = 0; m < 4; ++m) _Pragma("unroll") for (int n = 0; n < 2; ++n) _Pragma("unroll") for (int k = 0; k < 2; ++k) \
;         acc[ai][bj][m][n] = __builtin_amdgcn_mfma_f32_16x16x32_bf16(Bt[n][k], At[m][k], acc[ai][bj][m][n], 0, 0, 0); __builtin_amdgcn_s_setprio(0); } while (0)
; #define PG8_WAIT_V(n) asm volatile("s_waitcnt vmcnt(" #n ")" ::: "memory")
; #define PG8_WAIT_L(n) asm volatile("s_waitcnt lgkmcnt(" #n ")" ::: "memory")
; #define PG8_BAR __builtin_amdgcn_s_barrier()
; #define PG8_SCHED __builtin_amdgcn_sched_barrier(0)
; template <class Epi, class Sched, bool ALIGN_EPI = false, bool SP2 = false>
; __device__ __forceinline__ void gemm_phase(PG8_LAS unsigned char* lds, const Gemm g, const Sched& S, const Epi& E) {
;     ...
;             PG8_WAIT_V(8); PG8_WAIT_L(0); PG8_BAR; PG8_MMA(0, 0, At, B0); PG8_MMA(0, 1, At, B1); PG8_BAR; PG8_SCHED;
;             PG8_LDA(At, 1, 1); PG8_STAGE(PG8_SB(1, 0), b3, voffB); PG8_STAGE(PG8_SB(1, 1), b3 + hstep, voffB); PG8_STAGE(PG8_SA(1, 0), a3, voffA);
;             PG8_WAIT_V(8); PG8_WAIT_L(0); PG8_BAR; PG8_MMA(1, 0, At, B0); PG8_MMA(1, 1, At, B1); PG8_BAR; PG8_SCHED;
;     ...
;         if constexpr (ALIGN_EPI) { if (wr == 0) PG8_BAR; }
	s_setprio 0
	s_add_i32 s30, s49, s34
	v_lshl_add_u64 v[172:173], v[172:173], 0, s[10:11]
	s_mov_b32 m0, s30
	ds_read_b128 v[222:225], v214 offset:49152
	ds_read_b128 v[226:229], v214 offset:50176
	ds_read_b128 v[230:233], v214 offset:51200
	ds_read_b128 v[234:237], v214 offset:52224
	ds_read_b128 v[238:241], v214 offset:53248
	ds_read_b128 v[242:245], v214 offset:54272
	ds_read_b128 v[246:249], v214 offset:55296
	ds_read_b128 v[250:253], v214 offset:56320
	global_load_lds_dwordx4 v[172:173], off
	s_add_i32 m0, s30, 0x2000
	s_add_u32 s28, s28, 0x80080
	v_lshl_add_u64 v[172:173], v[176:177], 0, s[10:11]
	s_addc_u32 s29, s29, 0
	s_add_i32 s30, s50, s34
	global_load_lds_dwordx4 v[172:173], off
	v_lshl_add_u64 v[172:173], s[28:29], 0, v[146:147]
	s_mov_b32 m0, s30
	s_nop 0
	global_load_lds_dwordx4 v[172:173], off
	v_lshl_add_u64 v[172:173], s[28:29], 0, v[150:151]
	s_add_i32 m0, s30, 0x2000
	s_nop 0
	global_load_lds_dwordx4 v[172:173], off
	v_lshl_add_u64 v[172:173], v[180:181], 0, s[10:11]
	s_mov_b32 m0, s43
	s_nop 0
	global_load_lds_dwordx4 v[172:173], off
	v_lshl_add_u64 v[172:173], v[188:189], 0, s[10:11]
	s_mov_b32 m0, s46
	s_nop 0
	global_load_lds_dwordx4 v[172:173], off
	s_waitcnt vmcnt(8)
	s_waitcnt lgkmcnt(0)
	s_setprio 1
	s_barrier
	v_mfma_f32_16x16x32_bf16 v[60:63], v[128:131], v[222:225], v[60:63]
	v_mfma_f32_16x16x32_bf16 v[56:59], v[136:139], v[222:225], v[56:59]
	v_mfma_f32_16x16x32_bf16 v[52:55], v[128:131], v[230:233], v[52:55]
	v_mfma_f32_16x16x32_bf16 v[44:47], v[136:139], v[230:233], v[44:47]
	v_mfma_f32_16x16x32_bf16 v[36:39], v[128:131], v[238:241], v[36:39]
	v_mfma_f32_16x16x32_bf16 v[28:31], v[136:139], v[238:241], v[28:31]
	v_mfma_f32_16x16x32_bf16 v[20:23], v[128:131], v[246:249], v[20:23]
	v_mfma_f32_16x16x32_bf16 v[12:15], v[136:139], v[246:249], v[12:15]
	v_mfma_f32_16x16x32_bf16 v[60:63], v[132:135], v[226:229], v[60:63]
	v_mfma_f32_16x16x32_bf16 v[56:59], v[140:143], v[226:229], v[56:59]
	v_mfma_f32_16x16x32_bf16 v[52:55], v[132:135], v[234:237], v[52:55]
	v_mfma_f32_16x16x32_bf16 v[44:47], v[140:143], v[234:237], v[44:47]
	v_mfma_f32_16x16x32_bf16 v[36:39], v[132:135], v[242:245], v[36:39]
	v_mfma_f32_16x16x32_bf16 v[28:31], v[140:143], v[242:245], v[28:31]
	v_mfma_f32_16x16x32_bf16 v[20:23], v[132:135], v[250:253], v[20:23]
	v_mfma_f32_16x16x32_bf16 v[12:15], v[140:143], v[250:253], v[12:15]
	v_mfma_f32_16x16x32_bf16 v[48:51], v[184:187], v[222:225], v[48:51]
	v_mfma_f32_16x16x32_bf16 v[40:43], v[210:213], v[222:225], v[40:43]
	v_mfma_f32_16x16x32_bf16 v[32:35], v[184:187], v[230:233], v[32:35]
	v_mfma_f32_16x16x32_bf16 v[24:27], v[210:213], v[230:233], v[24:27]
	v_mfma_f32_16x16x32_bf16 v[16:19], v[184:187], v[238:241], v[16:19]
	v_mfma_f32_16x16x32_bf16 v[8:11], v[210:213], v[238:241], v[8:11]
	v_mfma_f32_16x16x32_bf16 v[4:7], v[184:187], v[246:249], v[4:7]
	v_mfma_f32_16x16x32_bf16 v[0:3], v[210:213], v[246:249], v[0:3]
	v_mfma_f32_16x16x32_bf16 v[48:51], v[206:209], v[226:229], v[48:51]
	v_mfma_f32_16x16x32_bf16 v[40:43], v[218:221], v[226:229], v[40:43]
	v_mfma_f32_16x16x32_bf16 v[32:35], v[206:209], v[234:237], v[32:35]
	v_mfma_f32_16x16x32_bf16 v[24:27], v[218:221], v[234:237], v[24:27]
	v_mfma_f32_16x16x32_bf16 v[16:19], v[206:209], v[242:245], v[16:19]
	v_mfma_f32_16x16x32_bf16 v[8:11], v[218:221], v[242:245], v[8:11]
	v_mfma_f32_16x16x32_bf16 v[4:7], v[206:209], v[250:253], v[4:7]
	v_mfma_f32_16x16x32_bf16 v[0:3], v[218:221], v[250:253], v[0:3]
	s_barrier
	s_setprio 0
	s_add_i32 s48, s48, 2
	s_add_u32 s0, s0, 0x100
	s_addc_u32 s1, s1, 0
	s_add_u32 s44, s44, 0x100
	s_addc_u32 s45, s45, 0
	s_cmp_gt_u32 s48, 29
	s_cbranch_scc0 .LBB0_491
	s_and_b64 vcc, exec, s[12:13]
	s_cbranch_vccz .LBB0_494
	s_barrier

; #define PG8_STAGE(bufoff, gbase, voff) do { _Pragma("unroll") for (int _i = 0; _i < 2; ++_i) \
;         __builtin_amdgcn_global_load_lds((const unsigned*)((const char*)(gbase) + (voff)[_i]), (PG8_LAS unsigned*)(lds + (bufoff) + ldsw + _i * 8192), 16, 0, 0); } while (0)
; #define PG8_LDA(dst, b, h) do { _Pragma("unroll") for (int m = 0; m < 4; ++m) _Pragma("unroll") for (int k = 0; k < 2; ++k) dst[m][k] = *(const PG8_LAS bf16x8*)(lds + PG8_SA(b, h) + aoff + m * 2048 + k * 1024); } while (0)
; #define PG8_LDB(dst, b, h) do { _Pragma("unroll") for (int n = 0; n < 2; ++n) _Pragma("unroll") for (int k = 0; k < 2; ++k) dst[n][k] = *(const PG8_LAS bf16x8*)(lds + PG8_SB(b, h) + boff + n * 2048 + k * 1024); } while (0)
; #define PG8_MMA(ai, bj, At, Bt) do { __builtin_amdgcn_s_setprio(1); _Pragma("unroll") for (int m = 0; m < 4; ++m) _Pragma("unroll") for (int n = 0; n < 2; ++n) _Pragma("unroll") for (int k = 0; k < 2; ++k) \
;         acc[ai][bj][m][n] = __builtin_amdgcn_mfma_f32_16x16x32_bf16(Bt[n][k], At[m][k], acc[ai][bj][m][n], 0, 0, 0); __builtin_amdgcn_s_setprio(0); } while (0)
; #define PG8_WAIT_V(n) asm volatile("s_waitcnt vmcnt(" #n ")" ::: "memory")
; #define PG8_WAIT_L(n) asm volatile("s_waitcnt lgkmcnt(" #n ")" ::: "memory")
; template <class Epi, class Sched, bool ALIGN_EPI = false, bool SP2 = false>
; __device__ __forceinline__ void gemm_phase(PG8_LAS unsigned char* lds, const Gemm g, const Sched& S, const Epi& E) {
;     ...
;             const bool last = (t == nt - 2);
;             const char* a1 = cA + (size_t)(t + 1) * kstep;
;             const char* a2 = last ? nA : cA + (size_t)(t + 2) * kstep; const char* b2 = last ? nB : cB + (size_t)(t + 2) * kstep;
;             const char* a3 = a2 + kstep; const char* b3 = b2 + kstep;
;             if (last && has_next) S.a_ready(nxt);
;             if constexpr (SP2) {
;             PG8_LDB(B0, 0, 0); PG8_LDB(B1, 0, 1); PG8_SCHED; PG8_LDA(At, 0, 0); PG8_STAGE(PG8_SA(1, 1), a1 + hstep, voffA);
;             PG8_WAIT_V(8); PG8_WAIT_L(0); PG8_BAR; PG8_MMA(0, 0, At, B0); PG8_MMA(0, 1, At, B1); PG8_BAR; PG8_SCHED;
;             PG8_LDA(At, 0, 1); PG8_STAGE(PG8_SB(0, 0), b2, voffB); PG8_STAGE(PG8_SB(0, 1), b2 + hstep, voffB); PG8_STAGE(PG8_SA(0, 0), a2, voffA);
;             PG8_WAIT_V(8); PG8_WAIT_L(0); PG8_BAR; PG8_MMA(1, 0, At, B0); PG8_MMA(1, 1, At, B1); PG8_BAR; PG8_SCHED;
.LBB0_763:
	ds_read_b128 v[128:131], v181
	ds_read_b128 v[132:135], v181 offset:1024
	ds_read_b128 v[136:139], v181 offset:2048
	ds_read_b128 v[140:143], v181 offset:3072
	ds_read_b128 v[144:147], v182
	ds_read_b128 v[148:151], v182 offset:1024
	ds_read_b128 v[168:171], v182 offset:2048
	ds_read_b128 v[172:175], v182 offset:3072
	s_add_u32 s28, s26, 0xfff00080
	s_addc_u32 s29, s27, -1
	s_cmp_eq_u32 s53, 60
	s_cselect_b32 s31, s7, s29
	s_cselect_b32 s30, s21, s28
	s_cselect_b32 s29, s19, s52
	s_cselect_b32 s28, s48, s49
	v_lshl_add_u64 v[176:177], s[26:27], 0, v[160:161]
	s_add_i32 m0, s35, 0xc000
	ds_read_b128 v[186:189], v183
	ds_read_b128 v[190:193], v183 offset:1024
	ds_read_b128 v[198:201], v183 offset:2048
	ds_read_b128 v[202:205], v183 offset:3072
	ds_read_b128 v[206:209], v183 offset:4096
	ds_read_b128 v[210:213], v183 offset:5120
	ds_read_b128 v[214:217], v183 offset:6144
	ds_read_b128 v[218:221], v183 offset:7168
	global_load_lds_dwordx4 v[176:177], off
	v_lshl_add_u64 v[176:177], s[26:27], 0, v[162:163]
	s_add_i32 m0, s35, 0xe000
	s_nop 0
	global_load_lds_dwordx4 v[176:177], off
	s_waitcnt vmcnt(8)
	s_waitcnt lgkmcnt(0)
	s_setprio 1
	s_barrier
	v_mfma_f32_16x16x32_bf16 v[124:127], v[128:131], v[186:189], v[124:127]
	v_mfma_f32_16x16x32_bf16 v[120:123], v[136:139], v[186:189], v[120:123]
	v_mfma_f32_16x16x32_bf16 v[104:107], v[128:131], v[198:201], v[104:107]
	v_mfma_f32_16x16x32_bf16 v[108:111], v[136:139], v[198:201], v[108:111]
	v_mfma_f32_16x16x32_bf16 v[88:91], v[128:131], v[206:209], v[88:91]
	v_mfma_f32_16x16x32_bf16 v[92:95], v[136:139], v[206:209], v[92:95]
	v_mfma_f32_16x16x32_bf16 v[72:75], v[128:131], v[214:217], v[72:75]
	v_mfma_f32_16x16x32_bf16 v[76:79], v[136:139], v[214:217], v[76:79]
	v_mfma_f32_16x16x32_bf16 v[124:127], v[132:135], v[190:193], v[124:127]
	v_mfma_f32_16x16x32_bf16 v[120:123], v[140:143], v[190:193], v[120:123]
	v_mfma_f32_16x16x32_bf16 v[104:107], v[132:135], v[202:205], v[104:107]
	v_mfma_f32_16x16x32_bf16 v[108:111], v[140:143], v[202:205], v[108:111]
	v_mfma_f32_16x16x32_bf16 v[88:91], v[132:135], v[210:213], v[88:91]
	v_mfma_f32_16x16x32_bf16 v[92:95], v[140:143], v[210:213], v[92:95]
	v_mfma_f32_16x16x32_bf16 v[72:75], v[132:135], v[218:221], v[72:75]
	v_mfma_f32_16x16x32_bf16 v[76:79], v[140:143], v[218:221], v[76:79]
	v_mfma_f32_16x16x32_bf16 v[116:119], v[144:147], v[186:189], v[116:119]
	v_mfma_f32_16x16x32_bf16 v[112:115], v[168:171], v[186:189], v[112:115]
	v_mfma_f32_16x16x32_bf16 v[100:103], v[144:147], v[198:201], v[100:103]
	v_mfma_f32_16x16x32_bf16 v[96:99], v[168:171], v[198:201], v[96:99]
	v_mfma_f32_16x16x32_bf16 v[84:87], v[144:147], v[206:209], v[84:87]
	v_mfma_f32_16x16x32_bf16 v[80:83], v[168:171], v[206:209], v[80:83]
	v_mfma_f32_16x16x32_bf16 v[68:71], v[144:147], v[214:217], v[68:71]
	v_mfma_f32_16x16x32_bf16 v[64:67], v[168:171], v[214:217], v[64:67]
	v_mfma_f32_16x16x32_bf16 v[116:119], v[148:151], v[190:193], v[116:119]
	v_mfma_f32_16x16x32_bf16 v[112:115], v[172:175], v[190:193], v[112:115]
	v_mfma_f32_16x16x32_bf16 v[100:103], v[148:151], v[202:205], v[100:103]
	v_mfma_f32_16x16x32_bf16 v[96:99], v[172:175], v[202:205], v[96:99]
	v_mfma_f32_16x16x32_bf16 v[84:87], v[148:151], v[210:213], v[84:87]
	v_mfma_f32_16x16x32_bf16 v[80:83], v[172:175], v[210:213], v[80:83]
	v_mfma_f32_16x16x32_bf16 v[68:71], v[148:151], v[218:221], v[68:71]
	v_mfma_f32_16x16x32_bf16 v[64:67], v[172:175], v[218:221], v[64:67]
	s_barrier
	s_setprio 0
	s_add_i32 s54, s47, s34
	v_lshl_add_u64 v[176:177], s[28:29], 0, v[154:155]
	s_mov_b32 m0, s54
	ds_read_b128 v[186:189], v183 offset:16384
	ds_read_b128 v[190:193], v183 offset:17408
	ds_read_b128 v[198:201], v183 offset:18432
	ds_read_b128 v[202:205], v183 offset:19456
	ds_read_b128 v[206:209], v183 offset:20480
	ds_read_b128 v[210:213], v183 offset:21504
	ds_read_b128 v[214:217], v183 offset:22528
	ds_read_b128 v[218:221], v183 offset:23552
	global_load_lds_dwordx4 v[176:177], off
	s_add_i32 m0, s54, 0x2000
	s_add_u32 s54, s28, 0x100000
	v_lshl_add_u64 v[194:195], s[28:29], 0, v[158:159]
	s_addc_u32 s55, s29, 0
	s_add_i32 s56, s50, s34
	global_load_lds_dwordx4 v[194:195], off
	v_lshl_add_u64 v[222:223], s[54:55], 0, v[154:155]
	s_mov_b32 m0, s56
	v_lshl_add_u64 v[224:225], s[30:31], 0, v[156:157]
	global_load_lds_dwordx4 v[222:223], off
	v_lshl_add_u64 v[222:223], s[54:55], 0, v[158:159]
	s_add_i32 m0, s56, 0x2000
	s_nop 0
	global_load_lds_dwordx4 v[222:223], off
	v_lshl_add_u64 v[222:223], s[30:31], 0, v[152:153]
	s_mov_b32 m0, s35
	s_nop 0
	global_load_lds_dwordx4 v[222:223], off
	s_mov_b32 m0, s33
	s_nop 0
	global_load_lds_dwordx4 v[224:225], off
	s_waitcnt vmcnt(8)
	s_waitcnt lgkmcnt(0)
	s_setprio 1
	s_barrier
; #define PG8_STAGE(bufoff, gbase, voff) do { _Pragma("unroll") for (int _i = 0; _i < 2; ++_i) \
;         __builtin_amdgcn_global_load_lds((const unsigned*)((const char*)(gbase) + (voff)[_i]), (PG8_LAS unsigned*)(lds + (bufoff) + ldsw + _i * 8192), 16, 0, 0); } while (0)
; #define PG8_LDA(dst, b, h) do { _Pragma("unroll") for (int m = 0; m < 4; ++m) _Pragma("unroll") for (int k = 0; k < 2; ++k) dst[m][k] = *(const PG8_LAS bf16x8*)(lds + PG8_SA(b, h) + aoff + m * 2048 + k * 1024); } while (0)
; #define PG8_LDB(dst, b, h) do { _Pragma("unroll") for (int n = 0; n < 2; ++n) _Pragma("unroll") for (int k = 0; k < 2; ++k) dst[n][k] = *(const PG8_LAS bf16x8*)(lds + PG8_SB(b, h) + boff + n * 2048 + k * 1024); } while (0)
; #define PG8_MMA(ai, bj, At, Bt) do { __builtin_amdgcn_s_setprio(1); _Pragma("unroll") for (int m = 0; m < 4; ++m) _Pragma("unroll") for (int n = 0; n < 2; ++n) _Pragma("unroll") for (int k = 0; k < 2; ++k) \
;         acc[ai][bj][m][n] = __builtin_amdgcn_mfma_f32_16x16x32_bf16(Bt[n][k], At[m][k], acc[ai][bj][m][n], 0, 0, 0); __builtin_amdgcn_s_setprio(0); } while (0)
; #define PG8_WAIT_V(n) asm volatile("s_waitcnt vmcnt(" #n ")" ::: "memory")
; #define PG8_WAIT_L(n) asm volatile("s_waitcnt lgkmcnt(" #n ")" ::: "memory")
; #define PG8_BAR __builtin_amdgcn_s_barrier()
; #define PG8_SCHED __builtin_amdgcn_sched_barrier(0)
; template <class Epi, class Sched, bool ALIGN_EPI = false, bool SP2 = false>
; __device__ __forceinline__ void gemm_phase(PG8_LAS unsigned char* lds, const Gemm g, const Sched& S, const Epi& E) {
;     ...
;             PG8_WAIT_V(8); PG8_WAIT_L(0); PG8_BAR; PG8_MMA(1, 0, At, B0); PG8_MMA(1, 1, At, B1); PG8_BAR; PG8_SCHED;
;             PG8_LDB(B0, 1, 0); PG8_LDB(B1, 1, 1); PG8_SCHED; PG8_LDA(At, 1, 0); PG8_STAGE(PG8_SA(0, 1), a2 + hstep, voffA);
;             PG8_WAIT_V(8); PG8_WAIT_L(0); PG8_BAR; PG8_MMA(0, 0, At, B0); PG8_MMA(0, 1, At, B1); PG8_BAR; PG8_SCHED;
	v_mfma_f32_16x16x32_bf16 v[56:59], v[128:131], v[186:189], v[56:59]
	v_mfma_f32_16x16x32_bf16 v[60:63], v[136:139], v[186:189], v[60:63]
	v_mfma_f32_16x16x32_bf16 v[40:43], v[128:131], v[198:201], v[40:43]
	v_mfma_f32_16x16x32_bf16 v[44:47], v[136:139], v[198:201], v[44:47]
	v_mfma_f32_16x16x32_bf16 v[24:27], v[128:131], v[206:209], v[24:27]
	v_mfma_f32_16x16x32_bf16 v[28:31], v[136:139], v[206:209], v[28:31]
	v_mfma_f32_16x16x32_bf16 v[8:11], v[128:131], v[214:217], v[8:11]
	v_mfma_f32_16x16x32_bf16 v[12:15], v[136:139], v[214:217], v[12:15]
	v_mfma_f32_16x16x32_bf16 v[56:59], v[132:135], v[190:193], v[56:59]
	v_mfma_f32_16x16x32_bf16 v[60:63], v[140:143], v[190:193], v[60:63]
	v_mfma_f32_16x16x32_bf16 v[40:43], v[132:135], v[202:205], v[40:43]
	v_mfma_f32_16x16x32_bf16 v[44:47], v[140:143], v[202:205], v[44:47]
	v_mfma_f32_16x16x32_bf16 v[24:27], v[132:135], v[210:213], v[24:27]
	v_mfma_f32_16x16x32_bf16 v[28:31], v[140:143], v[210:213], v[28:31]
	v_mfma_f32_16x16x32_bf16 v[8:11], v[132:135], v[218:221], v[8:11]
	v_mfma_f32_16x16x32_bf16 v[12:15], v[140:143], v[218:221], v[12:15]
	v_mfma_f32_16x16x32_bf16 v[52:55], v[144:147], v[186:189], v[52:55]
	v_mfma_f32_16x16x32_bf16 v[48:51], v[168:171], v[186:189], v[48:51]
	v_mfma_f32_16x16x32_bf16 v[36:39], v[144:147], v[198:201], v[36:39]
	v_mfma_f32_16x16x32_bf16 v[32:35], v[168:171], v[198:201], v[32:35]
	v_mfma_f32_16x16x32_bf16 v[20:23], v[144:147], v[206:209], v[20:23]
	v_mfma_f32_16x16x32_bf16 v[16:19], v[168:171], v[206:209], v[16:19]
	v_mfma_f32_16x16x32_bf16 v[4:7], v[144:147], v[214:217], v[4:7]
	v_mfma_f32_16x16x32_bf16 v[0:3], v[168:171], v[214:217], v[0:3]
	v_mfma_f32_16x16x32_bf16 v[52:55], v[148:151], v[190:193], v[52:55]
	v_mfma_f32_16x16x32_bf16 v[48:51], v[172:175], v[190:193], v[48:51]
	v_mfma_f32_16x16x32_bf16 v[36:39], v[148:151], v[202:205], v[36:39]
	v_mfma_f32_16x16x32_bf16 v[32:35], v[172:175], v[202:205], v[32:35]
	v_mfma_f32_16x16x32_bf16 v[20:23], v[148:151], v[210:213], v[20:23]
	v_mfma_f32_16x16x32_bf16 v[16:19], v[172:175], v[210:213], v[16:19]
	v_mfma_f32_16x16x32_bf16 v[4:7], v[148:151], v[218:221], v[4:7]
	v_mfma_f32_16x16x32_bf16 v[0:3], v[172:175], v[218:221], v[0:3]
	s_barrier
	s_setprio 0
	s_add_i32 s54, 0, 0x18000
	s_add_i32 s55, 0, 0x1c000
	v_add_u32_e32 v140, s54, v179
	v_add_u32_e32 v172, s55, v179
	ds_read_b128 v[128:131], v140
	ds_read_b128 v[132:135], v140 offset:1024
	ds_read_b128 v[136:139], v140 offset:2048
	ds_read_b128 v[140:143], v140 offset:3072
	ds_read_b128 v[144:147], v172
	ds_read_b128 v[148:151], v172 offset:1024
	ds_read_b128 v[168:171], v172 offset:2048
	ds_read_b128 v[172:175], v172 offset:3072
	s_add_u32 s30, s30, 0x100000
	s_addc_u32 s31, s31, 0
	s_mov_b32 m0, s37
	v_lshl_add_u64 v[226:227], s[30:31], 0, v[152:153]
	ds_read_b128 v[186:189], v183 offset:32768
	ds_read_b128 v[190:193], v183 offset:33792
	ds_read_b128 v[198:201], v183 offset:34816
	ds_read_b128 v[202:205], v183 offset:35840
	ds_read_b128 v[206:209], v183 offset:36864
	ds_read_b128 v[210:213], v183 offset:37888
	ds_read_b128 v[214:217], v183 offset:38912
	ds_read_b128 v[218:221], v183 offset:39936
	global_load_lds_dwordx4 v[226:227], off
	v_lshl_add_u64 v[226:227], s[30:31], 0, v[156:157]
	s_mov_b32 m0, s39
	s_nop 0
	global_load_lds_dwordx4 v[226:227], off
	s_waitcnt vmcnt(8)
	s_waitcnt lgkmcnt(0)
	s_setprio 1
	s_barrier
	v_mfma_f32_16x16x32_bf16 v[124:127], v[128:131], v[186:189], v[124:127]
	v_mfma_f32_16x16x32_bf16 v[120:123], v[136:139], v[186:189], v[120:123]
	v_mfma_f32_16x16x32_bf16 v[104:107], v[128:131], v[198:201], v[104:107]
	v_mfma_f32_16x16x32_bf16 v[108:111], v[136:139], v[198:201], v[108:111]
	v_mfma_f32_16x16x32_bf16 v[88:91], v[128:131], v[206:209], v[88:91]
	v_mfma_f32_16x16x32_bf16 v[92:95], v[136:139], v[206:209], v[92:95]
	v_mfma_f32_16x16x32_bf16 v[72:75], v[128:131], v[214:217], v[72:75]
	v_mfma_f32_16x16x32_bf16 v[76:79], v[136:139], v[214:217], v[76:79]
	v_mfma_f32_16x16x32_bf16 v[124:127], v[132:135], v[190:193], v[124:127]
	v_mfma_f32_16x16x32_bf16 v[120:123], v[140:143], v[190:193], v[120:123]
	v_mfma_f32_16x16x32_bf16 v[104:107], v[132:135], v[202:205], v[104:107]
	v_mfma_f32_16x16x32_bf16 v[108:111], v[140:143], v[202:205], v[108:111]
	v_mfma_f32_16x16x32_bf16 v[88:91], v[132:135], v[210:213], v[88:91]
	v_mfma_f32_16x16x32_bf16 v[92:95], v[140:143], v[210:213], v[92:95]
	v_mfma_f32_16x16x32_bf16 v[72:75], v[132:135], v[218:221], v[72:75]
	v_mfma_f32_16x16x32_bf16 v[76:79], v[140:143], v[218:221], v[76:79]
	v_mfma_f32_16x16x32_bf16 v[116:119], v[144:147], v[186:189], v[116:119]
	v_mfma_f32_16x16x32_bf16 v[112:115], v[168:171], v[186:189], v[112:115]
	v_mfma_f32_16x16x32_bf16 v[100:103], v[144:147], v[198:201], v[100:103]
	v_mfma_f32_16x16x32_bf16 v[96:99], v[168:171], v[198:201], v[96:99]
	v_mfma_f32_16x16x32_bf16 v[84:87], v[144:147], v[206:209], v[84:87]
	v_mfma_f32_16x16x32_bf16 v[80:83], v[168:171], v[206:209], v[80:83]
	v_mfma_f32_16x16x32_bf16 v[68:71], v[144:147], v[214:217], v[68:71]
	v_mfma_f32_16x16x32_bf16 v[64:67], v[168:171], v[214:217], v[64:67]
	v_mfma_f32_16x16x32_bf16 v[116:119], v[148:151], v[190:193], v[116:119]
	v_mfma_f32_16x16x32_bf16 v[112:115], v[172:175], v[190:193], v[112:115]
	v_mfma_f32_16x16x32_bf16 v[100:103], v[148:151], v[202:205], v[100:103]
	v_mfma_f32_16x16x32_bf16 v[96:99], v[172:175], v[202:205], v[96:99]
	v_mfma_f32_16x16x32_bf16 v[84:87], v[148:151], v[210:213], v[84:87]
	v_mfma_f32_16x16x32_bf16 v[80:83], v[172:175], v[210:213], v[80:83]
	v_mfma_f32_16x16x32_bf16 v[68:71], v[148:151], v[218:221], v[68:71]
	v_mfma_f32_16x16x32_bf16 v[64:67], v[172:175], v[218:221], v[64:67]
	s_barrier
; #define PG8_STAGE(bufoff, gbase, voff) do { _Pragma("unroll") for (int _i = 0; _i < 2; ++_i) \
;         __builtin_amdgcn_global_load_lds((const unsigned*)((const char*)(gbase) + (voff)[_i]), (PG8_LAS unsigned*)(lds + (bufoff) + ldsw + _i * 8192), 16, 0, 0); } while (0)
; #define PG8_LDA(dst, b, h) do { _Pragma("unroll") for (int m = 0; m < 4; ++m) _Pragma("unroll") for (int k = 0; k < 2; ++k) dst[m][k] = *(const PG8_LAS bf16x8*)(lds + PG8_SA(b, h) + aoff + m * 2048 + k * 1024); } while (0)
; #define PG8_MMA(ai, bj, At, Bt) do { __builtin_amdgcn_s_setprio(1); _Pragma("unroll") for (int m = 0; m < 4; ++m) _Pragma("unroll") for (int n = 0; n < 2; ++n) _Pragma("unroll") for (int k = 0; k < 2; ++k) \
;         acc[ai][bj][m][n] = __builtin_amdgcn_mfma_f32_16x16x32_bf16(Bt[n][k], At[m][k], acc[ai][bj][m][n], 0, 0, 0); __builtin_amdgcn_s_setprio(0); } while (0)
; #define PG8_WAIT_V(n) asm volatile("s_waitcnt vmcnt(" #n ")" ::: "memory")
; #define PG8_WAIT_L(n) asm volatile("s_waitcnt lgkmcnt(" #n ")" ::: "memory")
; #define PG8_BAR __builtin_amdgcn_s_barrier()
; #define PG8_SCHED __builtin_amdgcn_sched_barrier(0)
; template <class Epi, class Sched, bool ALIGN_EPI = false, bool SP2 = false>
; __device__ __forceinline__ void gemm_phase(PG8_LAS unsigned char* lds, const Gemm g, const Sched& S, const Epi& E) {
;     ...
;             PG8_WAIT_V(8); PG8_WAIT_L(0); PG8_BAR; PG8_MMA(0, 0, At, B0); PG8_MMA(0, 1, At, B1); PG8_BAR; PG8_SCHED;
;             PG8_LDA(At, 1, 1); PG8_STAGE(PG8_SB(1, 0), b3, voffB); PG8_STAGE(PG8_SB(1, 1), b3 + hstep, voffB); PG8_STAGE(PG8_SA(1, 0), a3, voffA);
;             PG8_WAIT_V(8); PG8_WAIT_L(0); PG8_BAR; PG8_MMA(1, 0, At, B0); PG8_MMA(1, 1, At, B1); PG8_BAR; PG8_SCHED;
;     ...
;         if constexpr (ALIGN_EPI) { if (wr == 0) PG8_BAR; }
	s_setprio 0
	s_add_i32 s30, s54, s34
	v_lshl_add_u64 v[176:177], v[176:177], 0, s[12:13]
	s_mov_b32 m0, s30
	ds_read_b128 v[186:189], v183 offset:49152
	ds_read_b128 v[190:193], v183 offset:50176
	ds_read_b128 v[198:201], v183 offset:51200
	ds_read_b128 v[202:205], v183 offset:52224
	ds_read_b128 v[206:209], v183 offset:53248
	ds_read_b128 v[210:213], v183 offset:54272
	ds_read_b128 v[214:217], v183 offset:55296
	ds_read_b128 v[218:221], v183 offset:56320
	global_load_lds_dwordx4 v[176:177], off
	s_add_i32 m0, s30, 0x2000
	s_add_u32 s28, s28, 0x100080
	v_lshl_add_u64 v[176:177], v[194:195], 0, s[12:13]
	s_addc_u32 s29, s29, 0
	s_add_i32 s30, s55, s34
	global_load_lds_dwordx4 v[176:177], off
	v_lshl_add_u64 v[176:177], s[28:29], 0, v[154:155]
	s_mov_b32 m0, s30
	s_nop 0
	global_load_lds_dwordx4 v[176:177], off
	v_lshl_add_u64 v[176:177], s[28:29], 0, v[158:159]
	s_add_i32 m0, s30, 0x2000
	s_nop 0
	global_load_lds_dwordx4 v[176:177], off
	v_lshl_add_u64 v[176:177], v[222:223], 0, s[12:13]
	s_mov_b32 m0, s43
	s_nop 0
	global_load_lds_dwordx4 v[176:177], off
	v_lshl_add_u64 v[176:177], v[224:225], 0, s[12:13]
	s_mov_b32 m0, s44
	s_nop 0
	global_load_lds_dwordx4 v[176:177], off
	s_waitcnt vmcnt(8)
	s_waitcnt lgkmcnt(0)
	s_setprio 1
	s_barrier
	v_mfma_f32_16x16x32_bf16 v[56:59], v[128:131], v[186:189], v[56:59]
	v_mfma_f32_16x16x32_bf16 v[60:63], v[136:139], v[186:189], v[60:63]
	v_mfma_f32_16x16x32_bf16 v[40:43], v[128:131], v[198:201], v[40:43]
	v_mfma_f32_16x16x32_bf16 v[44:47], v[136:139], v[198:201], v[44:47]
	v_mfma_f32_16x16x32_bf16 v[24:27], v[128:131], v[206:209], v[24:27]
	v_mfma_f32_16x16x32_bf16 v[28:31], v[136:139], v[206:209], v[28:31]
	v_mfma_f32_16x16x32_bf16 v[8:11], v[128:131], v[214:217], v[8:11]
	v_mfma_f32_16x16x32_bf16 v[12:15], v[136:139], v[214:217], v[12:15]
	v_mfma_f32_16x16x32_bf16 v[56:59], v[132:135], v[190:193], v[56:59]
	v_mfma_f32_16x16x32_bf16 v[60:63], v[140:143], v[190:193], v[60:63]
	v_mfma_f32_16x16x32_bf16 v[40:43], v[132:135], v[202:205], v[40:43]
	v_mfma_f32_16x16x32_bf16 v[44:47], v[140:143], v[202:205], v[44:47]
	v_mfma_f32_16x16x32_bf16 v[24:27], v[132:135], v[210:213], v[24:27]
	v_mfma_f32_16x16x32_bf16 v[28:31], v[140:143], v[210:213], v[28:31]
	v_mfma_f32_16x16x32_bf16 v[8:11], v[132:135], v[218:221], v[8:11]
	v_mfma_f32_16x16x32_bf16 v[12:15], v[140:143], v[218:221], v[12:15]
	v_mfma_f32_16x16x32_bf16 v[52:55], v[144:147], v[186:189], v[52:55]
	v_mfma_f32_16x16x32_bf16 v[48:51], v[168:171], v[186:189], v[48:51]
	v_mfma_f32_16x16x32_bf16 v[36:39], v[144:147], v[198:201], v[36:39]
	v_mfma_f32_16x16x32_bf16 v[32:35], v[168:171], v[198:201], v[32:35]
	v_mfma_f32_16x16x32_bf16 v[20:23], v[144:147], v[206:209], v[20:23]
	v_mfma_f32_16x16x32_bf16 v[16:19], v[168:171], v[206:209], v[16:19]
	v_mfma_f32_16x16x32_bf16 v[4:7], v[144:147], v[214:217], v[4:7]
	v_mfma_f32_16x16x32_bf16 v[0:3], v[168:171], v[214:217], v[0:3]
	v_mfma_f32_16x16x32_bf16 v[52:55], v[148:151], v[190:193], v[52:55]
	v_mfma_f32_16x16x32_bf16 v[48:51], v[172:175], v[190:193], v[48:51]
	v_mfma_f32_16x16x32_bf16 v[36:39], v[148:151], v[202:205], v[36:39]
	v_mfma_f32_16x16x32_bf16 v[32:35], v[172:175], v[202:205], v[32:35]
	v_mfma_f32_16x16x32_bf16 v[20:23], v[148:151], v[210:213], v[20:23]
	v_mfma_f32_16x16x32_bf16 v[16:19], v[172:175], v[210:213], v[16:19]
	v_mfma_f32_16x16x32_bf16 v[4:7], v[148:151], v[218:221], v[4:7]
	v_mfma_f32_16x16x32_bf16 v[0:3], v[172:175], v[218:221], v[0:3]
	s_barrier
	s_setprio 0
	s_add_i32 s53, s53, 2
	s_add_u32 s26, s26, 0x100
	s_addc_u32 s27, s27, 0
	s_add_u32 s49, s49, 0x100
	s_addc_u32 s52, s52, 0
	s_cmp_gt_u32 s53, 61
	s_cbranch_scc0 .LBB0_763
	s_and_b64 vcc, exec, s[14:15]
	s_cbranch_vccz .LBB0_766
	s_barrier

; #define PG8_STAGE(bufoff, gbase, voff) do { _Pragma("unroll") for (int _i = 0; _i < 2; ++_i) \
;         __builtin_amdgcn_global_load_lds((const unsigned*)((const char*)(gbase) + (voff)[_i]), (PG8_LAS unsigned*)(lds + (bufoff) + ldsw + _i * 8192), 16, 0, 0); } while (0)
; #define PG8_LDA(dst, b, h) do { _Pragma("unroll") for (int m = 0; m < 4; ++m) _Pragma("unroll") for (int k = 0; k < 2; ++k) dst[m][k] = *(const PG8_LAS bf16x8*)(lds + PG8_SA(b, h) + aoff + m * 2048 + k * 1024); } while (0)
; #define PG8_LDB(dst, b, h) do { _Pragma("unroll") for (int n = 0; n < 2; ++n) _Pragma("unroll") for (int k = 0; k < 2; ++k) dst[n][k] = *(const PG8_LAS bf16x8*)(lds + PG8_SB(b, h) + boff + n * 2048 + k * 1024); } while (0)
; #define PG8_MMA(ai, bj, At, Bt) do { __builtin_amdgcn_s_setprio(1); _Pragma("unroll") for (int m = 0; m < 4; ++m) _Pragma("unroll") for (int n = 0; n < 2; ++n) _Pragma("unroll") for (int k = 0; k < 2; ++k) \
;         acc[ai][bj][m][n] = __builtin_amdgcn_mfma_f32_16x16x32_bf16(Bt[n][k], At[m][k], acc[ai][bj][m][n], 0, 0, 0); __builtin_amdgcn_s_setprio(0); } while (0)
; #define PG8_WAIT_V(n) asm volatile("s_waitcnt vmcnt(" #n ")" ::: "memory")
; #define PG8_WAIT_L(n) asm volatile("s_waitcnt lgkmcnt(" #n ")" ::: "memory")
; template <class Epi, class Sched, bool ALIGN_EPI = false, bool SP2 = false>
; __device__ __forceinline__ void gemm_phase(PG8_LAS unsigned char* lds, const Gemm g, const Sched& S, const Epi& E) {
;     ...
;             const bool last = (t == nt - 2);
;             const char* a1 = cA + (size_t)(t + 1) * kstep;
;             const char* a2 = last ? nA : cA + (size_t)(t + 2) * kstep; const char* b2 = last ? nB : cB + (size_t)(t + 2) * kstep;
;             const char* a3 = a2 + kstep; const char* b3 = b2 + kstep;
;             if (last && has_next) S.a_ready(nxt);
;             if constexpr (SP2) {
;             PG8_LDB(B0, 0, 0); PG8_LDB(B1, 0, 1); PG8_SCHED; PG8_LDA(At, 0, 0); PG8_STAGE(PG8_SA(1, 1), a1 + hstep, voffA);
;             PG8_WAIT_V(8); PG8_WAIT_L(0); PG8_BAR; PG8_MMA(0, 0, At, B0); PG8_MMA(0, 1, At, B1); PG8_BAR; PG8_SCHED;
;             PG8_LDA(At, 0, 1); PG8_STAGE(PG8_SB(0, 0), b2, voffB); PG8_STAGE(PG8_SB(0, 1), b2 + hstep, voffB); PG8_STAGE(PG8_SA(0, 0), a2, voffA);
;             PG8_WAIT_V(8); PG8_WAIT_L(0); PG8_BAR; PG8_MMA(1, 0, At, B0); PG8_MMA(1, 1, At, B1); PG8_BAR; PG8_SCHED;
.LBB0_955:
	ds_read_b128 v[128:131], v209
	ds_read_b128 v[132:135], v209 offset:1024
	ds_read_b128 v[136:139], v209 offset:2048
	ds_read_b128 v[178:181], v209 offset:3072
	ds_read_b128 v[182:185], v210
	ds_read_b128 v[186:189], v210 offset:1024
	ds_read_b128 v[190:193], v210 offset:2048
	ds_read_b128 v[222:225], v210 offset:3072
	s_add_u32 s28, s26, 0xfff80080
	s_addc_u32 s29, s27, -1
	s_cmp_eq_u32 s45, 28
	s_cselect_b32 s31, s1, s29
	s_cselect_b32 s30, s5, s28
	s_cselect_b32 s29, s17, s44
	s_cselect_b32 s28, s19, s33
	v_lshl_add_u64 v[166:167], s[26:27], 0, v[150:151]
	s_add_i32 m0, s35, 0xc000
	ds_read_b128 v[226:229], v211
	ds_read_b128 v[230:233], v211 offset:1024
	ds_read_b128 v[234:237], v211 offset:2048
	ds_read_b128 v[238:241], v211 offset:3072
	ds_read_b128 v[242:245], v211 offset:4096
	ds_read_b128 v[246:249], v211 offset:5120
	ds_read_b128 v[250:253], v211 offset:6144
	ds_read_b128 v[160:163], v211 offset:7168
	global_load_lds_dwordx4 v[166:167], off
	v_lshl_add_u64 v[166:167], s[26:27], 0, v[152:153]
	s_add_i32 m0, s35, 0xe000
	s_nop 0
	global_load_lds_dwordx4 v[166:167], off
	s_waitcnt vmcnt(8)
	s_waitcnt lgkmcnt(0)
	s_setprio 1
	s_barrier
	v_mfma_f32_16x16x32_bf16 v[124:127], v[128:131], v[226:229], v[124:127]
	v_mfma_f32_16x16x32_bf16 v[120:123], v[136:139], v[226:229], v[120:123]
	v_mfma_f32_16x16x32_bf16 v[116:119], v[128:131], v[234:237], v[116:119]
	v_mfma_f32_16x16x32_bf16 v[108:111], v[136:139], v[234:237], v[108:111]
	v_mfma_f32_16x16x32_bf16 v[100:103], v[128:131], v[242:245], v[100:103]
	v_mfma_f32_16x16x32_bf16 v[92:95], v[136:139], v[242:245], v[92:95]
	v_mfma_f32_16x16x32_bf16 v[84:87], v[128:131], v[250:253], v[84:87]
	v_mfma_f32_16x16x32_bf16 v[76:79], v[136:139], v[250:253], v[76:79]
	v_mfma_f32_16x16x32_bf16 v[124:127], v[132:135], v[230:233], v[124:127]
	v_mfma_f32_16x16x32_bf16 v[120:123], v[178:181], v[230:233], v[120:123]
	v_mfma_f32_16x16x32_bf16 v[116:119], v[132:135], v[238:241], v[116:119]
	v_mfma_f32_16x16x32_bf16 v[108:111], v[178:181], v[238:241], v[108:111]
	v_mfma_f32_16x16x32_bf16 v[100:103], v[132:135], v[246:249], v[100:103]
	v_mfma_f32_16x16x32_bf16 v[92:95], v[178:181], v[246:249], v[92:95]
	v_mfma_f32_16x16x32_bf16 v[84:87], v[132:135], v[160:163], v[84:87]
	v_mfma_f32_16x16x32_bf16 v[76:79], v[178:181], v[160:163], v[76:79]
	v_mfma_f32_16x16x32_bf16 v[112:115], v[182:185], v[226:229], v[112:115]
	v_mfma_f32_16x16x32_bf16 v[104:107], v[190:193], v[226:229], v[104:107]
	v_mfma_f32_16x16x32_bf16 v[96:99], v[182:185], v[234:237], v[96:99]
	v_mfma_f32_16x16x32_bf16 v[88:91], v[190:193], v[234:237], v[88:91]
	v_mfma_f32_16x16x32_bf16 v[80:83], v[182:185], v[242:245], v[80:83]
	v_mfma_f32_16x16x32_bf16 v[72:75], v[190:193], v[242:245], v[72:75]
	v_mfma_f32_16x16x32_bf16 v[68:71], v[182:185], v[250:253], v[68:71]
	v_mfma_f32_16x16x32_bf16 v[64:67], v[190:193], v[250:253], v[64:67]
	v_mfma_f32_16x16x32_bf16 v[112:115], v[186:189], v[230:233], v[112:115]
	v_mfma_f32_16x16x32_bf16 v[104:107], v[222:225], v[230:233], v[104:107]
	v_mfma_f32_16x16x32_bf16 v[96:99], v[186:189], v[238:241], v[96:99]
	v_mfma_f32_16x16x32_bf16 v[88:91], v[222:225], v[238:241], v[88:91]
	v_mfma_f32_16x16x32_bf16 v[80:83], v[186:189], v[246:249], v[80:83]
	v_mfma_f32_16x16x32_bf16 v[72:75], v[222:225], v[246:249], v[72:75]
	v_mfma_f32_16x16x32_bf16 v[68:71], v[186:189], v[160:163], v[68:71]
	v_mfma_f32_16x16x32_bf16 v[64:67], v[222:225], v[160:163], v[64:67]
	s_barrier
	s_setprio 0
	s_add_i32 s48, s69, s34
	v_lshl_add_u64 v[166:167], s[28:29], 0, v[142:143]
	s_mov_b32 m0, s48
	ds_read_b128 v[160:163], v211 offset:16384
	ds_read_b128 v[226:229], v211 offset:17408
	ds_read_b128 v[230:233], v211 offset:18432
	ds_read_b128 v[234:237], v211 offset:19456
	ds_read_b128 v[238:241], v211 offset:20480
	ds_read_b128 v[242:245], v211 offset:21504
	ds_read_b128 v[246:249], v211 offset:22528
	ds_read_b128 v[250:253], v211 offset:23552
	global_load_lds_dwordx4 v[166:167], off
	s_add_i32 m0, s48, 0x2000
	s_add_u32 s48, s28, 0x80000
	v_lshl_add_u64 v[170:171], s[28:29], 0, v[146:147]
	s_addc_u32 s49, s29, 0
	s_add_i32 s50, s70, s34
	global_load_lds_dwordx4 v[170:171], off
	v_lshl_add_u64 v[174:175], s[48:49], 0, v[142:143]
	s_mov_b32 m0, s50
	v_lshl_add_u64 v[194:195], s[30:31], 0, v[144:145]
	global_load_lds_dwordx4 v[174:175], off
	v_lshl_add_u64 v[174:175], s[48:49], 0, v[146:147]
	s_add_i32 m0, s50, 0x2000
	s_nop 0
	global_load_lds_dwordx4 v[174:175], off
	v_lshl_add_u64 v[174:175], s[30:31], 0, v[140:141]
	s_mov_b32 m0, s35
	s_nop 0
	global_load_lds_dwordx4 v[174:175], off
	s_mov_b32 m0, s37
	s_nop 0
	global_load_lds_dwordx4 v[194:195], off
	s_waitcnt vmcnt(8)
	s_waitcnt lgkmcnt(0)
	s_setprio 1
	s_barrier
; #define PG8_STAGE(bufoff, gbase, voff) do { _Pragma("unroll") for (int _i = 0; _i < 2; ++_i) \
;         __builtin_amdgcn_global_load_lds((const unsigned*)((const char*)(gbase) + (voff)[_i]), (PG8_LAS unsigned*)(lds + (bufoff) + ldsw + _i * 8192), 16, 0, 0); } while (0)
; #define PG8_LDA(dst, b, h) do { _Pragma("unroll") for (int m = 0; m < 4; ++m) _Pragma("unroll") for (int k = 0; k < 2; ++k) dst[m][k] = *(const PG8_LAS bf16x8*)(lds + PG8_SA(b, h) + aoff + m * 2048 + k * 1024); } while (0)
; #define PG8_LDB(dst, b, h) do { _Pragma("unroll") for (int n = 0; n < 2; ++n) _Pragma("unroll") for (int k = 0; k < 2; ++k) dst[n][k] = *(const PG8_LAS bf16x8*)(lds + PG8_SB(b, h) + boff + n * 2048 + k * 1024); } while (0)
; #define PG8_MMA(ai, bj, At, Bt) do { __builtin_amdgcn_s_setprio(1); _Pragma("unroll") for (int m = 0; m < 4; ++m) _Pragma("unroll") for (int n = 0; n < 2; ++n) _Pragma("unroll") for (int k = 0; k < 2; ++k) \
;         acc[ai][bj][m][n] = __builtin_amdgcn_mfma_f32_16x16x32_bf16(Bt[n][k], At[m][k], acc[ai][bj][m][n], 0, 0, 0); __builtin_amdgcn_s_setprio(0); } while (0)
; #define PG8_WAIT_V(n) asm volatile("s_waitcnt vmcnt(" #n ")" ::: "memory")
; #define PG8_WAIT_L(n) asm volatile("s_waitcnt lgkmcnt(" #n ")" ::: "memory")
; #define PG8_BAR __builtin_amdgcn_s_barrier()
; #define PG8_SCHED __builtin_amdgcn_sched_barrier(0)
; template <class Epi, class Sched, bool ALIGN_EPI = false, bool SP2 = false>
; __device__ __forceinline__ void gemm_phase(PG8_LAS unsigned char* lds, const Gemm g, const Sched& S, const Epi& E) {
;     ...
;             PG8_WAIT_V(8); PG8_WAIT_L(0); PG8_BAR; PG8_MMA(1, 0, At, B0); PG8_MMA(1, 1, At, B1); PG8_BAR; PG8_SCHED;
;             PG8_LDB(B0, 1, 0); PG8_LDB(B1, 1, 1); PG8_SCHED; PG8_LDA(At, 1, 0); PG8_STAGE(PG8_SA(0, 1), a2 + hstep, voffA);
;             PG8_WAIT_V(8); PG8_WAIT_L(0); PG8_BAR; PG8_MMA(0, 0, At, B0); PG8_MMA(0, 1, At, B1); PG8_BAR; PG8_SCHED;
	v_mfma_f32_16x16x32_bf16 v[60:63], v[128:131], v[160:163], v[60:63]
	v_mfma_f32_16x16x32_bf16 v[56:59], v[136:139], v[160:163], v[56:59]
	v_mfma_f32_16x16x32_bf16 v[52:55], v[128:131], v[230:233], v[52:55]
	v_mfma_f32_16x16x32_bf16 v[44:47], v[136:139], v[230:233], v[44:47]
	v_mfma_f32_16x16x32_bf16 v[36:39], v[128:131], v[238:241], v[36:39]
	v_mfma_f32_16x16x32_bf16 v[28:31], v[136:139], v[238:241], v[28:31]
	v_mfma_f32_16x16x32_bf16 v[20:23], v[128:131], v[246:249], v[20:23]
	v_mfma_f32_16x16x32_bf16 v[12:15], v[136:139], v[246:249], v[12:15]
	v_mfma_f32_16x16x32_bf16 v[60:63], v[132:135], v[226:229], v[60:63]
	v_mfma_f32_16x16x32_bf16 v[56:59], v[178:181], v[226:229], v[56:59]
	v_mfma_f32_16x16x32_bf16 v[52:55], v[132:135], v[234:237], v[52:55]
	v_mfma_f32_16x16x32_bf16 v[44:47], v[178:181], v[234:237], v[44:47]
	v_mfma_f32_16x16x32_bf16 v[36:39], v[132:135], v[242:245], v[36:39]
	v_mfma_f32_16x16x32_bf16 v[28:31], v[178:181], v[242:245], v[28:31]
	v_mfma_f32_16x16x32_bf16 v[20:23], v[132:135], v[250:253], v[20:23]
	v_mfma_f32_16x16x32_bf16 v[12:15], v[178:181], v[250:253], v[12:15]
	v_mfma_f32_16x16x32_bf16 v[48:51], v[182:185], v[160:163], v[48:51]
	v_mfma_f32_16x16x32_bf16 v[40:43], v[190:193], v[160:163], v[40:43]
	v_mfma_f32_16x16x32_bf16 v[32:35], v[182:185], v[230:233], v[32:35]
	v_mfma_f32_16x16x32_bf16 v[24:27], v[190:193], v[230:233], v[24:27]
	v_mfma_f32_16x16x32_bf16 v[16:19], v[182:185], v[238:241], v[16:19]
	v_mfma_f32_16x16x32_bf16 v[8:11], v[190:193], v[238:241], v[8:11]
	v_mfma_f32_16x16x32_bf16 v[4:7], v[182:185], v[246:249], v[4:7]
	v_mfma_f32_16x16x32_bf16 v[0:3], v[190:193], v[246:249], v[0:3]
	v_mfma_f32_16x16x32_bf16 v[48:51], v[186:189], v[226:229], v[48:51]
	v_mfma_f32_16x16x32_bf16 v[40:43], v[222:225], v[226:229], v[40:43]
	v_mfma_f32_16x16x32_bf16 v[32:35], v[186:189], v[234:237], v[32:35]
	v_mfma_f32_16x16x32_bf16 v[24:27], v[222:225], v[234:237], v[24:27]
	v_mfma_f32_16x16x32_bf16 v[16:19], v[186:189], v[242:245], v[16:19]
	v_mfma_f32_16x16x32_bf16 v[8:11], v[222:225], v[242:245], v[8:11]
	v_mfma_f32_16x16x32_bf16 v[4:7], v[186:189], v[250:253], v[4:7]
	v_mfma_f32_16x16x32_bf16 v[0:3], v[222:225], v[250:253], v[0:3]
	s_barrier
	s_setprio 0
	s_add_i32 s48, 0, 0x18000
	v_add_u32_e32 v148, s48, v159
	s_add_i32 s49, 0, 0x1c000
	ds_read_b128 v[128:131], v148
	ds_read_b128 v[132:135], v148 offset:1024
	ds_read_b128 v[136:139], v148 offset:2048
	ds_read_b128 v[160:163], v148 offset:3072
	v_add_u32_e32 v148, s49, v159
	ds_read_b128 v[178:181], v148
	ds_read_b128 v[182:185], v148 offset:1024
	ds_read_b128 v[186:189], v148 offset:2048
	ds_read_b128 v[190:193], v148 offset:3072
	s_add_u32 s30, s30, 0x80000
	s_addc_u32 s31, s31, 0
	s_mov_b32 m0, s39
	v_lshl_add_u64 v[154:155], s[30:31], 0, v[140:141]
	ds_read_b128 v[222:225], v211 offset:32768
	ds_read_b128 v[226:229], v211 offset:33792
	ds_read_b128 v[230:233], v211 offset:34816
	ds_read_b128 v[234:237], v211 offset:35840
	ds_read_b128 v[238:241], v211 offset:36864
	ds_read_b128 v[242:245], v211 offset:37888
	ds_read_b128 v[246:249], v211 offset:38912
	ds_read_b128 v[250:253], v211 offset:39936
	global_load_lds_dwordx4 v[154:155], off
	v_lshl_add_u64 v[154:155], s[30:31], 0, v[144:145]
	s_mov_b32 m0, s42
	s_nop 0
	global_load_lds_dwordx4 v[154:155], off
	s_waitcnt vmcnt(8)
	s_waitcnt lgkmcnt(0)
	s_setprio 1
	s_barrier
	v_mfma_f32_16x16x32_bf16 v[124:127], v[128:131], v[222:225], v[124:127]
	v_mfma_f32_16x16x32_bf16 v[120:123], v[136:139], v[222:225], v[120:123]
	v_mfma_f32_16x16x32_bf16 v[116:119], v[128:131], v[230:233], v[116:119]
	v_mfma_f32_16x16x32_bf16 v[108:111], v[136:139], v[230:233], v[108:111]
	v_mfma_f32_16x16x32_bf16 v[100:103], v[128:131], v[238:241], v[100:103]
	v_mfma_f32_16x16x32_bf16 v[92:95], v[136:139], v[238:241], v[92:95]
	v_mfma_f32_16x16x32_bf16 v[84:87], v[128:131], v[246:249], v[84:87]
	v_mfma_f32_16x16x32_bf16 v[76:79], v[136:139], v[246:249], v[76:79]
	v_mfma_f32_16x16x32_bf16 v[124:127], v[132:135], v[226:229], v[124:127]
	v_mfma_f32_16x16x32_bf16 v[120:123], v[160:163], v[226:229], v[120:123]
	v_mfma_f32_16x16x32_bf16 v[116:119], v[132:135], v[234:237], v[116:119]
	v_mfma_f32_16x16x32_bf16 v[108:111], v[160:163], v[234:237], v[108:111]
	v_mfma_f32_16x16x32_bf16 v[100:103], v[132:135], v[242:245], v[100:103]
	v_mfma_f32_16x16x32_bf16 v[92:95], v[160:163], v[242:245], v[92:95]
	v_mfma_f32_16x16x32_bf16 v[84:87], v[132:135], v[250:253], v[84:87]
	v_mfma_f32_16x16x32_bf16 v[76:79], v[160:163], v[250:253], v[76:79]
	v_mfma_f32_16x16x32_bf16 v[112:115], v[178:181], v[222:225], v[112:115]
	v_mfma_f32_16x16x32_bf16 v[104:107], v[186:189], v[222:225], v[104:107]
	v_mfma_f32_16x16x32_bf16 v[96:99], v[178:181], v[230:233], v[96:99]
	v_mfma_f32_16x16x32_bf16 v[88:91], v[186:189], v[230:233], v[88:91]
	v_mfma_f32_16x16x32_bf16 v[80:83], v[178:181], v[238:241], v[80:83]
	v_mfma_f32_16x16x32_bf16 v[72:75], v[186:189], v[238:241], v[72:75]
	v_mfma_f32_16x16x32_bf16 v[68:71], v[178:181], v[246:249], v[68:71]
	v_mfma_f32_16x16x32_bf16 v[64:67], v[186:189], v[246:249], v[64:67]
	v_mfma_f32_16x16x32_bf16 v[112:115], v[182:185], v[226:229], v[112:115]
	v_mfma_f32_16x16x32_bf16 v[104:107], v[190:193], v[226:229], v[104:107]
	v_mfma_f32_16x16x32_bf16 v[96:99], v[182:185], v[234:237], v[96:99]
	v_mfma_f32_16x16x32_bf16 v[88:91], v[190:193], v[234:237], v[88:91]
	v_mfma_f32_16x16x32_bf16 v[80:83], v[182:185], v[242:245], v[80:83]
	v_mfma_f32_16x16x32_bf16 v[72:75], v[190:193], v[242:245], v[72:75]
	v_mfma_f32_16x16x32_bf16 v[68:71], v[182:185], v[250:253], v[68:71]
	v_mfma_f32_16x16x32_bf16 v[64:67], v[190:193], v[250:253], v[64:67]
	s_barrier
; #define PG8_STAGE(bufoff, gbase, voff) do { _Pragma("unroll") for (int _i = 0; _i < 2; ++_i) \
;         __builtin_amdgcn_global_load_lds((const unsigned*)((const char*)(gbase) + (voff)[_i]), (PG8_LAS unsigned*)(lds + (bufoff) + ldsw + _i * 8192), 16, 0, 0); } while (0)
; #define PG8_LDA(dst, b, h) do { _Pragma("unroll") for (int m = 0; m < 4; ++m) _Pragma("unroll") for (int k = 0; k < 2; ++k) dst[m][k] = *(const PG8_LAS bf16x8*)(lds + PG8_SA(b, h) + aoff + m * 2048 + k * 1024); } while (0)
; #define PG8_MMA(ai, bj, At, Bt) do { __builtin_amdgcn_s_setprio(1); _Pragma("unroll") for (int m = 0; m < 4; ++m) _Pragma("unroll") for (int n = 0; n < 2; ++n) _Pragma("unroll") for (int k = 0; k < 2; ++k) \
;         acc[ai][bj][m][n] = __builtin_amdgcn_mfma_f32_16x16x32_bf16(Bt[n][k], At[m][k], acc[ai][bj][m][n], 0, 0, 0); __builtin_amdgcn_s_setprio(0); } while (0)
; #define PG8_WAIT_V(n) asm volatile("s_waitcnt vmcnt(" #n ")" ::: "memory")
; #define PG8_WAIT_L(n) asm volatile("s_waitcnt lgkmcnt(" #n ")" ::: "memory")
; #define PG8_BAR __builtin_amdgcn_s_barrier()
; #define PG8_SCHED __builtin_amdgcn_sched_barrier(0)
; template <class Epi, class Sched, bool ALIGN_EPI = false, bool SP2 = false>
; __device__ __forceinline__ void gemm_phase(PG8_LAS unsigned char* lds, const Gemm g, const Sched& S, const Epi& E) {
;     ...
;             PG8_WAIT_V(8); PG8_WAIT_L(0); PG8_BAR; PG8_MMA(0, 0, At, B0); PG8_MMA(0, 1, At, B1); PG8_BAR; PG8_SCHED;
;             PG8_LDA(At, 1, 1); PG8_STAGE(PG8_SB(1, 0), b3, voffB); PG8_STAGE(PG8_SB(1, 1), b3 + hstep, voffB); PG8_STAGE(PG8_SA(1, 0), a3, voffA);
;             PG8_WAIT_V(8); PG8_WAIT_L(0); PG8_BAR; PG8_MMA(1, 0, At, B0); PG8_MMA(1, 1, At, B1); PG8_BAR; PG8_SCHED;
;     ...
;         if constexpr (ALIGN_EPI) { if (wr == 0) PG8_BAR; }
	s_setprio 0
	s_add_i32 s30, s48, s34
	v_lshl_add_u64 v[154:155], v[166:167], 0, s[10:11]
	s_mov_b32 m0, s30
	ds_read_b128 v[222:225], v211 offset:49152
	ds_read_b128 v[226:229], v211 offset:50176
	ds_read_b128 v[230:233], v211 offset:51200
	ds_read_b128 v[234:237], v211 offset:52224
	ds_read_b128 v[238:241], v211 offset:53248
	ds_read_b128 v[242:245], v211 offset:54272
	ds_read_b128 v[246:249], v211 offset:55296
	ds_read_b128 v[250:253], v211 offset:56320
	global_load_lds_dwordx4 v[154:155], off
	s_add_i32 m0, s30, 0x2000
	s_add_u32 s28, s28, 0x80080
	v_lshl_add_u64 v[154:155], v[170:171], 0, s[10:11]
	s_addc_u32 s29, s29, 0
	s_add_i32 s30, s49, s34
	global_load_lds_dwordx4 v[154:155], off
	v_lshl_add_u64 v[154:155], s[28:29], 0, v[142:143]
	s_mov_b32 m0, s30
	s_nop 0
	global_load_lds_dwordx4 v[154:155], off
	v_lshl_add_u64 v[154:155], s[28:29], 0, v[146:147]
	s_add_i32 m0, s30, 0x2000
	s_nop 0
	global_load_lds_dwordx4 v[154:155], off
	v_lshl_add_u64 v[154:155], v[174:175], 0, s[10:11]
	s_mov_b32 m0, s46
	s_nop 0
	global_load_lds_dwordx4 v[154:155], off
	v_lshl_add_u64 v[154:155], v[194:195], 0, s[10:11]
	s_mov_b32 m0, s47
	s_nop 0
	global_load_lds_dwordx4 v[154:155], off
	s_waitcnt vmcnt(8)
	s_waitcnt lgkmcnt(0)
	s_setprio 1
	s_barrier
	v_mfma_f32_16x16x32_bf16 v[60:63], v[128:131], v[222:225], v[60:63]
	v_mfma_f32_16x16x32_bf16 v[56:59], v[136:139], v[222:225], v[56:59]
	v_mfma_f32_16x16x32_bf16 v[52:55], v[128:131], v[230:233], v[52:55]
	v_mfma_f32_16x16x32_bf16 v[44:47], v[136:139], v[230:233], v[44:47]
	v_mfma_f32_16x16x32_bf16 v[36:39], v[128:131], v[238:241], v[36:39]
	v_mfma_f32_16x16x32_bf16 v[28:31], v[136:139], v[238:241], v[28:31]
	v_mfma_f32_16x16x32_bf16 v[20:23], v[128:131], v[246:249], v[20:23]
	v_mfma_f32_16x16x32_bf16 v[12:15], v[136:139], v[246:249], v[12:15]
	v_mfma_f32_16x16x32_bf16 v[60:63], v[132:135], v[226:229], v[60:63]
	v_mfma_f32_16x16x32_bf16 v[56:59], v[160:163], v[226:229], v[56:59]
	v_mfma_f32_16x16x32_bf16 v[52:55], v[132:135], v[234:237], v[52:55]
	v_mfma_f32_16x16x32_bf16 v[44:47], v[160:163], v[234:237], v[44:47]
	v_mfma_f32_16x16x32_bf16 v[36:39], v[132:135], v[242:245], v[36:39]
	v_mfma_f32_16x16x32_bf16 v[28:31], v[160:163], v[242:245], v[28:31]
	v_mfma_f32_16x16x32_bf16 v[20:23], v[132:135], v[250:253], v[20:23]
	v_mfma_f32_16x16x32_bf16 v[12:15], v[160:163], v[250:253], v[12:15]
	v_mfma_f32_16x16x32_bf16 v[48:51], v[178:181], v[222:225], v[48:51]
	v_mfma_f32_16x16x32_bf16 v[40:43], v[186:189], v[222:225], v[40:43]
	v_mfma_f32_16x16x32_bf16 v[32:35], v[178:181], v[230:233], v[32:35]
	v_mfma_f32_16x16x32_bf16 v[24:27], v[186:189], v[230:233], v[24:27]
	v_mfma_f32_16x16x32_bf16 v[16:19], v[178:181], v[238:241], v[16:19]
	v_mfma_f32_16x16x32_bf16 v[8:11], v[186:189], v[238:241], v[8:11]
	v_mfma_f32_16x16x32_bf16 v[4:7], v[178:181], v[246:249], v[4:7]
	v_mfma_f32_16x16x32_bf16 v[0:3], v[186:189], v[246:249], v[0:3]
	v_mfma_f32_16x16x32_bf16 v[48:51], v[182:185], v[226:229], v[48:51]
	v_mfma_f32_16x16x32_bf16 v[40:43], v[190:193], v[226:229], v[40:43]
	v_mfma_f32_16x16x32_bf16 v[32:35], v[182:185], v[234:237], v[32:35]
	v_mfma_f32_16x16x32_bf16 v[24:27], v[190:193], v[234:237], v[24:27]
	v_mfma_f32_16x16x32_bf16 v[16:19], v[182:185], v[242:245], v[16:19]
	v_mfma_f32_16x16x32_bf16 v[8:11], v[190:193], v[242:245], v[8:11]
	v_mfma_f32_16x16x32_bf16 v[4:7], v[182:185], v[250:253], v[4:7]
	v_mfma_f32_16x16x32_bf16 v[0:3], v[190:193], v[250:253], v[0:3]
	s_barrier
	s_setprio 0
	s_add_i32 s45, s45, 2
	s_add_u32 s26, s26, 0x100
	s_addc_u32 s27, s27, 0
	s_add_u32 s33, s33, 0x100
	s_addc_u32 s44, s44, 0
	s_cmp_gt_u32 s45, 29
	s_cbranch_scc0 .LBB0_955
	s_and_b64 vcc, exec, s[12:13]
	s_cbranch_vccz .LBB0_958
	s_barrier

; #define PG8_STAGE(bufoff, gbase, voff) do { _Pragma("unroll") for (int _i = 0; _i < 2; ++_i) \
;         __builtin_amdgcn_global_load_lds((const unsigned*)((const char*)(gbase) + (voff)[_i]), (PG8_LAS unsigned*)(lds + (bufoff) + ldsw + _i * 8192), 16, 0, 0); } while (0)
; #define PG8_LDA(dst, b, h) do { _Pragma("unroll") for (int m = 0; m < 4; ++m) _Pragma("unroll") for (int k = 0; k < 2; ++k) dst[m][k] = *(const PG8_LAS bf16x8*)(lds + PG8_SA(b, h) + aoff + m * 2048 + k * 1024); } while (0)
; #define PG8_LDB(dst, b, h) do { _Pragma("unroll") for (int n = 0; n < 2; ++n) _Pragma("unroll") for (int k = 0; k < 2; ++k) dst[n][k] = *(const PG8_LAS bf16x8*)(lds + PG8_SB(b, h) + boff + n * 2048 + k * 1024); } while (0)
; #define PG8_MMA(ai, bj, At, Bt) do { __builtin_amdgcn_s_setprio(1); _Pragma("unroll") for (int m = 0; m < 4; ++m) _Pragma("unroll") for (int n = 0; n < 2; ++n) _Pragma("unroll") for (int k = 0; k < 2; ++k) \
;         acc[ai][bj][m][n] = __builtin_amdgcn_mfma_f32_16x16x32_bf16(Bt[n][k], At[m][k], acc[ai][bj][m][n], 0, 0, 0); __builtin_amdgcn_s_setprio(0); } while (0)
; #define PG8_WAIT_V(n) asm volatile("s_waitcnt vmcnt(" #n ")" ::: "memory")
; #define PG8_WAIT_L(n) asm volatile("s_waitcnt lgkmcnt(" #n ")" ::: "memory")
; template <class Epi, class Sched, bool ALIGN_EPI = false, bool SP2 = false>
; __device__ __forceinline__ void gemm_phase(PG8_LAS unsigned char* lds, const Gemm g, const Sched& S, const Epi& E) {
;     ...
;             const bool last = (t == nt - 2);
;             const char* a1 = cA + (size_t)(t + 1) * kstep;
;             const char* a2 = last ? nA : cA + (size_t)(t + 2) * kstep; const char* b2 = last ? nB : cB + (size_t)(t + 2) * kstep;
;             const char* a3 = a2 + kstep; const char* b3 = b2 + kstep;
;             if (last && has_next) S.a_ready(nxt);
;             if constexpr (SP2) {
;             PG8_LDB(B0, 0, 0); PG8_LDB(B1, 0, 1); PG8_SCHED; PG8_LDA(At, 0, 0); PG8_STAGE(PG8_SA(1, 1), a1 + hstep, voffA);
;             PG8_WAIT_V(8); PG8_WAIT_L(0); PG8_BAR; PG8_MMA(0, 0, At, B0); PG8_MMA(0, 1, At, B1); PG8_BAR; PG8_SCHED;
;             PG8_LDA(At, 0, 1); PG8_STAGE(PG8_SB(0, 0), b2, voffB); PG8_STAGE(PG8_SB(0, 1), b2 + hstep, voffB); PG8_STAGE(PG8_SA(0, 0), a2, voffA);
;             PG8_WAIT_V(8); PG8_WAIT_L(0); PG8_BAR; PG8_MMA(1, 0, At, B0); PG8_MMA(1, 1, At, B1); PG8_BAR; PG8_SCHED;
.LBB0_1180:
	ds_read_b128 v[128:131], v181
	ds_read_b128 v[132:135], v181 offset:1024
	ds_read_b128 v[136:139], v181 offset:2048
	ds_read_b128 v[140:143], v181 offset:3072
	ds_read_b128 v[144:147], v182
	ds_read_b128 v[148:151], v182 offset:1024
	ds_read_b128 v[168:171], v182 offset:2048
	ds_read_b128 v[172:175], v182 offset:3072
	s_add_u32 s28, s26, 0xfff80080
	s_addc_u32 s29, s27, -1
	s_cmp_eq_u32 s49, 28
	s_cselect_b32 s31, s7, s29
	s_cselect_b32 s30, s21, s28
	s_cselect_b32 s29, s19, s48
	s_cselect_b32 s28, s46, s47
	v_lshl_add_u64 v[176:177], s[26:27], 0, v[160:161]
	s_add_i32 m0, s35, 0xc000
	ds_read_b128 v[186:189], v183
	ds_read_b128 v[190:193], v183 offset:1024
	ds_read_b128 v[198:201], v183 offset:2048
	ds_read_b128 v[202:205], v183 offset:3072
	ds_read_b128 v[206:209], v183 offset:4096
	ds_read_b128 v[210:213], v183 offset:5120
	ds_read_b128 v[214:217], v183 offset:6144
	ds_read_b128 v[218:221], v183 offset:7168
	global_load_lds_dwordx4 v[176:177], off
	v_lshl_add_u64 v[176:177], s[26:27], 0, v[162:163]
	s_add_i32 m0, s35, 0xe000
	s_nop 0
	global_load_lds_dwordx4 v[176:177], off
	s_waitcnt vmcnt(8)
	s_waitcnt lgkmcnt(0)
	s_setprio 1
	s_barrier
	v_mfma_f32_16x16x32_bf16 v[124:127], v[128:131], v[186:189], v[124:127]
	v_mfma_f32_16x16x32_bf16 v[120:123], v[136:139], v[186:189], v[120:123]
	v_mfma_f32_16x16x32_bf16 v[104:107], v[128:131], v[198:201], v[104:107]
	v_mfma_f32_16x16x32_bf16 v[108:111], v[136:139], v[198:201], v[108:111]
	v_mfma_f32_16x16x32_bf16 v[88:91], v[128:131], v[206:209], v[88:91]
	v_mfma_f32_16x16x32_bf16 v[92:95], v[136:139], v[206:209], v[92:95]
	v_mfma_f32_16x16x32_bf16 v[72:75], v[128:131], v[214:217], v[72:75]
	v_mfma_f32_16x16x32_bf16 v[76:79], v[136:139], v[214:217], v[76:79]
	v_mfma_f32_16x16x32_bf16 v[124:127], v[132:135], v[190:193], v[124:127]
	v_mfma_f32_16x16x32_bf16 v[120:123], v[140:143], v[190:193], v[120:123]
	v_mfma_f32_16x16x32_bf16 v[104:107], v[132:135], v[202:205], v[104:107]
	v_mfma_f32_16x16x32_bf16 v[108:111], v[140:143], v[202:205], v[108:111]
	v_mfma_f32_16x16x32_bf16 v[88:91], v[132:135], v[210:213], v[88:91]
	v_mfma_f32_16x16x32_bf16 v[92:95], v[140:143], v[210:213], v[92:95]
	v_mfma_f32_16x16x32_bf16 v[72:75], v[132:135], v[218:221], v[72:75]
	v_mfma_f32_16x16x32_bf16 v[76:79], v[140:143], v[218:221], v[76:79]
	v_mfma_f32_16x16x32_bf16 v[116:119], v[144:147], v[186:189], v[116:119]
	v_mfma_f32_16x16x32_bf16 v[112:115], v[168:171], v[186:189], v[112:115]
	v_mfma_f32_16x16x32_bf16 v[100:103], v[144:147], v[198:201], v[100:103]
	v_mfma_f32_16x16x32_bf16 v[96:99], v[168:171], v[198:201], v[96:99]
	v_mfma_f32_16x16x32_bf16 v[84:87], v[144:147], v[206:209], v[84:87]
	v_mfma_f32_16x16x32_bf16 v[80:83], v[168:171], v[206:209], v[80:83]
	v_mfma_f32_16x16x32_bf16 v[68:71], v[144:147], v[214:217], v[68:71]
	v_mfma_f32_16x16x32_bf16 v[64:67], v[168:171], v[214:217], v[64:67]
	v_mfma_f32_16x16x32_bf16 v[116:119], v[148:151], v[190:193], v[116:119]
	v_mfma_f32_16x16x32_bf16 v[112:115], v[172:175], v[190:193], v[112:115]
	v_mfma_f32_16x16x32_bf16 v[100:103], v[148:151], v[202:205], v[100:103]
	v_mfma_f32_16x16x32_bf16 v[96:99], v[172:175], v[202:205], v[96:99]
	v_mfma_f32_16x16x32_bf16 v[84:87], v[148:151], v[210:213], v[84:87]
	v_mfma_f32_16x16x32_bf16 v[80:83], v[172:175], v[210:213], v[80:83]
	v_mfma_f32_16x16x32_bf16 v[68:71], v[148:151], v[218:221], v[68:71]
	v_mfma_f32_16x16x32_bf16 v[64:67], v[172:175], v[218:221], v[64:67]
	s_barrier
	s_setprio 0
	s_add_i32 s50, s43, s34
	v_lshl_add_u64 v[176:177], s[28:29], 0, v[154:155]
	s_mov_b32 m0, s50
	ds_read_b128 v[186:189], v183 offset:16384
	ds_read_b128 v[190:193], v183 offset:17408
	ds_read_b128 v[198:201], v183 offset:18432
	ds_read_b128 v[202:205], v183 offset:19456
	ds_read_b128 v[206:209], v183 offset:20480
	ds_read_b128 v[210:213], v183 offset:21504
	ds_read_b128 v[214:217], v183 offset:22528
	ds_read_b128 v[218:221], v183 offset:23552
	global_load_lds_dwordx4 v[176:177], off
	s_add_i32 m0, s50, 0x2000
	s_add_u32 s50, s28, 0x80000
	v_lshl_add_u64 v[194:195], s[28:29], 0, v[158:159]
	s_addc_u32 s51, s29, 0
	s_add_i32 s52, s44, s34
	global_load_lds_dwordx4 v[194:195], off
	v_lshl_add_u64 v[222:223], s[50:51], 0, v[154:155]
	s_mov_b32 m0, s52
	v_lshl_add_u64 v[224:225], s[30:31], 0, v[156:157]
	global_load_lds_dwordx4 v[222:223], off
	v_lshl_add_u64 v[222:223], s[50:51], 0, v[158:159]
	s_add_i32 m0, s52, 0x2000
	s_nop 0
	global_load_lds_dwordx4 v[222:223], off
	v_lshl_add_u64 v[222:223], s[30:31], 0, v[152:153]
	s_mov_b32 m0, s35
	s_nop 0
	global_load_lds_dwordx4 v[222:223], off
	s_mov_b32 m0, s33
	s_nop 0
	global_load_lds_dwordx4 v[224:225], off
	s_waitcnt vmcnt(8)
	s_waitcnt lgkmcnt(0)
	s_setprio 1
	s_barrier
; #define PG8_STAGE(bufoff, gbase, voff) do { _Pragma("unroll") for (int _i = 0; _i < 2; ++_i) \
;         __builtin_amdgcn_global_load_lds((const unsigned*)((const char*)(gbase) + (voff)[_i]), (PG8_LAS unsigned*)(lds + (bufoff) + ldsw + _i * 8192), 16, 0, 0); } while (0)
; #define PG8_LDA(dst, b, h) do { _Pragma("unroll") for (int m = 0; m < 4; ++m) _Pragma("unroll") for (int k = 0; k < 2; ++k) dst[m][k] = *(const PG8_LAS bf16x8*)(lds + PG8_SA(b, h) + aoff + m * 2048 + k * 1024); } while (0)
; #define PG8_LDB(dst, b, h) do { _Pragma("unroll") for (int n = 0; n < 2; ++n) _Pragma("unroll") for (int k = 0; k < 2; ++k) dst[n][k] = *(const PG8_LAS bf16x8*)(lds + PG8_SB(b, h) + boff + n * 2048 + k * 1024); } while (0)
; #define PG8_MMA(ai, bj, At, Bt) do { __builtin_amdgcn_s_setprio(1); _Pragma("unroll") for (int m = 0; m < 4; ++m) _Pragma("unroll") for (int n = 0; n < 2; ++n) _Pragma("unroll") for (int k = 0; k < 2; ++k) \
;         acc[ai][bj][m][n] = __builtin_amdgcn_mfma_f32_16x16x32_bf16(Bt[n][k], At[m][k], acc[ai][bj][m][n], 0, 0, 0); __builtin_amdgcn_s_setprio(0); } while (0)
; #define PG8_WAIT_V(n) asm volatile("s_waitcnt vmcnt(" #n ")" ::: "memory")
; #define PG8_WAIT_L(n) asm volatile("s_waitcnt lgkmcnt(" #n ")" ::: "memory")
; #define PG8_BAR __builtin_amdgcn_s_barrier()
; #define PG8_SCHED __builtin_amdgcn_sched_barrier(0)
; template <class Epi, class Sched, bool ALIGN_EPI = false, bool SP2 = false>
; __device__ __forceinline__ void gemm_phase(PG8_LAS unsigned char* lds, const Gemm g, const Sched& S, const Epi& E) {
;     ...
;             PG8_WAIT_V(8); PG8_WAIT_L(0); PG8_BAR; PG8_MMA(1, 0, At, B0); PG8_MMA(1, 1, At, B1); PG8_BAR; PG8_SCHED;
;             PG8_LDB(B0, 1, 0); PG8_LDB(B1, 1, 1); PG8_SCHED; PG8_LDA(At, 1, 0); PG8_STAGE(PG8_SA(0, 1), a2 + hstep, voffA);
;             PG8_WAIT_V(8); PG8_WAIT_L(0); PG8_BAR; PG8_MMA(0, 0, At, B0); PG8_MMA(0, 1, At, B1); PG8_BAR; PG8_SCHED;
	v_mfma_f32_16x16x32_bf16 v[56:59], v[128:131], v[186:189], v[56:59]
	v_mfma_f32_16x16x32_bf16 v[60:63], v[136:139], v[186:189], v[60:63]
	v_mfma_f32_16x16x32_bf16 v[40:43], v[128:131], v[198:201], v[40:43]
	v_mfma_f32_16x16x32_bf16 v[44:47], v[136:139], v[198:201], v[44:47]
	v_mfma_f32_16x16x32_bf16 v[24:27], v[128:131], v[206:209], v[24:27]
	v_mfma_f32_16x16x32_bf16 v[28:31], v[136:139], v[206:209], v[28:31]
	v_mfma_f32_16x16x32_bf16 v[8:11], v[128:131], v[214:217], v[8:11]
	v_mfma_f32_16x16x32_bf16 v[12:15], v[136:139], v[214:217], v[12:15]
	v_mfma_f32_16x16x32_bf16 v[56:59], v[132:135], v[190:193], v[56:59]
	v_mfma_f32_16x16x32_bf16 v[60:63], v[140:143], v[190:193], v[60:63]
	v_mfma_f32_16x16x32_bf16 v[40:43], v[132:135], v[202:205], v[40:43]
	v_mfma_f32_16x16x32_bf16 v[44:47], v[140:143], v[202:205], v[44:47]
	v_mfma_f32_16x16x32_bf16 v[24:27], v[132:135], v[210:213], v[24:27]
	v_mfma_f32_16x16x32_bf16 v[28:31], v[140:143], v[210:213], v[28:31]
	v_mfma_f32_16x16x32_bf16 v[8:11], v[132:135], v[218:221], v[8:11]
	v_mfma_f32_16x16x32_bf16 v[12:15], v[140:143], v[218:221], v[12:15]
	v_mfma_f32_16x16x32_bf16 v[52:55], v[144:147], v[186:189], v[52:55]
	v_mfma_f32_16x16x32_bf16 v[48:51], v[168:171], v[186:189], v[48:51]
	v_mfma_f32_16x16x32_bf16 v[36:39], v[144:147], v[198:201], v[36:39]
	v_mfma_f32_16x16x32_bf16 v[32:35], v[168:171], v[198:201], v[32:35]
	v_mfma_f32_16x16x32_bf16 v[20:23], v[144:147], v[206:209], v[20:23]
	v_mfma_f32_16x16x32_bf16 v[16:19], v[168:171], v[206:209], v[16:19]
	v_mfma_f32_16x16x32_bf16 v[4:7], v[144:147], v[214:217], v[4:7]
	v_mfma_f32_16x16x32_bf16 v[0:3], v[168:171], v[214:217], v[0:3]
	v_mfma_f32_16x16x32_bf16 v[52:55], v[148:151], v[190:193], v[52:55]
	v_mfma_f32_16x16x32_bf16 v[48:51], v[172:175], v[190:193], v[48:51]
	v_mfma_f32_16x16x32_bf16 v[36:39], v[148:151], v[202:205], v[36:39]
	v_mfma_f32_16x16x32_bf16 v[32:35], v[172:175], v[202:205], v[32:35]
	v_mfma_f32_16x16x32_bf16 v[20:23], v[148:151], v[210:213], v[20:23]
	v_mfma_f32_16x16x32_bf16 v[16:19], v[172:175], v[210:213], v[16:19]
	v_mfma_f32_16x16x32_bf16 v[4:7], v[148:151], v[218:221], v[4:7]
	v_mfma_f32_16x16x32_bf16 v[0:3], v[172:175], v[218:221], v[0:3]
	s_barrier
	s_setprio 0
	s_add_i32 s50, 0, 0x18000
	s_add_i32 s51, 0, 0x1c000
	v_add_u32_e32 v140, s50, v179
	v_add_u32_e32 v172, s51, v179
	ds_read_b128 v[128:131], v140
	ds_read_b128 v[132:135], v140 offset:1024
	ds_read_b128 v[136:139], v140 offset:2048
	ds_read_b128 v[140:143], v140 offset:3072
	ds_read_b128 v[144:147], v172
	ds_read_b128 v[148:151], v172 offset:1024
	ds_read_b128 v[168:171], v172 offset:2048
	ds_read_b128 v[172:175], v172 offset:3072
	s_add_u32 s30, s30, 0x80000
	s_addc_u32 s31, s31, 0
	s_mov_b32 m0, s36
	v_lshl_add_u64 v[226:227], s[30:31], 0, v[152:153]
	ds_read_b128 v[186:189], v183 offset:32768
	ds_read_b128 v[190:193], v183 offset:33792
	ds_read_b128 v[198:201], v183 offset:34816
	ds_read_b128 v[202:205], v183 offset:35840
	ds_read_b128 v[206:209], v183 offset:36864
	ds_read_b128 v[210:213], v183 offset:37888
	ds_read_b128 v[214:217], v183 offset:38912
	ds_read_b128 v[218:221], v183 offset:39936
	global_load_lds_dwordx4 v[226:227], off
	v_lshl_add_u64 v[226:227], s[30:31], 0, v[156:157]
	s_mov_b32 m0, s37
	s_nop 0
	global_load_lds_dwordx4 v[226:227], off
	s_waitcnt vmcnt(8)
	s_waitcnt lgkmcnt(0)
	s_setprio 1
	s_barrier
	v_mfma_f32_16x16x32_bf16 v[124:127], v[128:131], v[186:189], v[124:127]
	v_mfma_f32_16x16x32_bf16 v[120:123], v[136:139], v[186:189], v[120:123]
	v_mfma_f32_16x16x32_bf16 v[104:107], v[128:131], v[198:201], v[104:107]
	v_mfma_f32_16x16x32_bf16 v[108:111], v[136:139], v[198:201], v[108:111]
	v_mfma_f32_16x16x32_bf16 v[88:91], v[128:131], v[206:209], v[88:91]
	v_mfma_f32_16x16x32_bf16 v[92:95], v[136:139], v[206:209], v[92:95]
	v_mfma_f32_16x16x32_bf16 v[72:75], v[128:131], v[214:217], v[72:75]
	v_mfma_f32_16x16x32_bf16 v[76:79], v[136:139], v[214:217], v[76:79]
	v_mfma_f32_16x16x32_bf16 v[124:127], v[132:135], v[190:193], v[124:127]
	v_mfma_f32_16x16x32_bf16 v[120:123], v[140:143], v[190:193], v[120:123]
	v_mfma_f32_16x16x32_bf16 v[104:107], v[132:135], v[202:205], v[104:107]
	v_mfma_f32_16x16x32_bf16 v[108:111], v[140:143], v[202:205], v[108:111]
	v_mfma_f32_16x16x32_bf16 v[88:91], v[132:135], v[210:213], v[88:91]
	v_mfma_f32_16x16x32_bf16 v[92:95], v[140:143], v[210:213], v[92:95]
	v_mfma_f32_16x16x32_bf16 v[72:75], v[132:135], v[218:221], v[72:75]
	v_mfma_f32_16x16x32_bf16 v[76:79], v[140:143], v[218:221], v[76:79]
	v_mfma_f32_16x16x32_bf16 v[116:119], v[144:147], v[186:189], v[116:119]
	v_mfma_f32_16x16x32_bf16 v[112:115], v[168:171], v[186:189], v[112:115]
	v_mfma_f32_16x16x32_bf16 v[100:103], v[144:147], v[198:201], v[100:103]
	v_mfma_f32_16x16x32_bf16 v[96:99], v[168:171], v[198:201], v[96:99]
	v_mfma_f32_16x16x32_bf16 v[84:87], v[144:147], v[206:209], v[84:87]
	v_mfma_f32_16x16x32_bf16 v[80:83], v[168:171], v[206:209], v[80:83]
	v_mfma_f32_16x16x32_bf16 v[68:71], v[144:147], v[214:217], v[68:71]
	v_mfma_f32_16x16x32_bf16 v[64:67], v[168:171], v[214:217], v[64:67]
	v_mfma_f32_16x16x32_bf16 v[116:119], v[148:151], v[190:193], v[116:119]
	v_mfma_f32_16x16x32_bf16 v[112:115], v[172:175], v[190:193], v[112:115]
	v_mfma_f32_16x16x32_bf16 v[100:103], v[148:151], v[202:205], v[100:103]
	v_mfma_f32_16x16x32_bf16 v[96:99], v[172:175], v[202:205], v[96:99]
	v_mfma_f32_16x16x32_bf16 v[84:87], v[148:151], v[210:213], v[84:87]
	v_mfma_f32_16x16x32_bf16 v[80:83], v[172:175], v[210:213], v[80:83]
	v_mfma_f32_16x16x32_bf16 v[68:71], v[148:151], v[218:221], v[68:71]
	v_mfma_f32_16x16x32_bf16 v[64:67], v[172:175], v[218:221], v[64:67]
	s_barrier
; #define PG8_STAGE(bufoff, gbase, voff) do { _Pragma("unroll") for (int _i = 0; _i < 2; ++_i) \
;         __builtin_amdgcn_global_load_lds((const unsigned*)((const char*)(gbase) + (voff)[_i]), (PG8_LAS unsigned*)(lds + (bufoff) + ldsw + _i * 8192), 16, 0, 0); } while (0)
; #define PG8_LDA(dst, b, h) do { _Pragma("unroll") for (int m = 0; m < 4; ++m) _Pragma("unroll") for (int k = 0; k < 2; ++k) dst[m][k] = *(const PG8_LAS bf16x8*)(lds + PG8_SA(b, h) + aoff + m * 2048 + k * 1024); } while (0)
; #define PG8_MMA(ai, bj, At, Bt) do { __builtin_amdgcn_s_setprio(1); _Pragma("unroll") for (int m = 0; m < 4; ++m) _Pragma("unroll") for (int n = 0; n < 2; ++n) _Pragma("unroll") for (int k = 0; k < 2; ++k) \
;         acc[ai][bj][m][n] = __builtin_amdgcn_mfma_f32_16x16x32_bf16(Bt[n][k], At[m][k], acc[ai][bj][m][n], 0, 0, 0); __builtin_amdgcn_s_setprio(0); } while (0)
; #define PG8_WAIT_V(n) asm volatile("s_waitcnt vmcnt(" #n ")" ::: "memory")
; #define PG8_WAIT_L(n) asm volatile("s_waitcnt lgkmcnt(" #n ")" ::: "memory")
; #define PG8_BAR __builtin_amdgcn_s_barrier()
; #define PG8_SCHED __builtin_amdgcn_sched_barrier(0)
; template <class Epi, class Sched, bool ALIGN_EPI = false, bool SP2 = false>
; __device__ __forceinline__ void gemm_phase(PG8_LAS unsigned char* lds, const Gemm g, const Sched& S, const Epi& E) {
;     ...
;             PG8_WAIT_V(8); PG8_WAIT_L(0); PG8_BAR; PG8_MMA(0, 0, At, B0); PG8_MMA(0, 1, At, B1); PG8_BAR; PG8_SCHED;
;             PG8_LDA(At, 1, 1); PG8_STAGE(PG8_SB(1, 0), b3, voffB); PG8_STAGE(PG8_SB(1, 1), b3 + hstep, voffB); PG8_STAGE(PG8_SA(1, 0), a3, voffA);
;             PG8_WAIT_V(8); PG8_WAIT_L(0); PG8_BAR; PG8_MMA(1, 0, At, B0); PG8_MMA(1, 1, At, B1); PG8_BAR; PG8_SCHED;
;     ...
;         if constexpr (ALIGN_EPI) { if (wr == 0) PG8_BAR; }
	s_setprio 0
	s_add_i32 s30, s50, s34
	v_lshl_add_u64 v[176:177], v[176:177], 0, s[12:13]
	s_mov_b32 m0, s30
	ds_read_b128 v[186:189], v183 offset:49152
	ds_read_b128 v[190:193], v183 offset:50176
	ds_read_b128 v[198:201], v183 offset:51200
	ds_read_b128 v[202:205], v183 offset:52224
	ds_read_b128 v[206:209], v183 offset:53248
	ds_read_b128 v[210:213], v183 offset:54272
	ds_read_b128 v[214:217], v183 offset:55296
	ds_read_b128 v[218:221], v183 offset:56320
	global_load_lds_dwordx4 v[176:177], off
	s_add_i32 m0, s30, 0x2000
	s_add_u32 s28, s28, 0x80080
	v_lshl_add_u64 v[176:177], v[194:195], 0, s[12:13]
	s_addc_u32 s29, s29, 0
	s_add_i32 s30, s51, s34
	global_load_lds_dwordx4 v[176:177], off
	v_lshl_add_u64 v[176:177], s[28:29], 0, v[154:155]
	s_mov_b32 m0, s30
	s_nop 0
	global_load_lds_dwordx4 v[176:177], off
	v_lshl_add_u64 v[176:177], s[28:29], 0, v[158:159]
	s_add_i32 m0, s30, 0x2000
	s_nop 0
	global_load_lds_dwordx4 v[176:177], off
	v_lshl_add_u64 v[176:177], v[222:223], 0, s[12:13]
	s_mov_b32 m0, s39
	s_nop 0
	global_load_lds_dwordx4 v[176:177], off
	v_lshl_add_u64 v[176:177], v[224:225], 0, s[12:13]
	s_mov_b32 m0, s40
	s_nop 0
	global_load_lds_dwordx4 v[176:177], off
	s_waitcnt vmcnt(8)
	s_waitcnt lgkmcnt(0)
	s_setprio 1
	s_barrier
	v_mfma_f32_16x16x32_bf16 v[56:59], v[128:131], v[186:189], v[56:59]
	v_mfma_f32_16x16x32_bf16 v[60:63], v[136:139], v[186:189], v[60:63]
	v_mfma_f32_16x16x32_bf16 v[40:43], v[128:131], v[198:201], v[40:43]
	v_mfma_f32_16x16x32_bf16 v[44:47], v[136:139], v[198:201], v[44:47]
	v_mfma_f32_16x16x32_bf16 v[24:27], v[128:131], v[206:209], v[24:27]
	v_mfma_f32_16x16x32_bf16 v[28:31], v[136:139], v[206:209], v[28:31]
	v_mfma_f32_16x16x32_bf16 v[8:11], v[128:131], v[214:217], v[8:11]
	v_mfma_f32_16x16x32_bf16 v[12:15], v[136:139], v[214:217], v[12:15]
	v_mfma_f32_16x16x32_bf16 v[56:59], v[132:135], v[190:193], v[56:59]
	v_mfma_f32_16x16x32_bf16 v[60:63], v[140:143], v[190:193], v[60:63]
	v_mfma_f32_16x16x32_bf16 v[40:43], v[132:135], v[202:205], v[40:43]
	v_mfma_f32_16x16x32_bf16 v[44:47], v[140:143], v[202:205], v[44:47]
	v_mfma_f32_16x16x32_bf16 v[24:27], v[132:135], v[210:213], v[24:27]
	v_mfma_f32_16x16x32_bf16 v[28:31], v[140:143], v[210:213], v[28:31]
	v_mfma_f32_16x16x32_bf16 v[8:11], v[132:135], v[218:221], v[8:11]
	v_mfma_f32_16x16x32_bf16 v[12:15], v[140:143], v[218:221], v[12:15]
	v_mfma_f32_16x16x32_bf16 v[52:55], v[144:147], v[186:189], v[52:55]
	v_mfma_f32_16x16x32_bf16 v[48:51], v[168:171], v[186:189], v[48:51]
	v_mfma_f32_16x16x32_bf16 v[36:39], v[144:147], v[198:201], v[36:39]
	v_mfma_f32_16x16x32_bf16 v[32:35], v[168:171], v[198:201], v[32:35]
	v_mfma_f32_16x16x32_bf16 v[20:23], v[144:147], v[206:209], v[20:23]
	v_mfma_f32_16x16x32_bf16 v[16:19], v[168:171], v[206:209], v[16:19]
	v_mfma_f32_16x16x32_bf16 v[4:7], v[144:147], v[214:217], v[4:7]
	v_mfma_f32_16x16x32_bf16 v[0:3], v[168:171], v[214:217], v[0:3]
	v_mfma_f32_16x16x32_bf16 v[52:55], v[148:151], v[190:193], v[52:55]
	v_mfma_f32_16x16x32_bf16 v[48:51], v[172:175], v[190:193], v[48:51]
	v_mfma_f32_16x16x32_bf16 v[36:39], v[148:151], v[202:205], v[36:39]
	v_mfma_f32_16x16x32_bf16 v[32:35], v[172:175], v[202:205], v[32:35]
	v_mfma_f32_16x16x32_bf16 v[20:23], v[148:151], v[210:213], v[20:23]
	v_mfma_f32_16x16x32_bf16 v[16:19], v[172:175], v[210:213], v[16:19]
	v_mfma_f32_16x16x32_bf16 v[4:7], v[148:151], v[218:221], v[4:7]
	v_mfma_f32_16x16x32_bf16 v[0:3], v[172:175], v[218:221], v[0:3]
	s_barrier
	s_setprio 0
	s_add_i32 s49, s49, 2
	s_add_u32 s26, s26, 0x100
	s_addc_u32 s27, s27, 0
	s_add_u32 s47, s47, 0x100
	s_addc_u32 s48, s48, 0
	s_cmp_gt_u32 s49, 29
	s_cbranch_scc0 .LBB0_1180
	s_and_b64 vcc, exec, s[14:15]
	s_cbranch_vccz .LBB0_1183
	s_barrier

; #define PG8_STAGE(bufoff, gbase, voff) do { _Pragma("unroll") for (int _i = 0; _i < 2; ++_i) \
;         __builtin_amdgcn_global_load_lds((const unsigned*)((const char*)(gbase) + (voff)[_i]), (PG8_LAS unsigned*)(lds + (bufoff) + ldsw + _i * 8192), 16, 0, 0); } while (0)
; #define PG8_LDA(dst, b, h) do { _Pragma("unroll") for (int m = 0; m < 4; ++m) _Pragma("unroll") for (int k = 0; k < 2; ++k) dst[m][k] = *(const PG8_LAS bf16x8*)(lds + PG8_SA(b, h) + aoff + m * 2048 + k * 1024); } while (0)
; #define PG8_LDB(dst, b, h) do { _Pragma("unroll") for (int n = 0; n < 2; ++n) _Pragma("unroll") for (int k = 0; k < 2; ++k) dst[n][k] = *(const PG8_LAS bf16x8*)(lds + PG8_SB(b, h) + boff + n * 2048 + k * 1024); } while (0)
; #define PG8_MMA(ai, bj, At, Bt) do { __builtin_amdgcn_s_setprio(1); _Pragma("unroll") for (int m = 0; m < 4; ++m) _Pragma("unroll") for (int n = 0; n < 2; ++n) _Pragma("unroll") for (int k = 0; k < 2; ++k) \
;         acc[ai][bj][m][n] = __builtin_amdgcn_mfma_f32_16x16x32_bf16(Bt[n][k], At[m][k], acc[ai][bj][m][n], 0, 0, 0); __builtin_amdgcn_s_setprio(0); } while (0)
; #define PG8_WAIT_V(n) asm volatile("s_waitcnt vmcnt(" #n ")" ::: "memory")
; #define PG8_WAIT_L(n) asm volatile("s_waitcnt lgkmcnt(" #n ")" ::: "memory")
; template <class Epi, class Sched, bool ALIGN_EPI = false, bool SP2 = false>
; __device__ __forceinline__ void gemm_phase(PG8_LAS unsigned char* lds, const Gemm g, const Sched& S, const Epi& E) {
;     ...
;             const bool last = (t == nt - 2);
;             const char* a1 = cA + (size_t)(t + 1) * kstep;
;             const char* a2 = last ? nA : cA + (size_t)(t + 2) * kstep; const char* b2 = last ? nB : cB + (size_t)(t + 2) * kstep;
;             const char* a3 = a2 + kstep; const char* b3 = b2 + kstep;
;             if (last && has_next) S.a_ready(nxt);
;             if constexpr (SP2) {
;             PG8_LDB(B0, 0, 0); PG8_LDB(B1, 0, 1); PG8_SCHED; PG8_LDA(At, 0, 0); PG8_STAGE(PG8_SA(1, 1), a1 + hstep, voffA);
;             PG8_WAIT_V(8); PG8_WAIT_L(0); PG8_BAR; PG8_MMA(0, 0, At, B0); PG8_MMA(0, 1, At, B1); PG8_BAR; PG8_SCHED;
;             PG8_LDA(At, 0, 1); PG8_STAGE(PG8_SB(0, 0), b2, voffB); PG8_STAGE(PG8_SB(0, 1), b2 + hstep, voffB); PG8_STAGE(PG8_SA(0, 0), a2, voffA);
;             PG8_WAIT_V(8); PG8_WAIT_L(0); PG8_BAR; PG8_MMA(1, 0, At, B0); PG8_MMA(1, 1, At, B1); PG8_BAR; PG8_SCHED;
.LBB0_1373:
	ds_read_b128 v[108:111], v173
	ds_read_b128 v[112:115], v173 offset:1024
	ds_read_b128 v[116:119], v173 offset:2048
	ds_read_b128 v[120:123], v173 offset:3072
	ds_read_b128 v[178:181], v175
	ds_read_b128 v[182:185], v175 offset:1024
	ds_read_b128 v[186:189], v175 offset:2048
	ds_read_b128 v[190:193], v175 offset:3072
	s_add_u32 s42, s8, 0xfff80080
	s_addc_u32 s43, s9, -1
	s_cmp_eq_u32 s66, 28
	s_cselect_b32 s45, s29, s43
	s_cselect_b32 s44, s39, s42
	s_cselect_b32 s43, s27, s49
	s_cselect_b32 s42, s41, s48
	v_lshl_add_u64 v[160:161], s[8:9], 0, v[154:155]
	s_add_i32 m0, s50, 0xc000
	ds_read_b128 v[198:201], v177
	ds_read_b128 v[202:205], v177 offset:1024
	ds_read_b128 v[206:209], v177 offset:2048
	ds_read_b128 v[210:213], v177 offset:3072
	ds_read_b128 v[214:217], v177 offset:4096
	ds_read_b128 v[218:221], v177 offset:5120
	ds_read_b128 v[222:225], v177 offset:6144
	ds_read_b128 v[226:229], v177 offset:7168
	global_load_lds_dwordx4 v[160:161], off
	v_lshl_add_u64 v[160:161], s[8:9], 0, v[156:157]
	s_add_i32 m0, s50, 0xe000
	s_nop 0
	global_load_lds_dwordx4 v[160:161], off
	s_waitcnt vmcnt(8)
	s_waitcnt lgkmcnt(0)
	s_setprio 1
	s_barrier
	v_mfma_f32_16x16x32_bf16 v[140:143], v[108:111], v[198:201], v[140:143]
	v_mfma_f32_16x16x32_bf16 v[136:139], v[116:119], v[198:201], v[136:139]
	v_mfma_f32_16x16x32_bf16 v[100:103], v[108:111], v[206:209], v[100:103]
	v_mfma_f32_16x16x32_bf16 v[124:127], v[116:119], v[206:209], v[124:127]
	v_mfma_f32_16x16x32_bf16 v[84:87], v[108:111], v[214:217], v[84:87]
	v_mfma_f32_16x16x32_bf16 v[92:95], v[116:119], v[214:217], v[92:95]
	v_mfma_f32_16x16x32_bf16 v[68:71], v[108:111], v[222:225], v[68:71]
	v_mfma_f32_16x16x32_bf16 v[76:79], v[116:119], v[222:225], v[76:79]
	v_mfma_f32_16x16x32_bf16 v[140:143], v[112:115], v[202:205], v[140:143]
	v_mfma_f32_16x16x32_bf16 v[136:139], v[120:123], v[202:205], v[136:139]
	v_mfma_f32_16x16x32_bf16 v[100:103], v[112:115], v[210:213], v[100:103]
	v_mfma_f32_16x16x32_bf16 v[124:127], v[120:123], v[210:213], v[124:127]
	v_mfma_f32_16x16x32_bf16 v[84:87], v[112:115], v[218:221], v[84:87]
	v_mfma_f32_16x16x32_bf16 v[92:95], v[120:123], v[218:221], v[92:95]
	v_mfma_f32_16x16x32_bf16 v[68:71], v[112:115], v[226:229], v[68:71]
	v_mfma_f32_16x16x32_bf16 v[76:79], v[120:123], v[226:229], v[76:79]
	v_mfma_f32_16x16x32_bf16 v[128:131], v[178:181], v[198:201], v[128:131]
	v_mfma_f32_16x16x32_bf16 v[132:135], v[186:189], v[198:201], v[132:135]
	v_mfma_f32_16x16x32_bf16 v[104:107], v[178:181], v[206:209], v[104:107]
	v_mfma_f32_16x16x32_bf16 v[96:99], v[186:189], v[206:209], v[96:99]
	v_mfma_f32_16x16x32_bf16 v[88:91], v[178:181], v[214:217], v[88:91]
	v_mfma_f32_16x16x32_bf16 v[80:83], v[186:189], v[214:217], v[80:83]
	v_mfma_f32_16x16x32_bf16 v[72:75], v[178:181], v[222:225], v[72:75]
	v_mfma_f32_16x16x32_bf16 v[64:67], v[186:189], v[222:225], v[64:67]
	v_mfma_f32_16x16x32_bf16 v[128:131], v[182:185], v[202:205], v[128:131]
	v_mfma_f32_16x16x32_bf16 v[132:135], v[190:193], v[202:205], v[132:135]
	v_mfma_f32_16x16x32_bf16 v[104:107], v[182:185], v[210:213], v[104:107]
	v_mfma_f32_16x16x32_bf16 v[96:99], v[190:193], v[210:213], v[96:99]
	v_mfma_f32_16x16x32_bf16 v[88:91], v[182:185], v[218:221], v[88:91]
	v_mfma_f32_16x16x32_bf16 v[80:83], v[190:193], v[218:221], v[80:83]
	v_mfma_f32_16x16x32_bf16 v[72:75], v[182:185], v[226:229], v[72:75]
	v_mfma_f32_16x16x32_bf16 v[64:67], v[190:193], v[226:229], v[64:67]
	s_barrier
	s_setprio 0
	s_add_i32 s67, s62, s47
	v_lshl_add_u64 v[160:161], s[42:43], 0, v[144:145]
	s_mov_b32 m0, s67
	ds_read_b128 v[198:201], v177 offset:16384
	ds_read_b128 v[202:205], v177 offset:17408
	ds_read_b128 v[206:209], v177 offset:18432
	ds_read_b128 v[210:213], v177 offset:19456
	ds_read_b128 v[214:217], v177 offset:20480
	ds_read_b128 v[218:221], v177 offset:21504
	ds_read_b128 v[222:225], v177 offset:22528
	ds_read_b128 v[226:229], v177 offset:23552
	global_load_lds_dwordx4 v[160:161], off
	s_add_i32 m0, s67, 0x2000
	s_add_u32 s68, s42, 0x80000
	v_lshl_add_u64 v[164:165], s[42:43], 0, v[146:147]
	s_addc_u32 s69, s43, 0
	s_add_i32 s67, s63, s47
	global_load_lds_dwordx4 v[164:165], off
	v_lshl_add_u64 v[170:171], s[68:69], 0, v[144:145]
	s_mov_b32 m0, s67
	v_lshl_add_u64 v[194:195], s[44:45], 0, v[146:147]
	global_load_lds_dwordx4 v[170:171], off
	v_lshl_add_u64 v[170:171], s[68:69], 0, v[146:147]
	s_add_i32 m0, s67, 0x2000
	s_nop 0
	global_load_lds_dwordx4 v[170:171], off
	v_lshl_add_u64 v[170:171], s[44:45], 0, v[144:145]
	s_mov_b32 m0, s50
	s_nop 0
	global_load_lds_dwordx4 v[170:171], off
	s_mov_b32 m0, s51
	s_nop 0
	global_load_lds_dwordx4 v[194:195], off
	s_waitcnt vmcnt(8)
	s_waitcnt lgkmcnt(0)
	s_setprio 1
	s_barrier
; #define PG8_STAGE(bufoff, gbase, voff) do { _Pragma("unroll") for (int _i = 0; _i < 2; ++_i) \
;         __builtin_amdgcn_global_load_lds((const unsigned*)((const char*)(gbase) + (voff)[_i]), (PG8_LAS unsigned*)(lds + (bufoff) + ldsw + _i * 8192), 16, 0, 0); } while (0)
; #define PG8_LDA(dst, b, h) do { _Pragma("unroll") for (int m = 0; m < 4; ++m) _Pragma("unroll") for (int k = 0; k < 2; ++k) dst[m][k] = *(const PG8_LAS bf16x8*)(lds + PG8_SA(b, h) + aoff + m * 2048 + k * 1024); } while (0)
; #define PG8_LDB(dst, b, h) do { _Pragma("unroll") for (int n = 0; n < 2; ++n) _Pragma("unroll") for (int k = 0; k < 2; ++k) dst[n][k] = *(const PG8_LAS bf16x8*)(lds + PG8_SB(b, h) + boff + n * 2048 + k * 1024); } while (0)
; #define PG8_MMA(ai, bj, At, Bt) do { __builtin_amdgcn_s_setprio(1); _Pragma("unroll") for (int m = 0; m < 4; ++m) _Pragma("unroll") for (int n = 0; n < 2; ++n) _Pragma("unroll") for (int k = 0; k < 2; ++k) \
;         acc[ai][bj][m][n] = __builtin_amdgcn_mfma_f32_16x16x32_bf16(Bt[n][k], At[m][k], acc[ai][bj][m][n], 0, 0, 0); __builtin_amdgcn_s_setprio(0); } while (0)
; #define PG8_WAIT_V(n) asm volatile("s_waitcnt vmcnt(" #n ")" ::: "memory")
; #define PG8_WAIT_L(n) asm volatile("s_waitcnt lgkmcnt(" #n ")" ::: "memory")
; #define PG8_BAR __builtin_amdgcn_s_barrier()
; #define PG8_SCHED __builtin_amdgcn_sched_barrier(0)
; template <class Epi, class Sched, bool ALIGN_EPI = false, bool SP2 = false>
; __device__ __forceinline__ void gemm_phase(PG8_LAS unsigned char* lds, const Gemm g, const Sched& S, const Epi& E) {
;     ...
;             PG8_WAIT_V(8); PG8_WAIT_L(0); PG8_BAR; PG8_MMA(1, 0, At, B0); PG8_MMA(1, 1, At, B1); PG8_BAR; PG8_SCHED;
;             PG8_LDB(B0, 1, 0); PG8_LDB(B1, 1, 1); PG8_SCHED; PG8_LDA(At, 1, 0); PG8_STAGE(PG8_SA(0, 1), a2 + hstep, voffA);
;             PG8_WAIT_V(8); PG8_WAIT_L(0); PG8_BAR; PG8_MMA(0, 0, At, B0); PG8_MMA(0, 1, At, B1); PG8_BAR; PG8_SCHED;
	v_mfma_f32_16x16x32_bf16 v[60:63], v[108:111], v[198:201], v[60:63]
	v_mfma_f32_16x16x32_bf16 v[56:59], v[116:119], v[198:201], v[56:59]
	v_mfma_f32_16x16x32_bf16 v[36:39], v[108:111], v[206:209], v[36:39]
	v_mfma_f32_16x16x32_bf16 v[44:47], v[116:119], v[206:209], v[44:47]
	v_mfma_f32_16x16x32_bf16 v[20:23], v[108:111], v[214:217], v[20:23]
	v_mfma_f32_16x16x32_bf16 v[28:31], v[116:119], v[214:217], v[28:31]
	v_mfma_f32_16x16x32_bf16 v[4:7], v[108:111], v[222:225], v[4:7]
	v_mfma_f32_16x16x32_bf16 v[12:15], v[116:119], v[222:225], v[12:15]
	v_mfma_f32_16x16x32_bf16 v[60:63], v[112:115], v[202:205], v[60:63]
	v_mfma_f32_16x16x32_bf16 v[56:59], v[120:123], v[202:205], v[56:59]
	v_mfma_f32_16x16x32_bf16 v[36:39], v[112:115], v[210:213], v[36:39]
	v_mfma_f32_16x16x32_bf16 v[44:47], v[120:123], v[210:213], v[44:47]
	v_mfma_f32_16x16x32_bf16 v[20:23], v[112:115], v[218:221], v[20:23]
	v_mfma_f32_16x16x32_bf16 v[28:31], v[120:123], v[218:221], v[28:31]
	v_mfma_f32_16x16x32_bf16 v[4:7], v[112:115], v[226:229], v[4:7]
	v_mfma_f32_16x16x32_bf16 v[12:15], v[120:123], v[226:229], v[12:15]
	v_mfma_f32_16x16x32_bf16 v[48:51], v[178:181], v[198:201], v[48:51]
	v_mfma_f32_16x16x32_bf16 v[52:55], v[186:189], v[198:201], v[52:55]
	v_mfma_f32_16x16x32_bf16 v[40:43], v[178:181], v[206:209], v[40:43]
	v_mfma_f32_16x16x32_bf16 v[32:35], v[186:189], v[206:209], v[32:35]
	v_mfma_f32_16x16x32_bf16 v[24:27], v[178:181], v[214:217], v[24:27]
	v_mfma_f32_16x16x32_bf16 v[16:19], v[186:189], v[214:217], v[16:19]
	v_mfma_f32_16x16x32_bf16 v[8:11], v[178:181], v[222:225], v[8:11]
	v_mfma_f32_16x16x32_bf16 v[0:3], v[186:189], v[222:225], v[0:3]
	v_mfma_f32_16x16x32_bf16 v[48:51], v[182:185], v[202:205], v[48:51]
	v_mfma_f32_16x16x32_bf16 v[52:55], v[190:193], v[202:205], v[52:55]
	v_mfma_f32_16x16x32_bf16 v[40:43], v[182:185], v[210:213], v[40:43]
	v_mfma_f32_16x16x32_bf16 v[32:35], v[190:193], v[210:213], v[32:35]
	v_mfma_f32_16x16x32_bf16 v[24:27], v[182:185], v[218:221], v[24:27]
	v_mfma_f32_16x16x32_bf16 v[16:19], v[190:193], v[218:221], v[16:19]
	v_mfma_f32_16x16x32_bf16 v[8:11], v[182:185], v[226:229], v[8:11]
	v_mfma_f32_16x16x32_bf16 v[0:3], v[190:193], v[226:229], v[0:3]
	s_barrier
	s_setprio 0
	s_add_i32 s67, 0, 0x18000
	s_add_i32 s68, 0, 0x1c000
	v_add_u32_e32 v120, s67, v167
	v_add_u32_e32 v162, s68, v167
	ds_read_b128 v[108:111], v120
	ds_read_b128 v[112:115], v120 offset:1024
	ds_read_b128 v[116:119], v120 offset:2048
	ds_read_b128 v[120:123], v120 offset:3072
	ds_read_b128 v[178:181], v162
	ds_read_b128 v[182:185], v162 offset:1024
	ds_read_b128 v[186:189], v162 offset:2048
	ds_read_b128 v[190:193], v162 offset:3072
	s_add_u32 s44, s44, 0x80000
	s_addc_u32 s45, s45, 0
	s_mov_b32 m0, s52
	v_lshl_add_u64 v[230:231], s[44:45], 0, v[144:145]
	ds_read_b128 v[198:201], v177 offset:32768
	ds_read_b128 v[202:205], v177 offset:33792
	ds_read_b128 v[206:209], v177 offset:34816
	ds_read_b128 v[210:213], v177 offset:35840
	ds_read_b128 v[214:217], v177 offset:36864
	ds_read_b128 v[218:221], v177 offset:37888
	ds_read_b128 v[222:225], v177 offset:38912
	ds_read_b128 v[226:229], v177 offset:39936
	global_load_lds_dwordx4 v[230:231], off
	v_lshl_add_u64 v[230:231], s[44:45], 0, v[146:147]
	s_mov_b32 m0, s53
	s_nop 0
	global_load_lds_dwordx4 v[230:231], off
	s_waitcnt vmcnt(8)
	s_waitcnt lgkmcnt(0)
	s_setprio 1
	s_barrier
	v_mfma_f32_16x16x32_bf16 v[140:143], v[108:111], v[198:201], v[140:143]
	v_mfma_f32_16x16x32_bf16 v[136:139], v[116:119], v[198:201], v[136:139]
	v_mfma_f32_16x16x32_bf16 v[100:103], v[108:111], v[206:209], v[100:103]
	v_mfma_f32_16x16x32_bf16 v[124:127], v[116:119], v[206:209], v[124:127]
	v_mfma_f32_16x16x32_bf16 v[84:87], v[108:111], v[214:217], v[84:87]
	v_mfma_f32_16x16x32_bf16 v[92:95], v[116:119], v[214:217], v[92:95]
	v_mfma_f32_16x16x32_bf16 v[68:71], v[108:111], v[222:225], v[68:71]
	v_mfma_f32_16x16x32_bf16 v[76:79], v[116:119], v[222:225], v[76:79]
	v_mfma_f32_16x16x32_bf16 v[140:143], v[112:115], v[202:205], v[140:143]
	v_mfma_f32_16x16x32_bf16 v[136:139], v[120:123], v[202:205], v[136:139]
	v_mfma_f32_16x16x32_bf16 v[100:103], v[112:115], v[210:213], v[100:103]
	v_mfma_f32_16x16x32_bf16 v[124:127], v[120:123], v[210:213], v[124:127]
	v_mfma_f32_16x16x32_bf16 v[84:87], v[112:115], v[218:221], v[84:87]
	v_mfma_f32_16x16x32_bf16 v[92:95], v[120:123], v[218:221], v[92:95]
	v_mfma_f32_16x16x32_bf16 v[68:71], v[112:115], v[226:229], v[68:71]
	v_mfma_f32_16x16x32_bf16 v[76:79], v[120:123], v[226:229], v[76:79]
	v_mfma_f32_16x16x32_bf16 v[128:131], v[178:181], v[198:201], v[128:131]
	v_mfma_f32_16x16x32_bf16 v[132:135], v[186:189], v[198:201], v[132:135]
	v_mfma_f32_16x16x32_bf16 v[104:107], v[178:181], v[206:209], v[104:107]
	v_mfma_f32_16x16x32_bf16 v[96:99], v[186:189], v[206:209], v[96:99]
	v_mfma_f32_16x16x32_bf16 v[88:91], v[178:181], v[214:217], v[88:91]
	v_mfma_f32_16x16x32_bf16 v[80:83], v[186:189], v[214:217], v[80:83]
	v_mfma_f32_16x16x32_bf16 v[72:75], v[178:181], v[222:225], v[72:75]
	v_mfma_f32_16x16x32_bf16 v[64:67], v[186:189], v[222:225], v[64:67]
	v_mfma_f32_16x16x32_bf16 v[128:131], v[182:185], v[202:205], v[128:131]
	v_mfma_f32_16x16x32_bf16 v[132:135], v[190:193], v[202:205], v[132:135]
	v_mfma_f32_16x16x32_bf16 v[104:107], v[182:185], v[210:213], v[104:107]
	v_mfma_f32_16x16x32_bf16 v[96:99], v[190:193], v[210:213], v[96:99]
	v_mfma_f32_16x16x32_bf16 v[88:91], v[182:185], v[218:221], v[88:91]
	v_mfma_f32_16x16x32_bf16 v[80:83], v[190:193], v[218:221], v[80:83]
	v_mfma_f32_16x16x32_bf16 v[72:75], v[182:185], v[226:229], v[72:75]
	v_mfma_f32_16x16x32_bf16 v[64:67], v[190:193], v[226:229], v[64:67]
	s_barrier
; #define PG8_STAGE(bufoff, gbase, voff) do { _Pragma("unroll") for (int _i = 0; _i < 2; ++_i) \
;         __builtin_amdgcn_global_load_lds((const unsigned*)((const char*)(gbase) + (voff)[_i]), (PG8_LAS unsigned*)(lds + (bufoff) + ldsw + _i * 8192), 16, 0, 0); } while (0)
; #define PG8_LDA(dst, b, h) do { _Pragma("unroll") for (int m = 0; m < 4; ++m) _Pragma("unroll") for (int k = 0; k < 2; ++k) dst[m][k] = *(const PG8_LAS bf16x8*)(lds + PG8_SA(b, h) + aoff + m * 2048 + k * 1024); } while (0)
; #define PG8_MMA(ai, bj, At, Bt) do { __builtin_amdgcn_s_setprio(1); _Pragma("unroll") for (int m = 0; m < 4; ++m) _Pragma("unroll") for (int n = 0; n < 2; ++n) _Pragma("unroll") for (int k = 0; k < 2; ++k) \
;         acc[ai][bj][m][n] = __builtin_amdgcn_mfma_f32_16x16x32_bf16(Bt[n][k], At[m][k], acc[ai][bj][m][n], 0, 0, 0); __builtin_amdgcn_s_setprio(0); } while (0)
; #define PG8_WAIT_V(n) asm volatile("s_waitcnt vmcnt(" #n ")" ::: "memory")
; #define PG8_WAIT_L(n) asm volatile("s_waitcnt lgkmcnt(" #n ")" ::: "memory")
; #define PG8_BAR __builtin_amdgcn_s_barrier()
; #define PG8_SCHED __builtin_amdgcn_sched_barrier(0)
; template <class Epi, class Sched, bool ALIGN_EPI = false, bool SP2 = false>
; __device__ __forceinline__ void gemm_phase(PG8_LAS unsigned char* lds, const Gemm g, const Sched& S, const Epi& E) {
;     ...
;             PG8_LDA(At, 1, 1); PG8_STAGE(PG8_SB(1, 0), b3, voffB); PG8_STAGE(PG8_SB(1, 1), b3 + hstep, voffB); PG8_STAGE(PG8_SA(1, 0), a3, voffA);
;             PG8_WAIT_V(8); PG8_WAIT_L(0); PG8_BAR; PG8_MMA(1, 0, At, B0); PG8_MMA(1, 1, At, B1); PG8_BAR; PG8_SCHED;
;     ...
;         if constexpr (ALIGN_EPI) { if (wr == 0) PG8_BAR; }
	s_setprio 0
	s_add_i32 s44, s67, s47
	v_lshl_add_u64 v[160:161], v[160:161], 0, s[16:17]
	s_mov_b32 m0, s44
	ds_read_b128 v[198:201], v177 offset:49152
	ds_read_b128 v[202:205], v177 offset:50176
	ds_read_b128 v[206:209], v177 offset:51200
	ds_read_b128 v[210:213], v177 offset:52224
	ds_read_b128 v[214:217], v177 offset:53248
	ds_read_b128 v[218:221], v177 offset:54272
	ds_read_b128 v[222:225], v177 offset:55296
	ds_read_b128 v[226:229], v177 offset:56320
	global_load_lds_dwordx4 v[160:161], off
	s_add_i32 m0, s44, 0x2000
	s_add_u32 s42, s42, 0x80080
	v_lshl_add_u64 v[160:161], v[164:165], 0, s[16:17]
	s_addc_u32 s43, s43, 0
	s_add_i32 s44, s68, s47
	global_load_lds_dwordx4 v[160:161], off
	v_lshl_add_u64 v[160:161], s[42:43], 0, v[144:145]
	s_mov_b32 m0, s44
	s_nop 0
	global_load_lds_dwordx4 v[160:161], off
	v_lshl_add_u64 v[160:161], s[42:43], 0, v[146:147]
	s_add_i32 m0, s44, 0x2000
	s_nop 0
	global_load_lds_dwordx4 v[160:161], off
	v_lshl_add_u64 v[160:161], v[170:171], 0, s[16:17]
	s_mov_b32 m0, s55
	s_nop 0
	global_load_lds_dwordx4 v[160:161], off
	v_lshl_add_u64 v[160:161], v[194:195], 0, s[16:17]
	s_mov_b32 m0, s56
	s_nop 0
	global_load_lds_dwordx4 v[160:161], off
	s_waitcnt vmcnt(8)
	s_waitcnt lgkmcnt(0)
	s_setprio 1
	s_barrier
	v_mfma_f32_16x16x32_bf16 v[60:63], v[108:111], v[198:201], v[60:63]
	v_mfma_f32_16x16x32_bf16 v[56:59], v[116:119], v[198:201], v[56:59]
	v_mfma_f32_16x16x32_bf16 v[36:39], v[108:111], v[206:209], v[36:39]
	v_mfma_f32_16x16x32_bf16 v[44:47], v[116:119], v[206:209], v[44:47]
	v_mfma_f32_16x16x32_bf16 v[20:23], v[108:111], v[214:217], v[20:23]
	v_mfma_f32_16x16x32_bf16 v[28:31], v[116:119], v[214:217], v[28:31]
	v_mfma_f32_16x16x32_bf16 v[4:7], v[108:111], v[222:225], v[4:7]
	v_mfma_f32_16x16x32_bf16 v[12:15], v[116:119], v[222:225], v[12:15]
	v_mfma_f32_16x16x32_bf16 v[60:63], v[112:115], v[202:205], v[60:63]
	v_mfma_f32_16x16x32_bf16 v[56:59], v[120:123], v[202:205], v[56:59]
	v_mfma_f32_16x16x32_bf16 v[36:39], v[112:115], v[210:213], v[36:39]
	v_mfma_f32_16x16x32_bf16 v[44:47], v[120:123], v[210:213], v[44:47]
	v_mfma_f32_16x16x32_bf16 v[20:23], v[112:115], v[218:221], v[20:23]
	v_mfma_f32_16x16x32_bf16 v[28:31], v[120:123], v[218:221], v[28:31]
	v_mfma_f32_16x16x32_bf16 v[4:7], v[112:115], v[226:229], v[4:7]
	v_mfma_f32_16x16x32_bf16 v[12:15], v[120:123], v[226:229], v[12:15]
	v_mfma_f32_16x16x32_bf16 v[48:51], v[178:181], v[198:201], v[48:51]
	v_mfma_f32_16x16x32_bf16 v[52:55], v[186:189], v[198:201], v[52:55]
	v_mfma_f32_16x16x32_bf16 v[40:43], v[178:181], v[206:209], v[40:43]
	v_mfma_f32_16x16x32_bf16 v[32:35], v[186:189], v[206:209], v[32:35]
	v_mfma_f32_16x16x32_bf16 v[24:27], v[178:181], v[214:217], v[24:27]
	v_mfma_f32_16x16x32_bf16 v[16:19], v[186:189], v[214:217], v[16:19]
	v_mfma_f32_16x16x32_bf16 v[8:11], v[178:181], v[222:225], v[8:11]
	v_mfma_f32_16x16x32_bf16 v[0:3], v[186:189], v[222:225], v[0:3]
	v_mfma_f32_16x16x32_bf16 v[48:51], v[182:185], v[202:205], v[48:51]
	v_mfma_f32_16x16x32_bf16 v[52:55], v[190:193], v[202:205], v[52:55]
	v_mfma_f32_16x16x32_bf16 v[40:43], v[182:185], v[210:213], v[40:43]
	v_mfma_f32_16x16x32_bf16 v[32:35], v[190:193], v[210:213], v[32:35]
	v_mfma_f32_16x16x32_bf16 v[24:27], v[182:185], v[218:221], v[24:27]
	v_mfma_f32_16x16x32_bf16 v[16:19], v[190:193], v[218:221], v[16:19]
	v_mfma_f32_16x16x32_bf16 v[8:11], v[182:185], v[226:229], v[8:11]
	v_mfma_f32_16x16x32_bf16 v[0:3], v[190:193], v[226:229], v[0:3]
	s_barrier
	s_setprio 0
	s_add_i32 s66, s66, 2
	s_add_u32 s8, s8, 0x100
	s_addc_u32 s9, s9, 0
	s_add_u32 s48, s48, 0x100
	s_addc_u32 s49, s49, 0
	s_cmp_gt_u32 s66, 29
	s_cbranch_scc0 .LBB0_1373
	s_and_b64 vcc, exec, s[18:19]
	s_cbranch_vccz .LBB0_1376
	s_barrier

; #define PG8_STAGE(bufoff, gbase, voff) do { _Pragma("unroll") for (int _i = 0; _i < 2; ++_i) \
;         __builtin_amdgcn_global_load_lds((const unsigned*)((const char*)(gbase) + (voff)[_i]), (PG8_LAS unsigned*)(lds + (bufoff) + ldsw + _i * 8192), 16, 0, 0); } while (0)
; #define PG8_LDA(dst, b, h) do { _Pragma("unroll") for (int m = 0; m < 4; ++m) _Pragma("unroll") for (int k = 0; k < 2; ++k) dst[m][k] = *(const PG8_LAS bf16x8*)(lds + PG8_SA(b, h) + aoff + m * 2048 + k * 1024); } while (0)
; #define PG8_LDB(dst, b, h) do { _Pragma("unroll") for (int n = 0; n < 2; ++n) _Pragma("unroll") for (int k = 0; k < 2; ++k) dst[n][k] = *(const PG8_LAS bf16x8*)(lds + PG8_SB(b, h) + boff + n * 2048 + k * 1024); } while (0)
; #define PG8_MMA(ai, bj, At, Bt) do { __builtin_amdgcn_s_setprio(1); _Pragma("unroll") for (int m = 0; m < 4; ++m) _Pragma("unroll") for (int n = 0; n < 2; ++n) _Pragma("unroll") for (int k = 0; k < 2; ++k) \
;         acc[ai][bj][m][n] = __builtin_amdgcn_mfma_f32_16x16x32_bf16(Bt[n][k], At[m][k], acc[ai][bj][m][n], 0, 0, 0); __builtin_amdgcn_s_setprio(0); } while (0)
; #define PG8_WAIT_V(n) asm volatile("s_waitcnt vmcnt(" #n ")" ::: "memory")
; #define PG8_WAIT_L(n) asm volatile("s_waitcnt lgkmcnt(" #n ")" ::: "memory")
; #define PG8_BAR __builtin_amdgcn_s_barrier()
; #define PG8_SCHED __builtin_amdgcn_sched_barrier(0)
; template <class Epi, class Sched, bool ALIGN_EPI = false, bool SP2 = false>
; __device__ __forceinline__ void gemm_phase(PG8_LAS unsigned char* lds, const Gemm g, const Sched& S, const Epi& E) {
;     ...
;             PG8_LDB(B0, 0, 0); PG8_LDB(B1, 0, 1); PG8_SCHED; PG8_LDA(At, 0, 0); PG8_STAGE(PG8_SA(1, 1), a1 + hstep, voffA);
;             PG8_WAIT_V(8); PG8_WAIT_L(0); PG8_BAR; PG8_MMA(0, 0, At, B0); PG8_MMA(0, 1, At, B1); PG8_BAR; PG8_SCHED;
;             PG8_LDA(At, 0, 1); PG8_STAGE(PG8_SB(0, 0), b2, voffB); PG8_STAGE(PG8_SB(0, 1), b2 + hstep, voffB); PG8_STAGE(PG8_SA(0, 0), a2, voffA);
;             PG8_WAIT_V(8); PG8_WAIT_L(0); PG8_BAR; PG8_MMA(1, 0, At, B0); PG8_MMA(1, 1, At, B1); PG8_BAR; PG8_SCHED;
.LBB0_1549:
	ds_read_b128 v[144:147], v155
	ds_read_b128 v[148:151], v155 offset:1024
	ds_read_b128 v[158:161], v155 offset:2048
	ds_read_b128 v[162:165], v155 offset:3072
	ds_read_b128 v[166:169], v156
	ds_read_b128 v[170:173], v156 offset:1024
	ds_read_b128 v[174:177], v156 offset:2048
	ds_read_b128 v[178:181], v156 offset:3072
	s_add_u32 s22, s20, 0xfff80080
	s_addc_u32 s23, s21, -1
	s_cmp_eq_u32 s43, 28
	s_cselect_b32 s25, s13, s23
	s_cselect_b32 s24, s39, s22
	s_cselect_b32 s23, s11, s42
	s_cselect_b32 s22, s40, s41
	v_lshl_add_u64 v[214:215], s[20:21], 0, v[136:137]
	s_add_i32 m0, s19, 0xc000
	ds_read_b128 v[182:185], v157
	ds_read_b128 v[186:189], v157 offset:1024
	ds_read_b128 v[190:193], v157 offset:2048
	ds_read_b128 v[194:197], v157 offset:3072
	ds_read_b128 v[198:201], v157 offset:4096
	ds_read_b128 v[202:205], v157 offset:5120
	ds_read_b128 v[206:209], v157 offset:6144
	ds_read_b128 v[210:213], v157 offset:7168
	global_load_lds_dwordx4 v[214:215], off
	v_lshl_add_u64 v[214:215], s[20:21], 0, v[138:139]
	s_add_i32 m0, s19, 0xe000
	s_nop 0
	global_load_lds_dwordx4 v[214:215], off
	s_waitcnt vmcnt(8)
	s_waitcnt lgkmcnt(0)
	s_setprio 1
	s_barrier
	v_mfma_f32_16x16x32_bf16 v[124:127], v[144:147], v[182:185], v[124:127]
	v_mfma_f32_16x16x32_bf16 v[120:123], v[158:161], v[182:185], v[120:123]
	v_mfma_f32_16x16x32_bf16 v[108:111], v[144:147], v[190:193], v[108:111]
	v_mfma_f32_16x16x32_bf16 v[104:107], v[158:161], v[190:193], v[104:107]
	v_mfma_f32_16x16x32_bf16 v[88:91], v[144:147], v[198:201], v[88:91]
	v_mfma_f32_16x16x32_bf16 v[92:95], v[158:161], v[198:201], v[92:95]
	v_mfma_f32_16x16x32_bf16 v[72:75], v[144:147], v[206:209], v[72:75]
	v_mfma_f32_16x16x32_bf16 v[76:79], v[158:161], v[206:209], v[76:79]
	v_mfma_f32_16x16x32_bf16 v[124:127], v[148:151], v[186:189], v[124:127]
	v_mfma_f32_16x16x32_bf16 v[120:123], v[162:165], v[186:189], v[120:123]
	v_mfma_f32_16x16x32_bf16 v[108:111], v[148:151], v[194:197], v[108:111]
	v_mfma_f32_16x16x32_bf16 v[104:107], v[162:165], v[194:197], v[104:107]
	v_mfma_f32_16x16x32_bf16 v[88:91], v[148:151], v[202:205], v[88:91]
	v_mfma_f32_16x16x32_bf16 v[92:95], v[162:165], v[202:205], v[92:95]
	v_mfma_f32_16x16x32_bf16 v[72:75], v[148:151], v[210:213], v[72:75]
	v_mfma_f32_16x16x32_bf16 v[76:79], v[162:165], v[210:213], v[76:79]
	v_mfma_f32_16x16x32_bf16 v[116:119], v[166:169], v[182:185], v[116:119]
	v_mfma_f32_16x16x32_bf16 v[112:115], v[174:177], v[182:185], v[112:115]
	v_mfma_f32_16x16x32_bf16 v[96:99], v[166:169], v[190:193], v[96:99]
	v_mfma_f32_16x16x32_bf16 v[100:103], v[174:177], v[190:193], v[100:103]
	v_mfma_f32_16x16x32_bf16 v[80:83], v[166:169], v[198:201], v[80:83]
	v_mfma_f32_16x16x32_bf16 v[84:87], v[174:177], v[198:201], v[84:87]
	v_mfma_f32_16x16x32_bf16 v[64:67], v[166:169], v[206:209], v[64:67]
	v_mfma_f32_16x16x32_bf16 v[68:71], v[174:177], v[206:209], v[68:71]
	v_mfma_f32_16x16x32_bf16 v[116:119], v[170:173], v[186:189], v[116:119]
	v_mfma_f32_16x16x32_bf16 v[112:115], v[178:181], v[186:189], v[112:115]
	v_mfma_f32_16x16x32_bf16 v[96:99], v[170:173], v[194:197], v[96:99]
	v_mfma_f32_16x16x32_bf16 v[100:103], v[178:181], v[194:197], v[100:103]
	v_mfma_f32_16x16x32_bf16 v[80:83], v[170:173], v[202:205], v[80:83]
	v_mfma_f32_16x16x32_bf16 v[84:87], v[178:181], v[202:205], v[84:87]
	v_mfma_f32_16x16x32_bf16 v[64:67], v[170:173], v[210:213], v[64:67]
	v_mfma_f32_16x16x32_bf16 v[68:71], v[178:181], v[210:213], v[68:71]
	s_barrier
	s_setprio 0
	s_add_i32 s44, s36, s27
	v_lshl_add_u64 v[214:215], s[22:23], 0, v[130:131]
	s_mov_b32 m0, s44
	ds_read_b128 v[182:185], v157 offset:16384
	ds_read_b128 v[186:189], v157 offset:17408
	ds_read_b128 v[190:193], v157 offset:18432
	ds_read_b128 v[194:197], v157 offset:19456
	ds_read_b128 v[198:201], v157 offset:20480
	ds_read_b128 v[202:205], v157 offset:21504
	ds_read_b128 v[206:209], v157 offset:22528
	ds_read_b128 v[210:213], v157 offset:23552
	global_load_lds_dwordx4 v[214:215], off
	s_add_i32 m0, s44, 0x2000
	s_add_u32 s44, s22, 0x80000
	v_lshl_add_u64 v[216:217], s[22:23], 0, v[134:135]
	s_addc_u32 s45, s23, 0
	s_add_i32 s46, s37, s27
	global_load_lds_dwordx4 v[216:217], off
	v_lshl_add_u64 v[218:219], s[44:45], 0, v[130:131]
	s_mov_b32 m0, s46
	v_lshl_add_u64 v[220:221], s[24:25], 0, v[132:133]
	global_load_lds_dwordx4 v[218:219], off
	v_lshl_add_u64 v[218:219], s[44:45], 0, v[134:135]
	s_add_i32 m0, s46, 0x2000
	s_nop 0
	global_load_lds_dwordx4 v[218:219], off
	v_lshl_add_u64 v[218:219], s[24:25], 0, v[128:129]
	s_mov_b32 m0, s19
	s_nop 0
	global_load_lds_dwordx4 v[218:219], off
	s_mov_b32 m0, s28
	s_nop 0
	global_load_lds_dwordx4 v[220:221], off
	s_waitcnt vmcnt(8)
	s_waitcnt lgkmcnt(0)
	s_setprio 1
	s_barrier
; #define PG8_STAGE(bufoff, gbase, voff) do { _Pragma("unroll") for (int _i = 0; _i < 2; ++_i) \
;         __builtin_amdgcn_global_load_lds((const unsigned*)((const char*)(gbase) + (voff)[_i]), (PG8_LAS unsigned*)(lds + (bufoff) + ldsw + _i * 8192), 16, 0, 0); } while (0)
; #define PG8_LDA(dst, b, h) do { _Pragma("unroll") for (int m = 0; m < 4; ++m) _Pragma("unroll") for (int k = 0; k < 2; ++k) dst[m][k] = *(const PG8_LAS bf16x8*)(lds + PG8_SA(b, h) + aoff + m * 2048 + k * 1024); } while (0)
; #define PG8_LDB(dst, b, h) do { _Pragma("unroll") for (int n = 0; n < 2; ++n) _Pragma("unroll") for (int k = 0; k < 2; ++k) dst[n][k] = *(const PG8_LAS bf16x8*)(lds + PG8_SB(b, h) + boff + n * 2048 + k * 1024); } while (0)
; #define PG8_MMA(ai, bj, At, Bt) do { __builtin_amdgcn_s_setprio(1); _Pragma("unroll") for (int m = 0; m < 4; ++m) _Pragma("unroll") for (int n = 0; n < 2; ++n) _Pragma("unroll") for (int k = 0; k < 2; ++k) \
;         acc[ai][bj][m][n] = __builtin_amdgcn_mfma_f32_16x16x32_bf16(Bt[n][k], At[m][k], acc[ai][bj][m][n], 0, 0, 0); __builtin_amdgcn_s_setprio(0); } while (0)
; #define PG8_WAIT_V(n) asm volatile("s_waitcnt vmcnt(" #n ")" ::: "memory")
; #define PG8_WAIT_L(n) asm volatile("s_waitcnt lgkmcnt(" #n ")" ::: "memory")
; #define PG8_BAR __builtin_amdgcn_s_barrier()
; #define PG8_SCHED __builtin_amdgcn_sched_barrier(0)
; template <class Epi, class Sched, bool ALIGN_EPI = false, bool SP2 = false>
; __device__ __forceinline__ void gemm_phase(PG8_LAS unsigned char* lds, const Gemm g, const Sched& S, const Epi& E) {
;     ...
;             PG8_WAIT_V(8); PG8_WAIT_L(0); PG8_BAR; PG8_MMA(1, 0, At, B0); PG8_MMA(1, 1, At, B1); PG8_BAR; PG8_SCHED;
;             PG8_LDB(B0, 1, 0); PG8_LDB(B1, 1, 1); PG8_SCHED; PG8_LDA(At, 1, 0); PG8_STAGE(PG8_SA(0, 1), a2 + hstep, voffA);
;             PG8_WAIT_V(8); PG8_WAIT_L(0); PG8_BAR; PG8_MMA(0, 0, At, B0); PG8_MMA(0, 1, At, B1); PG8_BAR; PG8_SCHED;
	v_mfma_f32_16x16x32_bf16 v[56:59], v[144:147], v[182:185], v[56:59]
	v_mfma_f32_16x16x32_bf16 v[60:63], v[158:161], v[182:185], v[60:63]
	v_mfma_f32_16x16x32_bf16 v[40:43], v[144:147], v[190:193], v[40:43]
	v_mfma_f32_16x16x32_bf16 v[44:47], v[158:161], v[190:193], v[44:47]
	v_mfma_f32_16x16x32_bf16 v[24:27], v[144:147], v[198:201], v[24:27]
	v_mfma_f32_16x16x32_bf16 v[28:31], v[158:161], v[198:201], v[28:31]
	v_mfma_f32_16x16x32_bf16 v[8:11], v[144:147], v[206:209], v[8:11]
	v_mfma_f32_16x16x32_bf16 v[12:15], v[158:161], v[206:209], v[12:15]
	v_mfma_f32_16x16x32_bf16 v[56:59], v[148:151], v[186:189], v[56:59]
	v_mfma_f32_16x16x32_bf16 v[60:63], v[162:165], v[186:189], v[60:63]
	v_mfma_f32_16x16x32_bf16 v[40:43], v[148:151], v[194:197], v[40:43]
	v_mfma_f32_16x16x32_bf16 v[44:47], v[162:165], v[194:197], v[44:47]
	v_mfma_f32_16x16x32_bf16 v[24:27], v[148:151], v[202:205], v[24:27]
	v_mfma_f32_16x16x32_bf16 v[28:31], v[162:165], v[202:205], v[28:31]
	v_mfma_f32_16x16x32_bf16 v[8:11], v[148:151], v[210:213], v[8:11]
	v_mfma_f32_16x16x32_bf16 v[12:15], v[162:165], v[210:213], v[12:15]
	v_mfma_f32_16x16x32_bf16 v[48:51], v[166:169], v[182:185], v[48:51]
	v_mfma_f32_16x16x32_bf16 v[52:55], v[174:177], v[182:185], v[52:55]
	v_mfma_f32_16x16x32_bf16 v[32:35], v[166:169], v[190:193], v[32:35]
	v_mfma_f32_16x16x32_bf16 v[36:39], v[174:177], v[190:193], v[36:39]
	v_mfma_f32_16x16x32_bf16 v[16:19], v[166:169], v[198:201], v[16:19]
	v_mfma_f32_16x16x32_bf16 v[20:23], v[174:177], v[198:201], v[20:23]
	v_mfma_f32_16x16x32_bf16 v[0:3], v[166:169], v[206:209], v[0:3]
	v_mfma_f32_16x16x32_bf16 v[4:7], v[174:177], v[206:209], v[4:7]
	v_mfma_f32_16x16x32_bf16 v[48:51], v[170:173], v[186:189], v[48:51]
	v_mfma_f32_16x16x32_bf16 v[52:55], v[178:181], v[186:189], v[52:55]
	v_mfma_f32_16x16x32_bf16 v[32:35], v[170:173], v[194:197], v[32:35]
	v_mfma_f32_16x16x32_bf16 v[36:39], v[178:181], v[194:197], v[36:39]
	v_mfma_f32_16x16x32_bf16 v[16:19], v[170:173], v[202:205], v[16:19]
	v_mfma_f32_16x16x32_bf16 v[20:23], v[178:181], v[202:205], v[20:23]
	v_mfma_f32_16x16x32_bf16 v[0:3], v[170:173], v[210:213], v[0:3]
	v_mfma_f32_16x16x32_bf16 v[4:7], v[178:181], v[210:213], v[4:7]
	s_barrier
	s_setprio 0
	s_add_i32 s44, 0, 0x18000
	s_add_i32 s45, 0, 0x1c000
	v_add_u32_e32 v162, s44, v153
	v_add_u32_e32 v178, s45, v153
	ds_read_b128 v[144:147], v162
	ds_read_b128 v[148:151], v162 offset:1024
	ds_read_b128 v[158:161], v162 offset:2048
	ds_read_b128 v[162:165], v162 offset:3072
	ds_read_b128 v[166:169], v178
	ds_read_b128 v[170:173], v178 offset:1024
	ds_read_b128 v[174:177], v178 offset:2048
	ds_read_b128 v[178:181], v178 offset:3072
	s_add_u32 s24, s24, 0x80000
	s_addc_u32 s25, s25, 0
	s_mov_b32 m0, s29
	v_lshl_add_u64 v[222:223], s[24:25], 0, v[128:129]
	ds_read_b128 v[182:185], v157 offset:32768
	ds_read_b128 v[186:189], v157 offset:33792
	ds_read_b128 v[190:193], v157 offset:34816
	ds_read_b128 v[194:197], v157 offset:35840
	ds_read_b128 v[198:201], v157 offset:36864
	ds_read_b128 v[202:205], v157 offset:37888
	ds_read_b128 v[206:209], v157 offset:38912
	ds_read_b128 v[210:213], v157 offset:39936
	global_load_lds_dwordx4 v[222:223], off
	v_lshl_add_u64 v[222:223], s[24:25], 0, v[132:133]
	s_mov_b32 m0, s30
	s_nop 0
	global_load_lds_dwordx4 v[222:223], off
	s_waitcnt vmcnt(8)
	s_waitcnt lgkmcnt(0)
	s_setprio 1
	s_barrier
	v_mfma_f32_16x16x32_bf16 v[124:127], v[144:147], v[182:185], v[124:127]
	v_mfma_f32_16x16x32_bf16 v[120:123], v[158:161], v[182:185], v[120:123]
	v_mfma_f32_16x16x32_bf16 v[108:111], v[144:147], v[190:193], v[108:111]
	v_mfma_f32_16x16x32_bf16 v[104:107], v[158:161], v[190:193], v[104:107]
	v_mfma_f32_16x16x32_bf16 v[88:91], v[144:147], v[198:201], v[88:91]
	v_mfma_f32_16x16x32_bf16 v[92:95], v[158:161], v[198:201], v[92:95]
	v_mfma_f32_16x16x32_bf16 v[72:75], v[144:147], v[206:209], v[72:75]
	v_mfma_f32_16x16x32_bf16 v[76:79], v[158:161], v[206:209], v[76:79]
	v_mfma_f32_16x16x32_bf16 v[124:127], v[148:151], v[186:189], v[124:127]
	v_mfma_f32_16x16x32_bf16 v[120:123], v[162:165], v[186:189], v[120:123]
	v_mfma_f32_16x16x32_bf16 v[108:111], v[148:151], v[194:197], v[108:111]
	v_mfma_f32_16x16x32_bf16 v[104:107], v[162:165], v[194:197], v[104:107]
	v_mfma_f32_16x16x32_bf16 v[88:91], v[148:151], v[202:205], v[88:91]
	v_mfma_f32_16x16x32_bf16 v[92:95], v[162:165], v[202:205], v[92:95]
	v_mfma_f32_16x16x32_bf16 v[72:75], v[148:151], v[210:213], v[72:75]
	v_mfma_f32_16x16x32_bf16 v[76:79], v[162:165], v[210:213], v[76:79]
	v_mfma_f32_16x16x32_bf16 v[116:119], v[166:169], v[182:185], v[116:119]
	v_mfma_f32_16x16x32_bf16 v[112:115], v[174:177], v[182:185], v[112:115]
	v_mfma_f32_16x16x32_bf16 v[96:99], v[166:169], v[190:193], v[96:99]
	v_mfma_f32_16x16x32_bf16 v[100:103], v[174:177], v[190:193], v[100:103]
	v_mfma_f32_16x16x32_bf16 v[80:83], v[166:169], v[198:201], v[80:83]
	v_mfma_f32_16x16x32_bf16 v[84:87], v[174:177], v[198:201], v[84:87]
	v_mfma_f32_16x16x32_bf16 v[64:67], v[166:169], v[206:209], v[64:67]
	v_mfma_f32_16x16x32_bf16 v[68:71], v[174:177], v[206:209], v[68:71]
	v_mfma_f32_16x16x32_bf16 v[116:119], v[170:173], v[186:189], v[116:119]
	v_mfma_f32_16x16x32_bf16 v[112:115], v[178:181], v[186:189], v[112:115]
	v_mfma_f32_16x16x32_bf16 v[96:99], v[170:173], v[194:197], v[96:99]
	v_mfma_f32_16x16x32_bf16 v[100:103], v[178:181], v[194:197], v[100:103]
	v_mfma_f32_16x16x32_bf16 v[80:83], v[170:173], v[202:205], v[80:83]
	v_mfma_f32_16x16x32_bf16 v[84:87], v[178:181], v[202:205], v[84:87]
	v_mfma_f32_16x16x32_bf16 v[64:67], v[170:173], v[210:213], v[64:67]
	v_mfma_f32_16x16x32_bf16 v[68:71], v[178:181], v[210:213], v[68:71]
	s_barrier
; #define PG8_STAGE(bufoff, gbase, voff) do { _Pragma("unroll") for (int _i = 0; _i < 2; ++_i) \
;         __builtin_amdgcn_global_load_lds((const unsigned*)((const char*)(gbase) + (voff)[_i]), (PG8_LAS unsigned*)(lds + (bufoff) + ldsw + _i * 8192), 16, 0, 0); } while (0)
; #define PG8_LDA(dst, b, h) do { _Pragma("unroll") for (int m = 0; m < 4; ++m) _Pragma("unroll") for (int k = 0; k < 2; ++k) dst[m][k] = *(const PG8_LAS bf16x8*)(lds + PG8_SA(b, h) + aoff + m * 2048 + k * 1024); } while (0)
; #define PG8_MMA(ai, bj, At, Bt) do { __builtin_amdgcn_s_setprio(1); _Pragma("unroll") for (int m = 0; m < 4; ++m) _Pragma("unroll") for (int n = 0; n < 2; ++n) _Pragma("unroll") for (int k = 0; k < 2; ++k) \
;         acc[ai][bj][m][n] = __builtin_amdgcn_mfma_f32_16x16x32_bf16(Bt[n][k], At[m][k], acc[ai][bj][m][n], 0, 0, 0); __builtin_amdgcn_s_setprio(0); } while (0)
; #define PG8_WAIT_V(n) asm volatile("s_waitcnt vmcnt(" #n ")" ::: "memory")
; #define PG8_WAIT_L(n) asm volatile("s_waitcnt lgkmcnt(" #n ")" ::: "memory")
; #define PG8_BAR __builtin_amdgcn_s_barrier()
; #define PG8_SCHED __builtin_amdgcn_sched_barrier(0)
; template <class Epi, class Sched, bool ALIGN_EPI = false, bool SP2 = false>
; __device__ __forceinline__ void gemm_phase(PG8_LAS unsigned char* lds, const Gemm g, const Sched& S, const Epi& E) {
;     ...
;             PG8_LDA(At, 1, 1); PG8_STAGE(PG8_SB(1, 0), b3, voffB); PG8_STAGE(PG8_SB(1, 1), b3 + hstep, voffB); PG8_STAGE(PG8_SA(1, 0), a3, voffA);
;             PG8_WAIT_V(8); PG8_WAIT_L(0); PG8_BAR; PG8_MMA(1, 0, At, B0); PG8_MMA(1, 1, At, B1); PG8_BAR; PG8_SCHED;
;     ...
;         if constexpr (ALIGN_EPI) { if (wr == 0) PG8_BAR; }
	s_setprio 0
	s_add_i32 s24, s44, s27
	v_lshl_add_u64 v[214:215], v[214:215], 0, s[4:5]
	s_mov_b32 m0, s24
	ds_read_b128 v[182:185], v157 offset:49152
	ds_read_b128 v[186:189], v157 offset:50176
	ds_read_b128 v[190:193], v157 offset:51200
	ds_read_b128 v[194:197], v157 offset:52224
	ds_read_b128 v[198:201], v157 offset:53248
	ds_read_b128 v[202:205], v157 offset:54272
	ds_read_b128 v[206:209], v157 offset:55296
	ds_read_b128 v[210:213], v157 offset:56320
	global_load_lds_dwordx4 v[214:215], off
	s_add_i32 m0, s24, 0x2000
	s_add_u32 s22, s22, 0x80080
	v_lshl_add_u64 v[214:215], v[216:217], 0, s[4:5]
	s_addc_u32 s23, s23, 0
	s_add_i32 s24, s45, s27
	global_load_lds_dwordx4 v[214:215], off
	v_lshl_add_u64 v[214:215], s[22:23], 0, v[130:131]
	s_mov_b32 m0, s24
	s_nop 0
	global_load_lds_dwordx4 v[214:215], off
	v_lshl_add_u64 v[214:215], s[22:23], 0, v[134:135]
	s_add_i32 m0, s24, 0x2000
	s_nop 0
	global_load_lds_dwordx4 v[214:215], off
	v_lshl_add_u64 v[214:215], v[218:219], 0, s[4:5]
	s_mov_b32 m0, s33
	s_nop 0
	global_load_lds_dwordx4 v[214:215], off
	v_lshl_add_u64 v[214:215], v[220:221], 0, s[4:5]
	s_mov_b32 m0, s34
	s_nop 0
	global_load_lds_dwordx4 v[214:215], off
	s_waitcnt vmcnt(8)
	s_waitcnt lgkmcnt(0)
	s_setprio 1
	s_barrier
	v_mfma_f32_16x16x32_bf16 v[56:59], v[144:147], v[182:185], v[56:59]
	v_mfma_f32_16x16x32_bf16 v[60:63], v[158:161], v[182:185], v[60:63]
	v_mfma_f32_16x16x32_bf16 v[40:43], v[144:147], v[190:193], v[40:43]
	v_mfma_f32_16x16x32_bf16 v[44:47], v[158:161], v[190:193], v[44:47]
	v_mfma_f32_16x16x32_bf16 v[24:27], v[144:147], v[198:201], v[24:27]
	v_mfma_f32_16x16x32_bf16 v[28:31], v[158:161], v[198:201], v[28:31]
	v_mfma_f32_16x16x32_bf16 v[8:11], v[144:147], v[206:209], v[8:11]
	v_mfma_f32_16x16x32_bf16 v[12:15], v[158:161], v[206:209], v[12:15]
	v_mfma_f32_16x16x32_bf16 v[56:59], v[148:151], v[186:189], v[56:59]
	v_mfma_f32_16x16x32_bf16 v[60:63], v[162:165], v[186:189], v[60:63]
	v_mfma_f32_16x16x32_bf16 v[40:43], v[148:151], v[194:197], v[40:43]
	v_mfma_f32_16x16x32_bf16 v[44:47], v[162:165], v[194:197], v[44:47]
	v_mfma_f32_16x16x32_bf16 v[24:27], v[148:151], v[202:205], v[24:27]
	v_mfma_f32_16x16x32_bf16 v[28:31], v[162:165], v[202:205], v[28:31]
	v_mfma_f32_16x16x32_bf16 v[8:11], v[148:151], v[210:213], v[8:11]
	v_mfma_f32_16x16x32_bf16 v[12:15], v[162:165], v[210:213], v[12:15]
	v_mfma_f32_16x16x32_bf16 v[48:51], v[166:169], v[182:185], v[48:51]
	v_mfma_f32_16x16x32_bf16 v[52:55], v[174:177], v[182:185], v[52:55]
	v_mfma_f32_16x16x32_bf16 v[32:35], v[166:169], v[190:193], v[32:35]
	v_mfma_f32_16x16x32_bf16 v[36:39], v[174:177], v[190:193], v[36:39]
	v_mfma_f32_16x16x32_bf16 v[16:19], v[166:169], v[198:201], v[16:19]
	v_mfma_f32_16x16x32_bf16 v[20:23], v[174:177], v[198:201], v[20:23]
	v_mfma_f32_16x16x32_bf16 v[0:3], v[166:169], v[206:209], v[0:3]
	v_mfma_f32_16x16x32_bf16 v[4:7], v[174:177], v[206:209], v[4:7]
	v_mfma_f32_16x16x32_bf16 v[48:51], v[170:173], v[186:189], v[48:51]
	v_mfma_f32_16x16x32_bf16 v[52:55], v[178:181], v[186:189], v[52:55]
	v_mfma_f32_16x16x32_bf16 v[32:35], v[170:173], v[194:197], v[32:35]
	v_mfma_f32_16x16x32_bf16 v[36:39], v[178:181], v[194:197], v[36:39]
	v_mfma_f32_16x16x32_bf16 v[16:19], v[170:173], v[202:205], v[16:19]
	v_mfma_f32_16x16x32_bf16 v[20:23], v[178:181], v[202:205], v[20:23]
	v_mfma_f32_16x16x32_bf16 v[0:3], v[170:173], v[210:213], v[0:3]
	v_mfma_f32_16x16x32_bf16 v[4:7], v[178:181], v[210:213], v[4:7]
	s_barrier
	s_setprio 0
	s_add_i32 s43, s43, 2
	s_add_u32 s20, s20, 0x100
	s_addc_u32 s21, s21, 0
	s_add_u32 s41, s41, 0x100
	s_addc_u32 s42, s42, 0
	s_cmp_gt_u32 s43, 29
	s_cbranch_scc0 .LBB0_1549
	s_and_b64 vcc, exec, s[6:7]
	s_cbranch_vccz .LBB0_1552
	s_barrier
